# hyena conv8 boundary loads batched (one wait per phase instead of 32 serialized), plus earlier epilogue/P0 load pipelining; bit-identical outputs
# speedup vs baseline: 1.0015x; 1.0015x over previous
; __device__ __forceinline__ float bf2f(bf16_t v) { return __uint_as_float((unsigned)v << 16); }
; __device__ __forceinline__ unsigned pk2(float lo, float hi) { return f2bf(lo) | (f2bf(hi) << 16); }
; __device__ __forceinline__ void conv8(const bf16_t* hyT, unsigned off, int t0, int L, float w0, float w1, float w2, float b, f32x4 (&o)[2]) {
;     const u32x4v raw = *(const u32x4v*)(hyT + (off + (unsigned)t0));
;     const float xm = t0 > 0 ? bf2f(hyT[off + (unsigned)t0 - 1u]) : 0.f, xp = t0 + 8 < L ? bf2f(hyT[off + (unsigned)t0 + 8u]) : 0.f;
;     const float x0 = __uint_as_float(raw.x << 16), x1 = __uint_as_float(raw.x & 0xffff0000u), x2 = __uint_as_float(raw.y << 16), x3 = __uint_as_float(raw.y & 0xffff0000u);
;     const float x4 = __uint_as_float(raw.z << 16), x5 = __uint_as_float(raw.z & 0xffff0000u), x6 = __uint_as_float(raw.w << 16), x7 = __uint_as_float(raw.w & 0xffff0000u);
;     o[0][0] = fmaf(xm, w0, fmaf(x0, w1, fmaf(x1, w2, b))); o[0][1] = fmaf(x0, w0, fmaf(x1, w1, fmaf(x2, w2, b))); o[0][2] = fmaf(x1, w0, fmaf(x2, w1, fmaf(x3, w2, b))); o[0][3] = fmaf(x2, w0, fmaf(x3, w1, fmaf(x4, w2, b)));
;     o[1][0] = fmaf(x3, w0, fmaf(x4, w1, fmaf(x5, w2, b))); o[1][1] = fmaf(x4, w0, fmaf(x5, w1, fmaf(x6, w2, b))); o[1][2] = fmaf(x5, w0, fmaf(x6, w1, fmaf(x7, w2, b))); o[1][3] = fmaf(x6, w0, fmaf(x7, w1, fmaf(xp, w2, b)));
; template <int R0> __device__ __forceinline__ void hy_pair(LAS cf* X, const int N, const int L, const int tid, const unsigned mA, const unsigned mB, const bf16_t* hyT, bf16_t* hyo, ...
;     ...
;     {   f32x4 yr[NL][2], yi[NL][2]; r0_inv_load<R0>(X, N, j0, yr, yi);
; #pragma unroll
;         for (int n = 0; n < NL; ++n) { const int t0 = j0 + n * 4096; f32x4 xa[2], xb[2];
;             conv8(hyT, ob + mA, t0, L, wb0, wb1, wb2, bb, xa); conv8(hyT, ob + mB, t0, L, wb0, wb1, wb2, bb, xb);
;             u32x4v oA, oB;
; #pragma unroll
;             for (int e = 0; e < 8; e += 2) { const f32x4 z = ZS[(unsigned)((t0 + e) >> 1)];
;                 oA[e >> 1] = pk2(VEL(xa, e) * (VEL(yr[n], e) + z.x * d1), VEL(xa, e + 1) * (VEL(yr[n], e + 1) + z.z * d1));
;                 oB[e >> 1] = pk2(VEL(xb, e) * (VEL(yi[n], e) + z.y * d1), VEL(xb, e + 1) * (VEL(yi[n], e + 1) + z.w * d1)); }
.LBB0_343:
	s_or_b64 exec, exec, s[6:7]
	v_pk_add_f32 v[124:125], v[6:7], v[124:125] neg_lo:[0,1] neg_hi:[0,1]
	v_pk_add_f32 v[118:119], v[4:5], v[118:119] neg_lo:[0,1] neg_hi:[0,1]
	v_pk_add_f32 v[112:113], v[2:3], v[112:113] neg_lo:[0,1] neg_hi:[0,1]
	v_pk_add_f32 v[30:31], v[0:1], v[30:31] neg_lo:[0,1] neg_hi:[0,1]
	global_load_dwordx4 v[0:3], v[96:97], off
	global_load_dwordx4 v[4:7], v[98:99], off
	s_waitcnt vmcnt(3)
	v_lshlrev_b32_e32 v105, 16, v22
	v_lshlrev_b32_e32 v104, 16, v21
	v_lshlrev_b32_e32 v96, 16, v20
	v_and_b32_e32 v99, 0xffff0000, v21
	v_and_b32_e32 v98, 0xffff0000, v20
	v_pk_fma_f32 v[20:21], v[104:105], v[58:59], v[60:61]
	v_pk_add_f32 v[28:29], v[28:29], v[108:109] neg_lo:[0,1] neg_hi:[0,1]
	v_mov_b32_e32 v97, v104
	v_pk_fma_f32 v[20:21], v[98:99], v[56:57], v[20:21]
	v_pk_fma_f32 v[108:109], v[98:99], v[58:59], v[60:61]
	v_pk_add_f32 v[122:123], v[122:123], v[126:127] neg_lo:[0,1] neg_hi:[0,1]
	v_pk_add_f32 v[110:111], v[110:111], v[114:115] neg_lo:[0,1] neg_hi:[0,1]
	v_pk_fma_f32 v[20:21], v[96:97], v[54:55], v[20:21]
	v_pk_fma_f32 v[96:97], v[96:97], v[56:57], v[108:109]
	v_mov_b32_e32 v107, v98
	v_pk_add_f32 v[116:117], v[116:117], v[120:121] neg_lo:[0,1] neg_hi:[0,1]
	s_waitcnt vmcnt(0)
	v_lshlrev_b32_e32 v106, 16, v106
	v_lshlrev_b32_e32 v27, 16, v27
	v_lshlrev_b32_e32 v154, 16, v154
	v_lshlrev_b32_e32 v25, 16, v25
	v_pk_fma_f32 v[96:97], v[106:107], v[54:55], v[96:97]
	v_mov_b32_e32 v106, v112
	v_mov_b32_e32 v107, v124
	v_mov_b32_e32 v108, v111
	v_mov_b32_e32 v109, v123
	v_pk_add_f32 v[106:107], v[106:107], v[108:109] neg_lo:[0,1] neg_hi:[0,1]
	v_mov_b32_e32 v108, v30
	v_mov_b32_e32 v109, v118
	v_mov_b32_e32 v114, v29
	v_mov_b32_e32 v115, v117
	v_pk_add_f32 v[108:109], v[108:109], v[114:115] neg_lo:[0,1] neg_hi:[0,1]
	v_mov_b32_e32 v124, v113
	v_mov_b32_e32 v111, v122
	v_mov_b32_e32 v118, v31
	v_mov_b32_e32 v29, v116
	s_waitcnt vmcnt(2)
	v_lshlrev_b32_e32 v31, 16, v18
	v_lshlrev_b32_e32 v26, 16, v23
	v_pk_add_f32 v[88:89], v[14:15], v[150:151] neg_lo:[0,1] neg_hi:[0,1]
	v_pk_add_f32 v[90:91], v[148:149], v[152:153] neg_lo:[0,1] neg_hi:[0,1]
	v_pk_add_f32 v[102:103], v[10:11], v[136:137] neg_lo:[0,1] neg_hi:[0,1]
	v_pk_add_f32 v[100:101], v[134:135], v[138:139] neg_lo:[0,1] neg_hi:[0,1]
	v_and_b32_e32 v23, 0xffff0000, v23
	v_and_b32_e32 v22, 0xffff0000, v22
	v_pk_add_f32 v[12:13], v[12:13], v[142:143] neg_lo:[0,1] neg_hi:[0,1]
	v_pk_add_f32 v[14:15], v[140:141], v[146:147] neg_lo:[0,1] neg_hi:[0,1]
	v_pk_add_f32 v[10:11], v[8:9], v[130:131] neg_lo:[0,1] neg_hi:[0,1]
	v_pk_add_f32 v[8:9], v[128:129], v[132:133] neg_lo:[0,1] neg_hi:[0,1]
	v_mov_b32_e32 v104, v105
	v_mov_b32_e32 v105, v26
	v_lshlrev_b32_e32 v24, 16, v19
	s_waitcnt vmcnt(1)
	v_mov_b32_e32 v114, v0
	s_waitcnt vmcnt(0)
; __device__ __forceinline__ unsigned pk2(float lo, float hi) { return f2bf(lo) | (f2bf(hi) << 16); }
; template <int R0> __device__ __forceinline__ void hy_pair(LAS cf* X, const int N, const int L, const int tid, const unsigned mA, const unsigned mB, const bf16_t* hyT, bf16_t* hyo, ...
;     ...
;         for (int n = 0; n < NL; ++n) { const int t0 = j0 + n * 4096; f32x4 xa[2], xb[2];
;             conv8(hyT, ob + mA, t0, L, wb0, wb1, wb2, bb, xa); conv8(hyT, ob + mB, t0, L, wb0, wb1, wb2, bb, xb);
;             u32x4v oA, oB;
; #pragma unroll
;             for (int e = 0; e < 8; e += 2) { const f32x4 z = ZS[(unsigned)((t0 + e) >> 1)];
;                 oA[e >> 1] = pk2(VEL(xa, e) * (VEL(yr[n], e) + z.x * d1), VEL(xa, e + 1) * (VEL(yr[n], e + 1) + z.z * d1));
;                 oB[e >> 1] = pk2(VEL(xb, e) * (VEL(yi[n], e) + z.y * d1), VEL(xb, e + 1) * (VEL(yi[n], e + 1) + z.w * d1)); }
;             *(u32x4v*)(hyo + (ov + mA + (unsigned)t0)) = oA; *(u32x4v*)(hyo + (ov + mB + (unsigned)t0)) = oB; } }
	v_mov_b32_e32 v115, v4
	v_pk_fma_f32 v[108:109], v[62:63], v[114:115], v[108:109]
	v_mov_b32_e32 v4, v1
	v_pk_mul_f32 v[96:97], v[96:97], v[108:109]
	v_mov_b32_e32 v108, v2
	v_mov_b32_e32 v109, v6
	v_pk_fma_f32 v[106:107], v[62:63], v[108:109], v[106:107]
	v_pk_add_f32 v[108:109], v[118:119], v[28:29]
	v_pk_mul_f32 v[106:107], v[20:21], v[106:107]
	v_pk_add_f32 v[20:21], v[124:125], v[110:111]
	v_lshlrev_b32_e32 v111, 16, v17
	v_and_b32_e32 v29, 0xffff0000, v17
	v_and_b32_e32 v28, 0xffff0000, v16
	v_lshlrev_b32_e32 v110, 16, v16
	v_mov_b32_e32 v30, v111
	v_pk_fma_f32 v[16:17], v[28:29], v[58:59], v[60:61]
	v_mov_b32_e32 v155, v28
	v_pk_fma_f32 v[16:17], v[110:111], v[56:57], v[16:17]
	v_pk_fma_f32 v[112:113], v[30:31], v[58:59], v[60:61]
	v_pk_fma_f32 v[16:17], v[154:155], v[54:55], v[16:17]
	v_pk_fma_f32 v[112:113], v[28:29], v[56:57], v[112:113]
	v_pk_fma_f32 v[0:1], v[62:63], v[4:5], v[108:109]
	v_mov_b32_e32 v6, v3
	v_pk_fma_f32 v[110:111], v[110:111], v[54:55], v[112:113]
	v_pk_mul_f32 v[16:17], v[16:17], v[0:1]
	v_pk_fma_f32 v[0:1], v[62:63], v[6:7], v[20:21]
	v_mov_b32_e32 v108, v102
	v_pk_mul_f32 v[20:21], v[110:111], v[0:1]
	global_load_dwordx4 v[4:7], v[92:93], off
	global_load_dwordx4 v[0:3], v[94:95], off
	v_pk_fma_f32 v[92:93], v[26:27], v[58:59], v[60:61]
	v_pk_fma_f32 v[94:95], v[22:23], v[58:59], v[60:61]
	v_pk_fma_f32 v[92:93], v[22:23], v[56:57], v[92:93]
	v_mov_b32_e32 v109, v88
	v_mov_b32_e32 v110, v101
	v_mov_b32_e32 v111, v91
	v_pk_add_f32 v[108:109], v[108:109], v[110:111] neg_lo:[0,1] neg_hi:[0,1]
	v_mov_b32_e32 v110, v10
	v_mov_b32_e32 v111, v12
	v_mov_b32_e32 v112, v9
	v_mov_b32_e32 v113, v15
	v_pk_fma_f32 v[26:27], v[104:105], v[54:55], v[92:93]
	v_pk_fma_f32 v[92:93], v[104:105], v[56:57], v[94:95]
	v_pk_mov_b32 v[22:23], v[98:99], v[22:23] op_sel:[1,0]
	v_pk_add_f32 v[110:111], v[110:111], v[112:113] neg_lo:[0,1] neg_hi:[0,1]
	v_pk_fma_f32 v[22:23], v[22:23], v[54:55], v[92:93]
	v_bfe_u32 v9, v96, 16, 1
	v_bfe_u32 v10, v97, 16, 1
	v_add3_u32 v10, v97, v10, s36
	v_add3_u32 v9, v96, v9, s36
	v_lshrrev_b32_e32 v9, 16, v9
	v_lshrrev_b32_e32 v10, 16, v10
	v_mov_b32_e32 v88, v103
	v_mov_b32_e32 v101, v90
	s_waitcnt vmcnt(1)
	v_mov_b32_e32 v92, v4
	s_waitcnt vmcnt(0)
	v_mov_b32_e32 v93, v0
	v_pk_fma_f32 v[92:93], v[62:63], v[92:93], v[110:111]
	v_bfe_u32 v4, v107, 16, 1
	v_pk_mul_f32 v[22:23], v[22:23], v[92:93]
	v_mov_b32_e32 v92, v6
	v_mov_b32_e32 v93, v2
	v_pk_fma_f32 v[92:93], v[62:63], v[92:93], v[108:109]
	v_bfe_u32 v12, v22, 16, 1
	v_pk_mul_f32 v[26:27], v[26:27], v[92:93]
	v_bfe_u32 v6, v106, 16, 1
	v_bfe_u32 v2, v26, 16, 1
	v_bfe_u32 v15, v23, 16, 1
	v_add3_u32 v12, v22, v12, s36
	v_bfe_u32 v0, v27, 16, 1
	v_add3_u32 v6, v106, v6, s36
	v_add3_u32 v4, v107, v4, s36
	v_add3_u32 v2, v26, v2, s36
	v_add3_u32 v15, v23, v15, s36
	v_lshrrev_b32_e32 v12, 16, v12
	v_add3_u32 v0, v27, v0, s36
	v_lshrrev_b32_e32 v15, 16, v15
	v_and_or_b32 v94, v2, s29, v12
	v_and_or_b32 v93, v4, s29, v10
	v_and_or_b32 v92, v6, s29, v9
	v_mov_b32_e32 v12, v11
	v_mov_b32_e32 v9, v14
	v_and_b32_e32 v11, 0xffff0000, v19
	v_and_b32_e32 v10, 0xffff0000, v18
	v_and_or_b32 v95, v0, s29, v15
	v_pk_add_f32 v[8:9], v[12:13], v[8:9]
	v_pk_fma_f32 v[12:13], v[10:11], v[58:59], v[60:61]
	v_pk_fma_f32 v[14:15], v[24:25], v[58:59], v[60:61]
	v_mov_b32_e32 v18, v31
	v_mov_b32_e32 v19, v24
	v_pk_add_f32 v[22:23], v[88:89], v[100:101]
	v_pk_fma_f32 v[14:15], v[10:11], v[56:57], v[14:15]
	v_pk_fma_f32 v[12:13], v[18:19], v[56:57], v[12:13]
	v_pk_mov_b32 v[10:11], v[28:29], v[10:11] op_sel:[1,0]
	v_mov_b32_e32 v2, v7
	v_pk_fma_f32 v[10:11], v[10:11], v[54:55], v[12:13]
	v_pk_fma_f32 v[12:13], v[18:19], v[54:55], v[14:15]
	v_mov_b32_e32 v0, v5
	v_pk_fma_f32 v[2:3], v[62:63], v[2:3], v[22:23]
	v_pk_fma_f32 v[0:1], v[62:63], v[0:1], v[8:9]
	v_pk_mul_f32 v[2:3], v[12:13], v[2:3]
	v_pk_mul_f32 v[0:1], v[10:11], v[0:1]
	v_bfe_u32 v4, v3, 16, 1
	v_bfe_u32 v5, v2, 16, 1
	v_add3_u32 v2, v2, v5, s36
	v_add3_u32 v3, v3, v4, s36
	v_bfe_u32 v4, v16, 16, 1
	v_bfe_u32 v5, v17, 16, 1
	v_bfe_u32 v8, v0, 16, 1
	v_bfe_u32 v9, v1, 16, 1
	v_bfe_u32 v6, v21, 16, 1
	v_bfe_u32 v7, v20, 16, 1
	v_add3_u32 v1, v1, v9, s36
	v_add3_u32 v0, v0, v8, s36
	v_add3_u32 v5, v17, v5, s36
	v_add3_u32 v4, v16, v4, s36
	v_add3_u32 v7, v20, v7, s36
	v_add3_u32 v6, v21, v6, s36
	v_lshrrev_b32_e32 v4, 16, v4
	v_lshrrev_b32_e32 v5, 16, v5
	v_lshrrev_b32_e32 v0, 16, v0
	v_lshrrev_b32_e32 v1, 16, v1
	v_and_or_b32 v3, v3, s29, v1
	v_and_or_b32 v2, v2, s29, v0
	v_and_or_b32 v1, v6, s29, v5
	v_and_or_b32 v0, v7, s29, v4
	v_lshl_add_u64 v[4:5], v[84:85], 1, s[38:39]
	global_store_dwordx4 v[4:5], v[92:95], off
	v_lshl_add_u64 v[4:5], v[86:87], 1, s[38:39]
	global_store_dwordx4 v[4:5], v[0:3], off

; __device__ __forceinline__ float bf2f(bf16_t v) { return __uint_as_float((unsigned)v << 16); }
; __device__ __forceinline__ void conv8(const bf16_t* hyT, unsigned off, int t0, int L, float w0, float w1, float w2, float b, f32x4 (&o)[2]) {
;     const u32x4v raw = *(const u32x4v*)(hyT + (off + (unsigned)t0));
;     const float xm = t0 > 0 ? bf2f(hyT[off + (unsigned)t0 - 1u]) : 0.f, xp = t0 + 8 < L ? bf2f(hyT[off + (unsigned)t0 + 8u]) : 0.f;
.LBB0_347:
	v_mov_b32_e32 v130, v206
	v_mov_b32_e32 v2, 0
	v_add_u32_e32 v1, s90, v130
	v_add_u32_e32 v84, s94, v1
	v_cmp_lt_i32_e32 vcc, 0, v130
	v_add_u32_e32 v88, -1, v84
	v_mov_b32_e32 v0, 0
	s_and_saveexec_b64 s[4:5], vcc
	s_cbranch_execz .LBB0_349
	v_mov_b32_e32 v89, v33
	v_lshl_add_u64 v[4:5], v[88:89], 1, s[14:15]
	global_load_ushort v0, v[4:5], off
.LBB0_349:
	s_or_b64 exec, exec, s[4:5]
	v_add_u32_e32 v32, 8, v84
	v_cmp_gt_i32_e64 s[4:5], s0, v130
	v_lshl_add_u64 v[90:91], v[32:33], 1, s[14:15]
	s_and_saveexec_b64 s[6:7], s[4:5]
	s_cbranch_execz .LBB0_351
	global_load_ushort v2, v[90:91], off
.LBB0_351:
	s_or_b64 exec, exec, s[6:7]
	v_add_u32_e32 v86, s1, v1
	v_add_u32_e32 v32, -1, v86
	v_lshl_add_u64 v[92:93], v[32:33], 1, s[14:15]
	v_mov_b32_e32 v3, 0
	v_mov_b32_e32 v1, 0
	s_and_saveexec_b64 s[6:7], vcc
	s_cbranch_execz .LBB0_353
	global_load_ushort v1, v[92:93], off
.LBB0_353:
	s_or_b64 exec, exec, s[6:7]
	v_add_u32_e32 v32, 8, v86
	v_lshl_add_u64 v[94:95], v[32:33], 1, s[14:15]
	s_and_saveexec_b64 s[6:7], s[4:5]
	s_cbranch_execz .LBB0_355
	global_load_ushort v3, v[94:95], off
; #define LAS __attribute__((address_space(3)))
; __device__ __forceinline__ float bf2f(bf16_t v) { return __uint_as_float((unsigned)v << 16); }
; template <int R0> __device__ __forceinline__ void r0_fwd_store(LAS cf* X, const int N, int j0, const f32x4 (&ar)[R0 / 2][2], const f32x4 (&ai)[R0 / 2][2]) {
;     constexpr int q = 4096; const float rN = 1.0f / (float)N; asm volatile("" : "+v"(j0));
; #pragma unroll
;     for (int e = 0; e < 8; e += 2) {
;         cf y[R0][2];
; #pragma unroll
;         for (int h = 0; h < 2; ++h) { const int j = j0 + e + h; const cf w1 = twid((float)j * rN, false);
;             if constexpr (R0 == 4) { const cf a0 = cf{VEL(ar[0], e + h), VEL(ai[0], e + h)}, a1 = cf{VEL(ar[1], e + h), VEL(ai[1], e + h)}; const cf m = cf{a1.y, -a1.x};
;                 const cf w2 = cmul(w1, w1), w3 = cmul(w2, w1);
;                 y[0][h] = a0 + a1; y[1][h] = cmul(a0 + m, w1); y[2][h] = cmul(a0 - a1, w2); y[3][h] = cmul(a0 - m, w3); }
;             else { const cf a0 = cf{VEL(ar[0], e + h), VEL(ai[0], e + h)}; y[0][h] = a0; y[1][h] = cmul(a0, w1); } }
; #pragma unroll
;         for (int k = 0; k < R0; ++k) *(LAS f32x4*)(X + fphys(j0 + e + k * q)) = (f32x4){y[k][0].x, y[k][0].y, y[k][1].x, y[k][1].y};
;     }
; __device__ __forceinline__ void conv8(const bf16_t* hyT, unsigned off, int t0, int L, float w0, float w1, float w2, float b, f32x4 (&o)[2]) {
;     const u32x4v raw = *(const u32x4v*)(hyT + (off + (unsigned)t0));
;     const float xm = t0 > 0 ? bf2f(hyT[off + (unsigned)t0 - 1u]) : 0.f, xp = t0 + 8 < L ? bf2f(hyT[off + (unsigned)t0 + 8u]) : 0.f;
;     const float x0 = __uint_as_float(raw.x << 16), x1 = __uint_as_float(raw.x & 0xffff0000u), x2 = __uint_as_float(raw.y << 16), x3 = __uint_as_float(raw.y & 0xffff0000u);
;     const float x4 = __uint_as_float(raw.z << 16), x5 = __uint_as_float(raw.z & 0xffff0000u), x6 = __uint_as_float(raw.w << 16), x7 = __uint_as_float(raw.w & 0xffff0000u);
;     o[0][0] = fmaf(xm, w0, fmaf(x0, w1, fmaf(x1, w2, b))); o[0][1] = fmaf(x0, w0, fmaf(x1, w1, fmaf(x2, w2, b))); o[0][2] = fmaf(x1, w0, fmaf(x2, w1, fmaf(x3, w2, b))); o[0][3] = fmaf(x2, w0, fmaf(x3, w1, fmaf(x4, w2, b)));
;     o[1][0] = fmaf(x3, w0, fmaf(x4, w1, fmaf(x5, w2, b))); o[1][1] = fmaf(x4, w0, fmaf(x5, w1, fmaf(x6, w2, b))); o[1][2] = fmaf(x5, w0, fmaf(x6, w1, fmaf(x7, w2, b))); o[1][3] = fmaf(x6, w0, fmaf(x7, w1, fmaf(xp, w2, b)));
; }
.LBB0_355:
	s_or_b64 exec, exec, s[6:7]
	v_mov_b32_e32 v85, v33
	v_lshl_add_u64 v[96:97], v[84:85], 1, s[14:15]
	global_load_dwordx4 v[4:7], v[96:97], off
	v_mov_b32_e32 v87, v33
	v_lshl_add_u64 v[98:99], v[86:87], 1, s[14:15]
	global_load_dwordx4 v[16:19], v[98:99], off
	s_waitcnt vmcnt(0)
	v_lshlrev_b32_e32 v0, 16, v0
	v_lshlrev_b32_e32 v2, 16, v2
	v_lshlrev_b32_e32 v1, 16, v1
	v_lshlrev_b32_e32 v3, 16, v3
	v_fma_f32 v2, v2, v42, v44
	v_fma_f32 v3, v3, v42, v44
	v_mov_b32_e32 v32, v145
	s_waitcnt vmcnt(1)
	v_lshlrev_b32_e32 v9, 16, v5
	v_lshlrev_b32_e32 v8, 16, v4
	v_and_b32_e32 v4, 0xffff0000, v4
	v_fma_f32 v14, v9, v42, v44
	v_and_b32_e32 v5, 0xffff0000, v5
	v_fma_f32 v12, v4, v42, v44
	v_fmac_f32_e32 v14, v4, v40
	v_fmac_f32_e32 v12, v8, v40
	v_fmac_f32_e32 v14, v8, v38
	v_fma_f32 v8, v5, v42, v44
	v_and_b32_e32 v13, 0xffff0000, v6
	v_fmac_f32_e32 v8, v9, v40
	v_lshlrev_b32_e32 v11, 16, v6
	v_fmac_f32_e32 v8, v4, v38
	v_fma_f32 v4, v13, v42, v44
	v_lshlrev_b32_e32 v15, 16, v7
	v_and_b32_e32 v7, 0xffff0000, v7
	v_fma_f32 v10, v11, v42, v44
	v_fmac_f32_e32 v4, v11, v40
	v_fmac_f32_e32 v12, v0, v38
	v_fmac_f32_e32 v10, v5, v40
	v_fmac_f32_e32 v4, v5, v38
	v_fma_f32 v0, v7, v42, v44
	v_fmac_f32_e32 v2, v7, v40
	s_waitcnt vmcnt(0)
	v_lshlrev_b32_e32 v5, 16, v16
	v_and_b32_e32 v7, 0xffff0000, v16
	v_lshlrev_b32_e32 v16, 16, v17
	v_and_b32_e32 v17, 0xffff0000, v17
	v_fmac_f32_e32 v10, v9, v38
	v_fma_f32 v9, v17, v42, v44
	v_fma_f32 v6, v15, v42, v44
	v_fmac_f32_e32 v0, v15, v40
	v_fmac_f32_e32 v2, v15, v38
	v_lshlrev_b32_e32 v21, 16, v19
	v_fma_f32 v15, v16, v42, v44
	v_fmac_f32_e32 v9, v16, v40
	v_fmac_f32_e32 v6, v13, v40
	v_fmac_f32_e32 v0, v13, v38
	v_lshlrev_b32_e32 v20, 16, v18
	v_and_b32_e32 v18, 0xffff0000, v18
	v_fma_f32 v13, v7, v42, v44
	v_fmac_f32_e32 v15, v7, v40
	v_fmac_f32_e32 v9, v7, v38
	v_fma_f32 v7, v21, v42, v44
	v_fmac_f32_e32 v6, v11, v38
	v_fmac_f32_e32 v13, v5, v40
	v_fmac_f32_e32 v15, v5, v38
	v_fma_f32 v11, v20, v42, v44
	v_fma_f32 v5, v18, v42, v44
	v_fmac_f32_e32 v7, v18, v40
	v_fmac_f32_e32 v11, v17, v40
	v_fmac_f32_e32 v5, v20, v40
	v_fmac_f32_e32 v7, v20, v38
	v_mov_b32_e32 v20, v130
	v_fmac_f32_e32 v11, v16, v38
	v_and_b32_e32 v19, 0xffff0000, v19
	v_cvt_f32_i32_e32 v16, v20
	v_fmac_f32_e32 v13, v1, v38
	v_fma_f32 v1, v19, v42, v44
	v_fmac_f32_e32 v1, v21, v40
	v_mul_f32_e32 v16, v207, v16
	v_fmac_f32_e32 v1, v18, v38
	v_fmac_f32_e32 v3, v19, v40
	v_cos_f32_e32 v18, v16
	v_sin_f32_e64 v19, -v16
	v_fmac_f32_e32 v5, v17, v38
	s_nop 1
	v_fmac_f32_e32 v3, v21, v38
	v_pk_mul_f32 v[16:17], v[12:13], v[18:19] op_sel:[0,0] op_sel_hi:[0,1]
	v_ashrrev_i32_e32 v21, 4, v20
	v_pk_fma_f32 v[16:17], v[12:13], v[18:19], v[16:17] op_sel:[1,1,0] op_sel_hi:[1,0,1] neg_lo:[0,1,0]
	v_add_u32_e32 v18, 1, v20
	v_cvt_f32_i32_e32 v18, v18
	v_lshlrev_b32_e32 v21, 3, v21
	v_and_b32_e32 v21, -16, v21
	v_mul_f32_e32 v18, v207, v18
	v_cos_f32_e32 v22, v18
	v_sin_f32_e64 v23, -v18
	s_nop 1
	s_nop 0
	v_pk_mul_f32 v[18:19], v[14:15], v[22:23] op_sel:[0,0] op_sel_hi:[0,1]
	s_nop 0
	v_pk_fma_f32 v[18:19], v[14:15], v[22:23], v[18:19] op_sel:[1,1,0] op_sel_hi:[1,0,1] neg_lo:[0,1,0]
	v_lshlrev_b32_e32 v22, 3, v20
	v_add3_u32 v21, 0, v21, v22
	ds_write_b128 v21, v[12:15]
	v_add_u32_e32 v12, 0x1000, v20
	v_ashrrev_i32_e32 v12, 4, v12
	v_lshlrev_b32_e32 v12, 3, v12
	v_and_b32_e32 v12, -16, v12
	v_add3_u32 v12, 0, v12, v22
	ds_write_b128 v12, v[16:19] offset:32768
	v_add_u32_e32 v18, 2, v20
	v_cvt_f32_i32_e32 v12, v18
	v_mul_f32_e32 v12, v207, v12
	v_cos_f32_e32 v14, v12
	v_sin_f32_e64 v15, -v12
	s_nop 1
	s_nop 0
	v_pk_mul_f32 v[12:13], v[8:9], v[14:15] op_sel:[0,0] op_sel_hi:[0,1]
	s_nop 0
	v_pk_fma_f32 v[12:13], v[8:9], v[14:15], v[12:13] op_sel:[1,1,0] op_sel_hi:[1,0,1] neg_lo:[0,1,0]
	v_add_u32_e32 v14, 3, v20
	v_cvt_f32_i32_e32 v14, v14
	v_mul_f32_e32 v14, v207, v14
	v_cos_f32_e32 v16, v14
	v_sin_f32_e64 v17, -v14
	s_nop 1
	s_nop 0
	v_pk_mul_f32 v[14:15], v[10:11], v[16:17] op_sel:[0,0] op_sel_hi:[0,1]
	s_nop 0
	v_pk_fma_f32 v[14:15], v[10:11], v[16:17], v[14:15] op_sel:[1,1,0] op_sel_hi:[1,0,1] neg_lo:[0,1,0]
	v_ashrrev_i32_e32 v16, 4, v18
	v_lshlrev_b32_e32 v16, 3, v16
	v_and_b32_e32 v16, -16, v16
	v_add3_u32 v16, 0, v16, v22
	ds_write_b128 v16, v[8:11] offset:16
	v_add_u32_e32 v8, 0x1002, v20
	v_ashrrev_i32_e32 v8, 4, v8
	v_lshlrev_b32_e32 v8, 3, v8
	v_and_b32_e32 v8, -16, v8
	v_add3_u32 v8, 0, v8, v22
	ds_write_b128 v8, v[12:15] offset:32784
	v_add_u32_e32 v14, 4, v20
	v_cvt_f32_i32_e32 v8, v14
	v_mul_f32_e32 v8, v207, v8
	v_cos_f32_e32 v10, v8
	v_sin_f32_e64 v11, -v8
	s_nop 1
	s_nop 0
	v_pk_mul_f32 v[8:9], v[4:5], v[10:11] op_sel:[0,0] op_sel_hi:[0,1]
	s_nop 0
	v_pk_fma_f32 v[8:9], v[4:5], v[10:11], v[8:9] op_sel:[1,1,0] op_sel_hi:[1,0,1] neg_lo:[0,1,0]
	v_add_u32_e32 v10, 5, v20
	v_cvt_f32_i32_e32 v10, v10
	v_mul_f32_e32 v10, v207, v10
	v_cos_f32_e32 v12, v10
	v_sin_f32_e64 v13, -v10
	s_nop 1
	s_nop 0
	v_pk_mul_f32 v[10:11], v[6:7], v[12:13] op_sel:[0,0] op_sel_hi:[0,1]
	s_nop 0
	v_pk_fma_f32 v[10:11], v[6:7], v[12:13], v[10:11] op_sel:[1,1,0] op_sel_hi:[1,0,1] neg_lo:[0,1,0]
	v_ashrrev_i32_e32 v12, 4, v14
	v_lshlrev_b32_e32 v12, 3, v12
	v_and_b32_e32 v12, -16, v12
	v_add3_u32 v12, 0, v12, v22
	ds_write_b128 v12, v[4:7] offset:32
	v_add_u32_e32 v4, 0x1004, v20
	v_ashrrev_i32_e32 v4, 4, v4
	v_lshlrev_b32_e32 v4, 3, v4
	v_and_b32_e32 v4, -16, v4
	v_add3_u32 v4, 0, v4, v22
	ds_write_b128 v4, v[8:11] offset:32800
	v_add_u32_e32 v10, 6, v20
	v_cvt_f32_i32_e32 v4, v10
	v_mul_f32_e32 v4, v207, v4
	v_cos_f32_e32 v6, v4
	v_sin_f32_e64 v7, -v4
	s_nop 1
	s_nop 0
	v_pk_mul_f32 v[4:5], v[0:1], v[6:7] op_sel:[0,0] op_sel_hi:[0,1]
	s_nop 0
	v_pk_fma_f32 v[4:5], v[0:1], v[6:7], v[4:5] op_sel:[1,1,0] op_sel_hi:[1,0,1] neg_lo:[0,1,0]
	v_add_u32_e32 v6, 7, v20
	v_cvt_f32_i32_e32 v6, v6
	v_mul_f32_e32 v6, v207, v6
	v_cos_f32_e32 v8, v6
	v_sin_f32_e64 v9, -v6
	s_nop 1
	s_nop 0
	v_pk_mul_f32 v[6:7], v[2:3], v[8:9] op_sel:[0,0] op_sel_hi:[0,1]
	s_nop 0
	v_pk_fma_f32 v[6:7], v[2:3], v[8:9], v[6:7] op_sel:[1,1,0] op_sel_hi:[1,0,1] neg_lo:[0,1,0]
	v_ashrrev_i32_e32 v8, 4, v10
	v_lshlrev_b32_e32 v8, 3, v8
	v_and_b32_e32 v8, -16, v8
	v_add3_u32 v8, 0, v8, v22
	ds_write_b128 v8, v[0:3] offset:48
	v_add_u32_e32 v0, 0x1006, v20
	v_ashrrev_i32_e32 v0, 4, v0
	v_lshlrev_b32_e32 v0, 3, v0
	v_and_b32_e32 v0, -16, v0
	v_add3_u32 v0, 0, v0, v22
	ds_write_b128 v0, v[4:7] offset:32816
	s_waitcnt lgkmcnt(0)
	s_barrier
	s_nop 0
	v_cmp_gt_i32_e64 s[6:7], s34, v32
	s_and_saveexec_b64 s[8:9], s[6:7]
	s_xor_b64 s[8:9], exec, s[8:9]
	s_cbranch_execz .LBB0_359
	v_lshl_add_u32 v39, v32, 3, 0
	s_mov_b64 s[12:13], 0

; #define LAS __attribute__((address_space(3)))
; template <int R0> __device__ __forceinline__ void r0_inv_load(const LAS cf* X, const int N, int j0, f32x4 (&yr)[R0 / 2][2], f32x4 (&yi)[R0 / 2][2]) {
;     constexpr int q = 4096; const float rN = 1.0f / (float)N; asm volatile("" : "+v"(j0));
; #pragma unroll
;     for (int e = 0; e < 8; e += 2) {
;         f32x4 v[R0];
; #pragma unroll
;         for (int k = 0; k < R0; ++k) v[k] = *(const LAS f32x4*)(X + fphys(j0 + e + k * q));
; #pragma unroll
;         for (int h = 0; h < 2; ++h) { const int j = j0 + e + h; const cf w1 = twid((float)j * rN, true);
;             if constexpr (R0 == 4) { const cf w2 = cmul(w1, w1), w3 = cmul(w2, w1);
;                 const cf a0 = h ? cf{v[0].z, v[0].w} : cf{v[0].x, v[0].y}; const cf a1 = cmul(h ? cf{v[1].z, v[1].w} : cf{v[1].x, v[1].y}, w1);
;                 const cf a2 = cmul(h ? cf{v[2].z, v[2].w} : cf{v[2].x, v[2].y}, w2); const cf a3 = cmul(h ? cf{v[3].z, v[3].w} : cf{v[3].x, v[3].y}, w3);
;                 const cf t0 = a0 + a2, t1 = a0 - a2, t2 = a1 + a3, t3 = a1 - a3;
;                 VEL(yr[0], e + h) = t0.x + t2.x; VEL(yi[0], e + h) = t0.y + t2.y; VEL(yr[1], e + h) = t1.x - t3.y; VEL(yi[1], e + h) = t1.y + t3.x; }
;             else { const cf a0 = h ? cf{v[0].z, v[0].w} : cf{v[0].x, v[0].y}; const cf a1 = cmul(h ? cf{v[1].z, v[1].w} : cf{v[1].x, v[1].y}, w1);
;                 VEL(yr[0], e + h) = a0.x + a1.x; VEL(yi[0], e + h) = a0.y + a1.y; } }
;     }
; }
; __device__ __forceinline__ void conv8(const bf16_t* hyT, unsigned off, int t0, int L, float w0, float w1, float w2, float b, f32x4 (&o)[2]) {
;     const u32x4v raw = *(const u32x4v*)(hyT + (off + (unsigned)t0));
;     const float xm = t0 > 0 ? bf2f(hyT[off + (unsigned)t0 - 1u]) : 0.f, xp = t0 + 8 < L ? bf2f(hyT[off + (unsigned)t0 + 8u]) : 0.f;
; template <int R0> __device__ __forceinline__ void hy_pair(LAS cf* X, const int N, const int L, const int tid, const unsigned mA, const unsigned mB, const bf16_t* hyT, bf16_t* hyo, ...
;     ...
;         for (int n = 0; n < NL; ++n) { const int t0 = j0 + n * 4096; f32x4 va[2], vb[2], xa[2], xb[2];
;             conv8(hyT, ov + mA, t0, L, wv0, wv1, wv2, bv, va); conv8(hyT, ov + mB, t0, L, wv0, wv1, wv2, bv, vb);
;             conv8(hyT, oa + mA, t0, L, wa0, wa1, wa2, ba, xa); conv8(hyT, oa + mB, t0, L, wa0, wa1, wa2, ba, xb);
.LBB0_371:
	s_or_b64 exec, exec, s[8:9]
	v_mov_b32_e32 v22, v130
	s_waitcnt lgkmcnt(0)
	s_barrier
	v_mov_b32_e32 v116, 0
	v_cvt_f32_i32_e32 v8, v22
	v_add_u32_e32 v4, 0x1000, v22
	v_ashrrev_i32_e32 v0, 4, v22
	v_ashrrev_i32_e32 v4, 4, v4
	v_lshlrev_b32_e32 v0, 3, v0
	v_lshlrev_b32_e32 v4, 3, v4
	v_and_b32_e32 v0, -16, v0
	v_lshlrev_b32_e32 v18, 3, v22
	v_and_b32_e32 v4, -16, v4
	v_mul_f32_e32 v9, v207, v8
	v_add3_u32 v0, 0, v0, v18
	v_add3_u32 v4, 0, v4, v18
	v_cos_f32_e32 v8, v9
	v_sin_f32_e32 v9, v9
	ds_read_b128 v[0:3], v0
	ds_read_b128 v[4:7], v4 offset:32768
	s_nop 1
	v_add_u32_e32 v12, 2, v22
	s_waitcnt lgkmcnt(0)
	v_pk_mul_f32 v[100:101], v[4:5], v[8:9] op_sel:[0,0] op_sel_hi:[0,1]
	v_add_u32_e32 v16, 4, v22
	v_pk_fma_f32 v[100:101], v[4:5], v[8:9], v[100:101] op_sel:[1,1,0] op_sel_hi:[1,0,1] neg_lo:[0,1,0]
	v_add_u32_e32 v4, 1, v22
	v_cvt_f32_i32_e32 v4, v4
	v_add_u32_e32 v8, 0x1002, v22
	v_ashrrev_i32_e32 v8, 4, v8
	v_lshlrev_b32_e32 v8, 3, v8
	v_mul_f32_e32 v5, v207, v4
	v_cos_f32_e32 v4, v5
	v_sin_f32_e32 v5, v5
	s_nop 1
	v_and_b32_e32 v8, -16, v8
	v_pk_mul_f32 v[102:103], v[6:7], v[4:5] op_sel:[0,0] op_sel_hi:[0,1]
	v_add3_u32 v8, 0, v8, v18
	v_pk_fma_f32 v[102:103], v[6:7], v[4:5], v[102:103] op_sel:[1,1,0] op_sel_hi:[1,0,1] neg_lo:[0,1,0]
	v_ashrrev_i32_e32 v4, 4, v12
	v_cvt_f32_i32_e32 v12, v12
	v_lshlrev_b32_e32 v4, 3, v4
	v_and_b32_e32 v4, -16, v4
	v_add3_u32 v4, 0, v4, v18
	v_mul_f32_e32 v13, v207, v12
	v_cos_f32_e32 v12, v13
	v_sin_f32_e32 v13, v13
	ds_read_b128 v[4:7], v4 offset:16
	ds_read_b128 v[8:11], v8 offset:32784
	s_nop 1
	v_add_u32_e32 v20, 6, v22
	s_waitcnt lgkmcnt(0)
	v_pk_mul_f32 v[104:105], v[8:9], v[12:13] op_sel:[0,0] op_sel_hi:[0,1]
	s_nop 0
	v_pk_fma_f32 v[104:105], v[8:9], v[12:13], v[104:105] op_sel:[1,1,0] op_sel_hi:[1,0,1] neg_lo:[0,1,0]
	v_add_u32_e32 v8, 3, v22
	v_cvt_f32_i32_e32 v8, v8
	v_add_u32_e32 v12, 0x1004, v22
	v_ashrrev_i32_e32 v12, 4, v12
	v_lshlrev_b32_e32 v12, 3, v12
	v_mul_f32_e32 v9, v207, v8
	v_cos_f32_e32 v8, v9
	v_sin_f32_e32 v9, v9
	s_nop 1
	v_and_b32_e32 v12, -16, v12
	v_pk_mul_f32 v[106:107], v[10:11], v[8:9] op_sel:[0,0] op_sel_hi:[0,1]
	v_add3_u32 v12, 0, v12, v18
	v_pk_fma_f32 v[106:107], v[10:11], v[8:9], v[106:107] op_sel:[1,1,0] op_sel_hi:[1,0,1] neg_lo:[0,1,0]
	v_ashrrev_i32_e32 v8, 4, v16
	v_cvt_f32_i32_e32 v16, v16
	v_lshlrev_b32_e32 v8, 3, v8
	v_and_b32_e32 v8, -16, v8
	v_add3_u32 v8, 0, v8, v18
	v_mul_f32_e32 v17, v207, v16
	v_cos_f32_e32 v16, v17
	v_sin_f32_e32 v17, v17
	ds_read_b128 v[8:11], v8 offset:32
	ds_read_b128 v[12:15], v12 offset:32800
	s_nop 1
	s_waitcnt lgkmcnt(0)
	v_pk_mul_f32 v[108:109], v[12:13], v[16:17] op_sel:[0,0] op_sel_hi:[0,1]
	s_nop 0
	v_pk_fma_f32 v[108:109], v[12:13], v[16:17], v[108:109] op_sel:[1,1,0] op_sel_hi:[1,0,1] neg_lo:[0,1,0]
	v_add_u32_e32 v12, 5, v22
	v_cvt_f32_i32_e32 v12, v12
	v_add_u32_e32 v16, 0x1006, v22
	v_ashrrev_i32_e32 v16, 4, v16
	v_lshlrev_b32_e32 v16, 3, v16
	v_mul_f32_e32 v13, v207, v12
	v_cos_f32_e32 v12, v13
	v_sin_f32_e32 v13, v13
	s_nop 1
	v_and_b32_e32 v16, -16, v16
	v_pk_mul_f32 v[110:111], v[14:15], v[12:13] op_sel:[0,0] op_sel_hi:[0,1]
	v_add3_u32 v16, 0, v16, v18
	v_pk_fma_f32 v[110:111], v[14:15], v[12:13], v[110:111] op_sel:[1,1,0] op_sel_hi:[1,0,1] neg_lo:[0,1,0]
	v_ashrrev_i32_e32 v12, 4, v20
	v_cvt_f32_i32_e32 v20, v20
	v_lshlrev_b32_e32 v12, 3, v12
	v_and_b32_e32 v12, -16, v12
	v_add3_u32 v12, 0, v12, v18
	v_mul_f32_e32 v21, v207, v20
	v_cos_f32_e32 v20, v21
	v_sin_f32_e32 v21, v21
	ds_read_b128 v[12:15], v12 offset:48
	ds_read_b128 v[16:19], v16 offset:32816
	s_nop 1
	s_waitcnt lgkmcnt(0)
	v_pk_mul_f32 v[112:113], v[16:17], v[20:21] op_sel:[0,0] op_sel_hi:[0,1]
	s_nop 0
	v_pk_fma_f32 v[112:113], v[16:17], v[20:21], v[112:113] op_sel:[1,1,0] op_sel_hi:[1,0,1] neg_lo:[0,1,0]
	v_add_u32_e32 v16, 7, v22
	v_cvt_f32_i32_e32 v16, v16
	v_mul_f32_e32 v17, v207, v16
	v_cos_f32_e32 v16, v17
	v_sin_f32_e32 v17, v17
	s_nop 1
	s_nop 0
	v_pk_mul_f32 v[114:115], v[18:19], v[16:17] op_sel:[0,0] op_sel_hi:[0,1]
	s_nop 0
	v_pk_fma_f32 v[114:115], v[18:19], v[16:17], v[114:115] op_sel:[1,1,0] op_sel_hi:[1,0,1] neg_lo:[0,1,0]
	global_load_dwordx4 v[16:19], v[96:97], off
	v_mov_b32_e32 v97, 0
	s_and_saveexec_b64 s[6:7], vcc
	s_cbranch_execz .LBB0_373
	v_mov_b32_e32 v89, v33
	v_lshl_add_u64 v[20:21], v[88:89], 1, s[14:15]
	global_load_ushort v116, v[20:21], off
.LBB0_373:
	s_or_b64 exec, exec, s[6:7]
	s_and_saveexec_b64 s[6:7], s[4:5]
	s_cbranch_execz .LBB0_375
	global_load_ushort v97, v[90:91], off
.LBB0_375:
	s_or_b64 exec, exec, s[6:7]
	global_load_dwordx4 v[24:27], v[98:99], off
	v_mov_b32_e32 v99, 0
	v_mov_b32_e32 v118, 0
	s_and_saveexec_b64 s[6:7], vcc
	s_cbranch_execz .LBB0_377
	global_load_ushort v118, v[92:93], off
.LBB0_377:
	s_or_b64 exec, exec, s[6:7]
	s_and_saveexec_b64 s[6:7], s[4:5]
	s_cbranch_execz .LBB0_379
	global_load_ushort v99, v[94:95], off
.LBB0_379:
	s_or_b64 exec, exec, s[6:7]
	v_add_u32_e32 v127, s94, v130
	v_add_u32_e32 v32, s96, v127
	v_lshl_add_u64 v[20:21], v[32:33], 1, s[14:15]
	global_load_dwordx4 v[28:31], v[20:21], off
	v_mov_b32_e32 v93, 0
	v_mov_b32_e32 v94, 0
	s_and_saveexec_b64 s[6:7], vcc
	s_cbranch_execz .LBB0_381
	v_add_u32_e32 v20, -1, v32
	v_mov_b32_e32 v21, v33
	v_lshl_add_u64 v[20:21], v[20:21], 1, s[14:15]
	global_load_ushort v94, v[20:21], off
.LBB0_381:
	s_or_b64 exec, exec, s[6:7]
	s_and_saveexec_b64 s[6:7], s[4:5]
	s_cbranch_execz .LBB0_383
	v_add_u32_e32 v32, 8, v32
	v_lshl_add_u64 v[20:21], v[32:33], 1, s[14:15]
	global_load_ushort v93, v[20:21], off
; __device__ __forceinline__ float bf2f(bf16_t v) { return __uint_as_float((unsigned)v << 16); }
; __device__ __forceinline__ void conv8(const bf16_t* hyT, unsigned off, int t0, int L, float w0, float w1, float w2, float b, f32x4 (&o)[2]) {
;     const u32x4v raw = *(const u32x4v*)(hyT + (off + (unsigned)t0));
;     const float xm = t0 > 0 ? bf2f(hyT[off + (unsigned)t0 - 1u]) : 0.f, xp = t0 + 8 < L ? bf2f(hyT[off + (unsigned)t0 + 8u]) : 0.f;
;     const float x0 = __uint_as_float(raw.x << 16), x1 = __uint_as_float(raw.x & 0xffff0000u), x2 = __uint_as_float(raw.y << 16), x3 = __uint_as_float(raw.y & 0xffff0000u);
;     const float x4 = __uint_as_float(raw.z << 16), x5 = __uint_as_float(raw.z & 0xffff0000u), x6 = __uint_as_float(raw.w << 16), x7 = __uint_as_float(raw.w & 0xffff0000u);
;     o[0][0] = fmaf(xm, w0, fmaf(x0, w1, fmaf(x1, w2, b))); o[0][1] = fmaf(x0, w0, fmaf(x1, w1, fmaf(x2, w2, b))); o[0][2] = fmaf(x1, w0, fmaf(x2, w1, fmaf(x3, w2, b))); o[0][3] = fmaf(x2, w0, fmaf(x3, w1, fmaf(x4, w2, b)));
;     o[1][0] = fmaf(x3, w0, fmaf(x4, w1, fmaf(x5, w2, b))); o[1][1] = fmaf(x4, w0, fmaf(x5, w1, fmaf(x6, w2, b))); o[1][2] = fmaf(x5, w0, fmaf(x6, w1, fmaf(x7, w2, b))); o[1][3] = fmaf(x6, w0, fmaf(x7, w1, fmaf(xp, w2, b)));
; }
; template <int R0> __device__ __forceinline__ void hy_pair(LAS cf* X, const int N, const int L, const int tid, const unsigned mA, const unsigned mB, const bf16_t* hyT, bf16_t* hyo, ...
;     ...
;         for (int n = 0; n < NL; ++n) { const int t0 = j0 + n * 4096; f32x4 va[2], vb[2], xa[2], xb[2];
;             conv8(hyT, ov + mA, t0, L, wv0, wv1, wv2, bv, va); conv8(hyT, ov + mB, t0, L, wv0, wv1, wv2, bv, vb);
;             conv8(hyT, oa + mA, t0, L, wa0, wa1, wa2, ba, xa); conv8(hyT, oa + mB, t0, L, wa0, wa1, wa2, ba, xb);
; #pragma unroll
;             for (int q4 = 0; q4 < 2; ++q4) { yr[n][q4] = xa[q4] * (yr[n][q4] + va[q4] * d0); yi[n][q4] = xb[q4] * (yi[n][q4] + vb[q4] * d0); }
.LBB0_383:
	s_or_b64 exec, exec, s[6:7]
	v_add_u32_e32 v126, s1, v130
	v_add_u32_e32 v32, s96, v126
	v_lshl_add_u64 v[20:21], v[32:33], 1, s[14:15]
	global_load_dwordx4 v[20:23], v[20:21], off
	v_mov_b32_e32 v89, 0
	v_mov_b32_e32 v90, 0
	s_and_saveexec_b64 s[6:7], vcc
	s_cbranch_execz .LBB0_385
	v_add_u32_e32 v90, -1, v32
	v_mov_b32_e32 v91, v33
	v_lshl_add_u64 v[90:91], v[90:91], 1, s[14:15]
	global_load_ushort v90, v[90:91], off
.LBB0_385:
	s_or_b64 exec, exec, s[6:7]
	s_and_saveexec_b64 s[6:7], s[4:5]
	s_cbranch_execz .LBB0_387
	v_add_u32_e32 v32, 8, v32
	v_lshl_add_u64 v[88:89], v[32:33], 1, s[14:15]
	global_load_ushort v89, v[88:89], off
.LBB0_387:
	s_or_b64 exec, exec, s[6:7]
	s_waitcnt vmcnt(1)
	v_and_b32_e32 v123, 0xffff0000, v28
	v_and_b32_e32 v124, 0xffff0000, v29
	v_lshlrev_b32_e32 v121, 16, v29
	v_lshlrev_b32_e32 v122, 16, v28
	v_mov_b32_e32 v120, v123
	v_and_b32_e32 v125, 16, v30
	v_lshlrev_b32_e32 v29, 16, v30
	v_mov_b32_e32 v28, v124
	v_mov_b32_e32 v53, v52
	v_mov_b32_e32 v51, v50
	v_and_b32_e32 v128, 0xffff0000, v30
	v_pk_mov_b32 v[124:125], v[120:121], v[124:125] op_sel:[1,0]
	v_pk_fma_f32 v[132:133], v[28:29], v[50:51], v[52:53]
	v_pk_fma_f32 v[134:135], v[120:121], v[80:81], v[82:83]
	v_mov_b32_e32 v49, v48
	v_and_b32_e32 v92, 0xffff0000, v31
	v_mov_b32_e32 v95, v122
	v_and_b32_e32 v129, 16, v31
	v_lshlrev_b32_e32 v31, 16, v31
	v_mov_b32_e32 v30, v128
	v_pk_fma_f32 v[124:125], v[124:125], v[48:49], v[132:133]
	v_pk_fma_f32 v[122:123], v[122:123], v[78:79], v[134:135]
	v_mov_b32_e32 v47, v46
	v_pk_mov_b32 v[128:129], v[28:29], v[128:129] op_sel:[1,0]
	v_pk_fma_f32 v[120:121], v[120:121], v[46:47], v[124:125]
	s_waitcnt vmcnt(0)
	v_lshlrev_b32_e32 v116, 16, v116
	v_lshlrev_b32_e32 v97, 16, v97
	v_lshlrev_b32_e32 v118, 16, v118
	v_lshlrev_b32_e32 v99, 16, v99
	v_lshlrev_b32_e32 v94, 16, v94
	v_lshlrev_b32_e32 v93, 16, v93
	v_lshlrev_b32_e32 v90, 16, v90
	v_lshlrev_b32_e32 v89, 16, v89
	v_pk_fma_f32 v[94:95], v[94:95], v[76:77], v[122:123]
	v_mov_b32_e32 v122, v31
	v_mov_b32_e32 v123, v92
	v_pk_fma_f32 v[124:125], v[30:31], v[80:81], v[82:83]
	v_pk_fma_f32 v[92:93], v[92:93], v[50:51], v[52:53]
	v_mov_b32_e32 v45, v44
	v_pk_fma_f32 v[92:93], v[122:123], v[48:49], v[92:93]
	v_pk_fma_f32 v[122:123], v[128:129], v[78:79], v[124:125]
	v_pk_fma_f32 v[30:31], v[30:31], v[46:47], v[92:93]
	v_pk_fma_f32 v[28:29], v[28:29], v[76:77], v[122:123]
	v_and_b32_e32 v123, 0xffff0000, v24
	v_lshlrev_b32_e32 v93, 16, v25
	v_mov_b32_e32 v92, v123
	v_and_b32_e32 v124, 0xffff0000, v25
	v_lshlrev_b32_e32 v122, 16, v24
	v_and_b32_e32 v125, 16, v26
	v_lshlrev_b32_e32 v25, 16, v26
	v_mov_b32_e32 v24, v124
	v_mov_b32_e32 v43, v42
	v_pk_fma_f32 v[134:135], v[92:93], v[72:73], v[74:75]
	v_and_b32_e32 v98, 0xffff0000, v27
	v_mov_b32_e32 v119, v122
	v_and_b32_e32 v129, 16, v27
	v_and_b32_e32 v128, 0xffff0000, v26
	v_lshlrev_b32_e32 v27, 16, v27
	v_pk_mov_b32 v[124:125], v[92:93], v[124:125] op_sel:[1,0]
	v_pk_fma_f32 v[132:133], v[24:25], v[42:43], v[44:45]
	v_mov_b32_e32 v41, v40
	v_pk_fma_f32 v[122:123], v[122:123], v[70:71], v[134:135]
	v_mov_b32_e32 v26, v128
	v_pk_fma_f32 v[124:125], v[124:125], v[40:41], v[132:133]
	v_mov_b32_e32 v39, v38
	v_pk_fma_f32 v[118:119], v[118:119], v[68:69], v[122:123]
	v_mov_b32_e32 v122, v27
	v_mov_b32_e32 v123, v98
	v_pk_fma_f32 v[98:99], v[98:99], v[42:43], v[44:45]
	v_pk_mov_b32 v[128:129], v[24:25], v[128:129] op_sel:[1,0]
	v_pk_fma_f32 v[92:93], v[92:93], v[38:39], v[124:125]
	v_pk_fma_f32 v[124:125], v[26:27], v[72:73], v[74:75]
	v_pk_fma_f32 v[98:99], v[122:123], v[40:41], v[98:99]
	v_and_b32_e32 v123, 0xffff0000, v16
	v_pk_fma_f32 v[124:125], v[128:129], v[70:71], v[124:125]
	v_pk_fma_f32 v[26:27], v[26:27], v[38:39], v[98:99]
	v_lshlrev_b32_e32 v99, 16, v17
	v_mov_b32_e32 v98, v123
	v_pk_fma_f32 v[24:25], v[24:25], v[68:69], v[124:125]
	v_lshlrev_b32_e32 v122, 16, v16
	v_and_b32_e32 v124, 0xffff0000, v17
	v_pk_fma_f32 v[134:135], v[98:99], v[72:73], v[74:75]
	v_and_b32_e32 v96, 0xffff0000, v19
	v_mov_b32_e32 v117, v122
	v_and_b32_e32 v125, 16, v18
	v_lshlrev_b32_e32 v17, 16, v18
	v_mov_b32_e32 v16, v124
	v_and_b32_e32 v129, 16, v19
	v_lshlrev_b32_e32 v19, 16, v19
	v_pk_fma_f32 v[122:123], v[122:123], v[70:71], v[134:135]
	v_and_b32_e32 v128, 0xffff0000, v18
	v_pk_mov_b32 v[124:125], v[98:99], v[124:125] op_sel:[1,0]
	v_pk_fma_f32 v[132:133], v[16:17], v[42:43], v[44:45]
	v_pk_fma_f32 v[116:117], v[116:117], v[68:69], v[122:123]
	v_mov_b32_e32 v122, v19
	v_mov_b32_e32 v123, v96
	v_pk_fma_f32 v[96:97], v[96:97], v[42:43], v[44:45]
	v_mov_b32_e32 v18, v128
	v_pk_fma_f32 v[124:125], v[124:125], v[40:41], v[132:133]
	v_pk_fma_f32 v[96:97], v[122:123], v[40:41], v[96:97]
	v_pk_fma_f32 v[98:99], v[98:99], v[38:39], v[124:125]
	v_pk_fma_f32 v[124:125], v[18:19], v[72:73], v[74:75]
	v_pk_fma_f32 v[18:19], v[18:19], v[38:39], v[96:97]
	v_mov_b32_e32 v97, v2
	v_mov_b32_e32 v123, v102
	v_mov_b32_e32 v2, v1
	v_mov_b32_e32 v102, v101
	v_mov_b32_e32 v96, v0
	v_mov_b32_e32 v122, v100
	v_pk_add_f32 v[0:1], v[2:3], v[102:103]
	v_mov_b32_e32 v2, v4
	v_mov_b32_e32 v3, v6
	v_mov_b32_e32 v100, v104
	v_mov_b32_e32 v101, v106
	v_mov_b32_e32 v6, v5
	v_mov_b32_e32 v106, v105
	v_pk_add_f32 v[2:3], v[2:3], v[100:101]
	v_pk_add_f32 v[4:5], v[6:7], v[106:107]
	v_mov_b32_e32 v6, v8
	v_mov_b32_e32 v7, v10
	v_mov_b32_e32 v100, v108
	v_mov_b32_e32 v101, v110
	v_mov_b32_e32 v10, v9
	v_mov_b32_e32 v110, v109
	v_pk_add_f32 v[6:7], v[6:7], v[100:101]
	v_pk_add_f32 v[8:9], v[10:11], v[110:111]
	v_mov_b32_e32 v10, v12
	v_mov_b32_e32 v11, v14
	v_mov_b32_e32 v100, v112
	v_mov_b32_e32 v101, v114
	v_pk_add_f32 v[10:11], v[10:11], v[100:101]
	v_mov_b32_e32 v14, v13
	v_mov_b32_e32 v114, v113
	s_waitcnt vmcnt(0)
; template <int R0> __device__ __forceinline__ void r0_fwd_store(LAS cf* X, const int N, int j0, const f32x4 (&ar)[R0 / 2][2], const f32x4 (&ai)[R0 / 2][2]) {
;     ...
;         for (int h = 0; h < 2; ++h) { const int j = j0 + e + h; const cf w1 = twid((float)j * rN, false);
;             if constexpr (R0 == 4) { const cf a0 = cf{VEL(ar[0], e + h), VEL(ai[0], e + h)}, a1 = cf{VEL(ar[1], e + h), VEL(ai[1], e + h)}; const cf m = cf{a1.y, -a1.x};
;                 const cf w2 = cmul(w1, w1), w3 = cmul(w2, w1);
;                 y[0][h] = a0 + a1; y[1][h] = cmul(a0 + m, w1); y[2][h] = cmul(a0 - a1, w2); y[3][h] = cmul(a0 - m, w3); }
;             else { const cf a0 = cf{VEL(ar[0], e + h), VEL(ai[0], e + h)}; y[0][h] = a0; y[1][h] = cmul(a0, w1); } }
; __device__ __forceinline__ void conv8(const bf16_t* hyT, unsigned off, int t0, int L, float w0, float w1, float w2, float b, f32x4 (&o)[2]) {
;     ...
;     o[0][0] = fmaf(xm, w0, fmaf(x0, w1, fmaf(x1, w2, b))); o[0][1] = fmaf(x0, w0, fmaf(x1, w1, fmaf(x2, w2, b))); o[0][2] = fmaf(x1, w0, fmaf(x2, w1, fmaf(x3, w2, b))); o[0][3] = fmaf(x2, w0, fmaf(x3, w1, fmaf(x4, w2, b)));
;     o[1][0] = fmaf(x3, w0, fmaf(x4, w1, fmaf(x5, w2, b))); o[1][1] = fmaf(x4, w0, fmaf(x5, w1, fmaf(x6, w2, b))); o[1][2] = fmaf(x5, w0, fmaf(x6, w1, fmaf(x7, w2, b))); o[1][3] = fmaf(x6, w0, fmaf(x7, w1, fmaf(xp, w2, b)));
; template <int R0> __device__ __forceinline__ void hy_pair(LAS cf* X, const int N, const int L, const int tid, const unsigned mA, const unsigned mB, const bf16_t* hyT, bf16_t* hyo, ...
;     ...
; #pragma unroll
;             for (int q4 = 0; q4 < 2; ++q4) { yr[n][q4] = xa[q4] * (yr[n][q4] + va[q4] * d0); yi[n][q4] = xb[q4] * (yi[n][q4] + vb[q4] * d0); }
; #pragma unroll
;             for (int e = 0; e < 8; e += 2) ZS[(unsigned)((t0 + e) >> 1)] = (f32x4){VEL(yr[n], e), VEL(yi[n], e), VEL(yr[n], e + 1), VEL(yi[n], e + 1)}; }
;         r0_fwd_store<R0>(X, N, j0, yr, yi); }
	v_and_b32_e32 v101, 0xffff0000, v20
	v_pk_add_f32 v[12:13], v[14:15], v[114:115]
	v_lshlrev_b32_e32 v15, 16, v21
	v_mov_b32_e32 v14, v101
	v_and_b32_e32 v102, 0xffff0000, v21
	v_lshlrev_b32_e32 v100, 16, v20
	v_and_b32_e32 v103, 16, v22
	v_lshlrev_b32_e32 v21, 16, v22
	v_mov_b32_e32 v20, v102
	v_pk_fma_f32 v[108:109], v[14:15], v[80:81], v[82:83]
	v_pk_mov_b32 v[128:129], v[16:17], v[128:129] op_sel:[1,0]
	v_and_b32_e32 v88, 0xffff0000, v23
	v_mov_b32_e32 v91, v100
	v_and_b32_e32 v105, 16, v23
	v_and_b32_e32 v104, 0xffff0000, v22
	v_lshlrev_b32_e32 v23, 16, v23
	v_pk_mov_b32 v[102:103], v[14:15], v[102:103] op_sel:[1,0]
	v_pk_fma_f32 v[106:107], v[20:21], v[50:51], v[52:53]
	v_pk_fma_f32 v[100:101], v[100:101], v[78:79], v[108:109]
	v_pk_fma_f32 v[124:125], v[128:129], v[70:71], v[124:125]
	v_mov_b32_e32 v22, v104
	v_pk_fma_f32 v[102:103], v[102:103], v[48:49], v[106:107]
	v_pk_fma_f32 v[90:91], v[90:91], v[76:77], v[100:101]
	v_mov_b32_e32 v100, v23
	v_mov_b32_e32 v101, v88
	v_pk_fma_f32 v[88:89], v[88:89], v[50:51], v[52:53]
	v_mov_b32_e32 v65, v64
	v_pk_fma_f32 v[16:17], v[16:17], v[68:69], v[124:125]
	v_pk_add_f32 v[96:97], v[96:97], v[122:123]
	v_pk_mov_b32 v[104:105], v[20:21], v[104:105] op_sel:[1,0]
	v_pk_fma_f32 v[14:15], v[14:15], v[46:47], v[102:103]
	v_pk_fma_f32 v[102:103], v[22:23], v[80:81], v[82:83]
	v_pk_fma_f32 v[88:89], v[100:101], v[48:49], v[88:89]
	v_pk_fma_f32 v[2:3], v[64:65], v[98:99], v[2:3]
	v_pk_fma_f32 v[0:1], v[66:67], v[118:119], v[0:1]
	v_pk_fma_f32 v[100:101], v[104:105], v[78:79], v[102:103]
	v_pk_fma_f32 v[22:23], v[22:23], v[46:47], v[88:89]
	v_pk_fma_f32 v[88:89], v[66:67], v[116:117], v[96:97]
	v_pk_mul_f32 v[96:97], v[2:3], v[120:121]
	v_pk_fma_f32 v[2:3], v[64:65], v[92:93], v[4:5]
	v_pk_mul_f32 v[102:103], v[0:1], v[90:91]
	v_pk_fma_f32 v[0:1], v[66:67], v[16:17], v[6:7]
	v_ashrrev_i32_e32 v32, 1, v130
	v_add_u32_e32 v6, 2, v130
	v_pk_fma_f32 v[20:21], v[20:21], v[76:77], v[100:101]
	v_pk_mul_f32 v[100:101], v[2:3], v[14:15]
	v_pk_fma_f32 v[2:3], v[64:65], v[18:19], v[10:11]
	v_lshl_add_u64 v[92:93], v[32:33], 4, s[44:45]
	v_ashrrev_i32_e32 v32, 1, v6
	v_add_u32_e32 v10, 4, v130
	v_pk_mul_f32 v[98:99], v[88:89], v[94:95]
	v_pk_mul_f32 v[30:31], v[2:3], v[30:31]
	v_pk_mul_f32 v[28:29], v[0:1], v[28:29]
	v_pk_fma_f32 v[2:3], v[66:67], v[24:25], v[8:9]
	v_pk_fma_f32 v[0:1], v[64:65], v[26:27], v[12:13]
	v_lshl_add_u64 v[94:95], v[32:33], 4, s[44:45]
	v_ashrrev_i32_e32 v32, 1, v10
	v_add_u32_e32 v14, 6, v130
	v_pk_mul_f32 v[0:1], v[0:1], v[22:23]
	v_pk_mul_f32 v[22:23], v[2:3], v[20:21]
	v_lshl_add_u64 v[88:89], v[32:33], 4, s[44:45]
	v_ashrrev_i32_e32 v32, 1, v14
	v_mov_b32_e32 v2, v98
	v_mov_b32_e32 v3, v102
	v_mov_b32_e32 v4, v99
	v_mov_b32_e32 v5, v103
	v_mov_b32_e32 v6, v96
	v_mov_b32_e32 v7, v100
	v_mov_b32_e32 v8, v97
	v_mov_b32_e32 v9, v101
	v_mov_b32_e32 v10, v28
	v_mov_b32_e32 v11, v22
	v_mov_b32_e32 v12, v29
	v_mov_b32_e32 v13, v23
	v_lshl_add_u64 v[90:91], v[32:33], 4, s[44:45]
	v_mov_b32_e32 v14, v30
	v_mov_b32_e32 v15, v0
	v_mov_b32_e32 v16, v31
	v_mov_b32_e32 v17, v1
	v_mov_b32_e32 v32, v130
	global_store_dwordx4 v[92:93], v[2:5], off
	global_store_dwordx4 v[94:95], v[6:9], off
	global_store_dwordx4 v[88:89], v[10:13], off
	global_store_dwordx4 v[90:91], v[14:17], off
	v_mov_b32_e32 v24, v98
	v_cvt_f32_i32_e32 v18, v32
	v_mov_b32_e32 v25, v102
	v_mov_b32_e32 v102, v99
	v_mul_f32_e32 v18, v207, v18
	v_cos_f32_e32 v20, v18
	v_sin_f32_e64 v21, -v18
	v_add_u32_e32 v18, 1, v32
	v_cvt_f32_i32_e32 v18, v18
	s_nop 1
	v_mul_f32_e32 v18, v207, v18
	v_cos_f32_e32 v26, v18
	v_sin_f32_e64 v27, -v18
	v_pk_mul_f32 v[18:19], v[24:25], v[20:21] op_sel:[0,0] op_sel_hi:[0,1]
	s_nop 1
	s_nop 0
	v_pk_fma_f32 v[18:19], v[24:25], v[20:21], v[18:19] op_sel:[1,1,0] op_sel_hi:[1,0,1] neg_lo:[0,1,0]
; #define LAS __attribute__((address_space(3)))
; template <int R0> __device__ __forceinline__ void r0_fwd_store(LAS cf* X, const int N, int j0, const f32x4 (&ar)[R0 / 2][2], const f32x4 (&ai)[R0 / 2][2]) {
;     constexpr int q = 4096; const float rN = 1.0f / (float)N; asm volatile("" : "+v"(j0));
; #pragma unroll
;     for (int e = 0; e < 8; e += 2) {
;         cf y[R0][2];
; #pragma unroll
;         for (int h = 0; h < 2; ++h) { const int j = j0 + e + h; const cf w1 = twid((float)j * rN, false);
;             if constexpr (R0 == 4) { const cf a0 = cf{VEL(ar[0], e + h), VEL(ai[0], e + h)}, a1 = cf{VEL(ar[1], e + h), VEL(ai[1], e + h)}; const cf m = cf{a1.y, -a1.x};
;                 const cf w2 = cmul(w1, w1), w3 = cmul(w2, w1);
;                 y[0][h] = a0 + a1; y[1][h] = cmul(a0 + m, w1); y[2][h] = cmul(a0 - a1, w2); y[3][h] = cmul(a0 - m, w3); }
;             else { const cf a0 = cf{VEL(ar[0], e + h), VEL(ai[0], e + h)}; y[0][h] = a0; y[1][h] = cmul(a0, w1); } }
; #pragma unroll
;         for (int k = 0; k < R0; ++k) *(LAS f32x4*)(X + fphys(j0 + e + k * q)) = (f32x4){y[k][0].x, y[k][0].y, y[k][1].x, y[k][1].y};
;     }
; }
; __device__ __forceinline__ void fft_mid_chain(LAS cf* X, const int N, const f32x4* Kst, const float sc) {
;     __syncthreads();
;     stage16<4096, false>(X, N); __syncthreads();
	v_ashrrev_i32_e32 v24, 4, v32
	v_lshlrev_b32_e32 v24, 3, v24
	v_and_b32_e32 v24, -16, v24
	v_lshlrev_b32_e32 v25, 3, v32
	v_add3_u32 v24, 0, v24, v25
	ds_write_b128 v24, v[2:5]
	v_add_u32_e32 v24, 2, v32
	v_cvt_f32_i32_e32 v3, v24
	v_add_u32_e32 v2, 0x1000, v32
	v_ashrrev_i32_e32 v2, 4, v2
	v_lshlrev_b32_e32 v2, 3, v2
	v_mul_f32_e32 v3, v207, v3
	v_cos_f32_e32 v4, v3
	v_sin_f32_e64 v5, -v3
	v_add_u32_e32 v3, 3, v32
	v_cvt_f32_i32_e32 v3, v3
	v_and_b32_e32 v2, -16, v2
	v_pk_mul_f32 v[20:21], v[102:103], v[26:27] op_sel:[0,0] op_sel_hi:[0,1]
	v_add3_u32 v2, 0, v2, v25
	v_pk_fma_f32 v[20:21], v[102:103], v[26:27], v[20:21] op_sel:[1,1,0] op_sel_hi:[1,0,1] neg_lo:[0,1,0]
	ds_write_b128 v2, v[18:21] offset:32768
	v_mul_f32_e32 v2, v207, v3
	s_nop 1
	v_mov_b32_e32 v18, v96
	v_cos_f32_e32 v20, v2
	v_sin_f32_e64 v21, -v2
	v_mov_b32_e32 v19, v100
	v_pk_mul_f32 v[2:3], v[18:19], v[4:5] op_sel:[0,0] op_sel_hi:[0,1]
	s_nop 1
	v_mov_b32_e32 v100, v97
	v_pk_fma_f32 v[2:3], v[18:19], v[4:5], v[2:3] op_sel:[1,1,0] op_sel_hi:[1,0,1] neg_lo:[0,1,0]
	v_ashrrev_i32_e32 v18, 4, v24
	v_lshlrev_b32_e32 v18, 3, v18
	v_and_b32_e32 v18, -16, v18
	v_add3_u32 v18, 0, v18, v25
	ds_write_b128 v18, v[6:9] offset:16
	v_add_u32_e32 v18, 4, v32
	v_add_u32_e32 v6, 0x1002, v32
	v_cvt_f32_i32_e32 v7, v18
	v_add_u32_e32 v9, 5, v32
	v_ashrrev_i32_e32 v6, 4, v6
	v_cvt_f32_i32_e32 v9, v9
	v_lshlrev_b32_e32 v6, 3, v6
	v_and_b32_e32 v6, -16, v6
	v_pk_mul_f32 v[4:5], v[100:101], v[20:21] op_sel:[0,0] op_sel_hi:[0,1]
	v_add3_u32 v8, 0, v6, v25
	v_mul_f32_e32 v7, v207, v7
	v_pk_fma_f32 v[4:5], v[100:101], v[20:21], v[4:5] op_sel:[1,1,0] op_sel_hi:[1,0,1] neg_lo:[0,1,0]
	v_cos_f32_e32 v6, v7
	v_sin_f32_e64 v7, -v7
	ds_write_b128 v8, v[2:5] offset:32784
	v_mul_f32_e32 v2, v207, v9
	s_nop 1
	v_mov_b32_e32 v4, v28
	v_cos_f32_e32 v8, v2
	v_sin_f32_e64 v9, -v2
	v_mov_b32_e32 v5, v22
	v_pk_mul_f32 v[2:3], v[4:5], v[6:7] op_sel:[0,0] op_sel_hi:[0,1]
	s_nop 1
	v_mov_b32_e32 v22, v29
	v_pk_fma_f32 v[2:3], v[4:5], v[6:7], v[2:3] op_sel:[1,1,0] op_sel_hi:[1,0,1] neg_lo:[0,1,0]
	v_ashrrev_i32_e32 v6, 4, v18
	v_lshlrev_b32_e32 v6, 3, v6
	v_and_b32_e32 v6, -16, v6
	v_add3_u32 v6, 0, v6, v25
	v_pk_mul_f32 v[4:5], v[22:23], v[8:9] op_sel:[0,0] op_sel_hi:[0,1]
	ds_write_b128 v6, v[10:13] offset:32
	v_add_u32_e32 v10, 6, v32
	v_pk_fma_f32 v[4:5], v[22:23], v[8:9], v[4:5] op_sel:[1,1,0] op_sel_hi:[1,0,1] neg_lo:[0,1,0]
	v_add_u32_e32 v6, 0x1004, v32
	v_cvt_f32_i32_e32 v7, v10
	v_add_u32_e32 v9, 7, v32
	v_ashrrev_i32_e32 v6, 4, v6
	v_cvt_f32_i32_e32 v9, v9
	v_lshlrev_b32_e32 v6, 3, v6
	v_and_b32_e32 v6, -16, v6
	v_add3_u32 v8, 0, v6, v25
	v_mul_f32_e32 v7, v207, v7
	v_cos_f32_e32 v6, v7
	v_sin_f32_e64 v7, -v7
	ds_write_b128 v8, v[2:5] offset:32800
	v_mul_f32_e32 v2, v207, v9
	s_nop 1
	v_mov_b32_e32 v4, v30
	v_cos_f32_e32 v8, v2
	v_sin_f32_e64 v9, -v2
	v_mov_b32_e32 v5, v0
	v_pk_mul_f32 v[2:3], v[4:5], v[6:7] op_sel:[0,0] op_sel_hi:[0,1]
	s_nop 1
	v_mov_b32_e32 v0, v31
	v_pk_fma_f32 v[2:3], v[4:5], v[6:7], v[2:3] op_sel:[1,1,0] op_sel_hi:[1,0,1] neg_lo:[0,1,0]
	v_pk_mul_f32 v[4:5], v[0:1], v[8:9] op_sel:[0,0] op_sel_hi:[0,1]
	s_nop 0
	v_pk_fma_f32 v[4:5], v[0:1], v[8:9], v[4:5] op_sel:[1,1,0] op_sel_hi:[1,0,1] neg_lo:[0,1,0]
	v_ashrrev_i32_e32 v0, 4, v10
	v_lshlrev_b32_e32 v0, 3, v0
	v_and_b32_e32 v0, -16, v0
	v_add3_u32 v0, 0, v0, v25
	ds_write_b128 v0, v[14:17] offset:48
	v_add_u32_e32 v0, 0x1006, v32
	v_ashrrev_i32_e32 v0, 4, v0
	v_lshlrev_b32_e32 v0, 3, v0
	v_and_b32_e32 v0, -16, v0
	v_add3_u32 v0, 0, v0, v25
	v_mov_b32_e32 v32, v145
	ds_write_b128 v0, v[2:5] offset:32816
	s_waitcnt lgkmcnt(0)
	s_barrier
	s_nop 0
	v_cmp_gt_i32_e64 s[6:7], s34, v32
	s_and_saveexec_b64 s[8:9], s[6:7]
	s_xor_b64 s[8:9], exec, s[8:9]
	s_cbranch_execz .LBB0_391
	v_lshl_add_u32 v39, v32, 3, 0
	s_mov_b64 s[12:13], 0

; #define LAS __attribute__((address_space(3)))
; template <int R0> __device__ __forceinline__ void r0_inv_load(const LAS cf* X, const int N, int j0, f32x4 (&yr)[R0 / 2][2], f32x4 (&yi)[R0 / 2][2]) {
;     constexpr int q = 4096; const float rN = 1.0f / (float)N; asm volatile("" : "+v"(j0));
; #pragma unroll
;     for (int e = 0; e < 8; e += 2) {
;         f32x4 v[R0];
; #pragma unroll
;         for (int k = 0; k < R0; ++k) v[k] = *(const LAS f32x4*)(X + fphys(j0 + e + k * q));
; #pragma unroll
;         for (int h = 0; h < 2; ++h) { const int j = j0 + e + h; const cf w1 = twid((float)j * rN, true);
;             if constexpr (R0 == 4) { const cf w2 = cmul(w1, w1), w3 = cmul(w2, w1);
;                 const cf a0 = h ? cf{v[0].z, v[0].w} : cf{v[0].x, v[0].y}; const cf a1 = cmul(h ? cf{v[1].z, v[1].w} : cf{v[1].x, v[1].y}, w1);
;                 const cf a2 = cmul(h ? cf{v[2].z, v[2].w} : cf{v[2].x, v[2].y}, w2); const cf a3 = cmul(h ? cf{v[3].z, v[3].w} : cf{v[3].x, v[3].y}, w3);
;                 const cf t0 = a0 + a2, t1 = a0 - a2, t2 = a1 + a3, t3 = a1 - a3;
;                 VEL(yr[0], e + h) = t0.x + t2.x; VEL(yi[0], e + h) = t0.y + t2.y; VEL(yr[1], e + h) = t1.x - t3.y; VEL(yi[1], e + h) = t1.y + t3.x; }
;             else { const cf a0 = h ? cf{v[0].z, v[0].w} : cf{v[0].x, v[0].y}; const cf a1 = cmul(h ? cf{v[1].z, v[1].w} : cf{v[1].x, v[1].y}, w1);
;                 VEL(yr[0], e + h) = a0.x + a1.x; VEL(yi[0], e + h) = a0.y + a1.y; } }
; template <int R0> __device__ __forceinline__ void hy_pair(LAS cf* X, const int N, const int L, const int tid, const unsigned mA, const unsigned mB, const bf16_t* hyT, bf16_t* hyo, ...
;     ...
;     {   f32x4 yr[NL][2], yi[NL][2]; r0_inv_load<R0>(X, N, j0, yr, yi);
; #pragma unroll
;         for (int n = 0; n < NL; ++n) { const int t0 = j0 + n * 4096; f32x4 xa[2], xb[2];
;             conv8(hyT, ob + mA, t0, L, wb0, wb1, wb2, bb, xa); conv8(hyT, ob + mB, t0, L, wb0, wb1, wb2, bb, xb);
.LBB0_403:
	s_or_b64 exec, exec, s[8:9]
	s_waitcnt lgkmcnt(0)
	s_barrier
	v_add_u32_e32 v32, s89, v127
	v_ashrrev_i32_e32 v0, 4, v130
	v_lshlrev_b32_e32 v0, 3, v0
	v_and_b32_e32 v0, -16, v0
	v_lshlrev_b32_e32 v10, 3, v130
	v_add3_u32 v0, 0, v0, v10
	v_cvt_f32_i32_e32 v4, v130
	ds_read_b128 v[12:15], v0
	v_add_u32_e32 v0, 0x1000, v130
	v_ashrrev_i32_e32 v0, 4, v0
	v_lshlrev_b32_e32 v0, 3, v0
	v_and_b32_e32 v0, -16, v0
	v_mul_f32_e32 v5, v207, v4
	v_add3_u32 v0, 0, v0, v10
	v_cos_f32_e32 v4, v5
	v_sin_f32_e32 v5, v5
	ds_read_b128 v[0:3], v0 offset:32768
	s_nop 1
	v_add_u32_e32 v8, 4, v130
	s_waitcnt lgkmcnt(0)
	v_pk_mul_f32 v[100:101], v[0:1], v[4:5] op_sel:[0,0] op_sel_hi:[0,1]
	v_add_u32_e32 v16, 6, v130
	v_pk_fma_f32 v[100:101], v[0:1], v[4:5], v[100:101] op_sel:[1,1,0] op_sel_hi:[1,0,1] neg_lo:[0,1,0]
	v_add_u32_e32 v0, 1, v130
	v_cvt_f32_i32_e32 v0, v0
	v_add_u32_e32 v4, 2, v130
	v_mov_b32_e32 v105, 0
	v_mov_b32_e32 v98, 0
	v_mul_f32_e32 v1, v207, v0
	v_cos_f32_e32 v0, v1
	v_sin_f32_e32 v1, v1
	s_nop 1
	s_nop 0
	v_pk_mul_f32 v[106:107], v[2:3], v[0:1] op_sel:[0,0] op_sel_hi:[0,1]
	s_nop 0
	v_pk_fma_f32 v[106:107], v[2:3], v[0:1], v[106:107] op_sel:[1,1,0] op_sel_hi:[1,0,1] neg_lo:[0,1,0]
	v_ashrrev_i32_e32 v0, 4, v4
	v_lshlrev_b32_e32 v0, 3, v0
	v_and_b32_e32 v0, -16, v0
	v_add3_u32 v0, 0, v0, v10
	v_cvt_f32_i32_e32 v4, v4
	ds_read_b128 v[20:23], v0 offset:16
	v_add_u32_e32 v0, 0x1002, v130
	v_ashrrev_i32_e32 v0, 4, v0
	v_lshlrev_b32_e32 v0, 3, v0
	v_and_b32_e32 v0, -16, v0
	v_mul_f32_e32 v5, v207, v4
	v_add3_u32 v0, 0, v0, v10
	v_cos_f32_e32 v4, v5
	v_sin_f32_e32 v5, v5
	ds_read_b128 v[0:3], v0 offset:32784
	s_nop 1
	s_waitcnt lgkmcnt(0)
	v_pk_mul_f32 v[110:111], v[0:1], v[4:5] op_sel:[0,0] op_sel_hi:[0,1]
	s_nop 0
	v_pk_fma_f32 v[110:111], v[0:1], v[4:5], v[110:111] op_sel:[1,1,0] op_sel_hi:[1,0,1] neg_lo:[0,1,0]
	v_add_u32_e32 v0, 3, v130
	v_cvt_f32_i32_e32 v0, v0
	v_add_u32_e32 v4, 0x1004, v130
	v_ashrrev_i32_e32 v4, 4, v4
	v_lshlrev_b32_e32 v4, 3, v4
	v_mul_f32_e32 v1, v207, v0
	v_cos_f32_e32 v0, v1
	v_sin_f32_e32 v1, v1
	s_nop 1
	v_and_b32_e32 v4, -16, v4
	v_pk_mul_f32 v[114:115], v[2:3], v[0:1] op_sel:[0,0] op_sel_hi:[0,1]
	v_add3_u32 v4, 0, v4, v10
	v_pk_fma_f32 v[114:115], v[2:3], v[0:1], v[114:115] op_sel:[1,1,0] op_sel_hi:[1,0,1] neg_lo:[0,1,0]
	v_ashrrev_i32_e32 v0, 4, v8
	v_cvt_f32_i32_e32 v8, v8
	v_lshlrev_b32_e32 v0, 3, v0
	v_and_b32_e32 v0, -16, v0
	v_add3_u32 v0, 0, v0, v10
	v_mul_f32_e32 v9, v207, v8
	v_cos_f32_e32 v8, v9
	v_sin_f32_e32 v9, v9
	ds_read_b128 v[0:3], v0 offset:32
	ds_read_b128 v[4:7], v4 offset:32800
	s_nop 1
	s_waitcnt lgkmcnt(0)
	v_pk_mul_f32 v[24:25], v[4:5], v[8:9] op_sel:[0,0] op_sel_hi:[0,1]
	s_nop 0
	v_pk_fma_f32 v[24:25], v[4:5], v[8:9], v[24:25] op_sel:[1,1,0] op_sel_hi:[1,0,1] neg_lo:[0,1,0]
	v_add_u32_e32 v4, 5, v130
	v_cvt_f32_i32_e32 v4, v4
	v_add_u32_e32 v8, 0x1006, v130
	v_ashrrev_i32_e32 v8, 4, v8
	v_lshlrev_b32_e32 v8, 3, v8
	v_mul_f32_e32 v5, v207, v4
	v_cos_f32_e32 v4, v5
	v_sin_f32_e32 v5, v5
	s_nop 1
	v_and_b32_e32 v8, -16, v8
	v_pk_mul_f32 v[26:27], v[6:7], v[4:5] op_sel:[0,0] op_sel_hi:[0,1]
	v_add3_u32 v8, 0, v8, v10
	v_pk_fma_f32 v[26:27], v[6:7], v[4:5], v[26:27] op_sel:[1,1,0] op_sel_hi:[1,0,1] neg_lo:[0,1,0]
	v_ashrrev_i32_e32 v4, 4, v16
	v_cvt_f32_i32_e32 v16, v16
	v_lshlrev_b32_e32 v4, 3, v4
	v_and_b32_e32 v4, -16, v4
	v_add3_u32 v4, 0, v4, v10
	v_mul_f32_e32 v17, v207, v16
	v_cos_f32_e32 v16, v17
	v_sin_f32_e32 v17, v17
	ds_read_b128 v[4:7], v4 offset:48
	ds_read_b128 v[8:11], v8 offset:32816
	s_nop 1
	s_waitcnt lgkmcnt(0)
	v_pk_mul_f32 v[28:29], v[8:9], v[16:17] op_sel:[0,0] op_sel_hi:[0,1]
	s_nop 0
	v_pk_fma_f32 v[28:29], v[8:9], v[16:17], v[28:29] op_sel:[1,1,0] op_sel_hi:[1,0,1] neg_lo:[0,1,0]
	v_add_u32_e32 v8, 7, v130
	v_cvt_f32_i32_e32 v8, v8
	v_mul_f32_e32 v9, v207, v8
	v_cos_f32_e32 v8, v9
	v_sin_f32_e32 v9, v9
	s_nop 1
	s_nop 0
	v_pk_mul_f32 v[30:31], v[10:11], v[8:9] op_sel:[0,0] op_sel_hi:[0,1]
	s_nop 0
	v_pk_fma_f32 v[30:31], v[10:11], v[8:9], v[30:31] op_sel:[1,1,0] op_sel_hi:[1,0,1] neg_lo:[0,1,0]
	v_lshl_add_u64 v[8:9], v[32:33], 1, s[14:15]
	global_load_dwordx4 v[16:19], v[8:9], off
	s_and_saveexec_b64 s[6:7], vcc
	s_cbranch_execz .LBB0_405
	v_add_u32_e32 v8, -1, v32
	v_mov_b32_e32 v9, v33
	v_lshl_add_u64 v[8:9], v[8:9], 1, s[14:15]
	global_load_ushort v98, v[8:9], off
.LBB0_405:
	s_or_b64 exec, exec, s[6:7]
	s_and_saveexec_b64 s[6:7], s[4:5]
	s_cbranch_execz .LBB0_407
	v_add_u32_e32 v32, 8, v32
	v_lshl_add_u64 v[8:9], v[32:33], 1, s[14:15]
	global_load_ushort v105, v[8:9], off
.LBB0_407:
	s_or_b64 exec, exec, s[6:7]
	v_add_u32_e32 v32, s89, v126
	v_lshl_add_u64 v[8:9], v[32:33], 1, s[14:15]
	global_load_dwordx4 v[8:11], v[8:9], off
	v_mov_b32_e32 v97, 0
	v_mov_b32_e32 v116, 0
	s_and_saveexec_b64 s[6:7], vcc
	s_cbranch_execz .LBB0_409
	v_add_u32_e32 v102, -1, v32
	v_mov_b32_e32 v103, v33
	v_lshl_add_u64 v[102:103], v[102:103], 1, s[14:15]
	global_load_ushort v116, v[102:103], off
.LBB0_409:
	s_or_b64 exec, exec, s[6:7]
	s_and_saveexec_b64 s[6:7], s[4:5]
	s_cbranch_execz .LBB0_411
	v_add_u32_e32 v32, 8, v32
	v_lshl_add_u64 v[96:97], v[32:33], 1, s[14:15]
	global_load_ushort v97, v[96:97], off
; __device__ __forceinline__ float bf2f(bf16_t v) { return __uint_as_float((unsigned)v << 16); }
; __device__ __forceinline__ unsigned pk2(float lo, float hi) { return f2bf(lo) | (f2bf(hi) << 16); }
; __device__ __forceinline__ void conv8(const bf16_t* hyT, unsigned off, int t0, int L, float w0, float w1, float w2, float b, f32x4 (&o)[2]) {
;     const u32x4v raw = *(const u32x4v*)(hyT + (off + (unsigned)t0));
;     const float xm = t0 > 0 ? bf2f(hyT[off + (unsigned)t0 - 1u]) : 0.f, xp = t0 + 8 < L ? bf2f(hyT[off + (unsigned)t0 + 8u]) : 0.f;
;     const float x0 = __uint_as_float(raw.x << 16), x1 = __uint_as_float(raw.x & 0xffff0000u), x2 = __uint_as_float(raw.y << 16), x3 = __uint_as_float(raw.y & 0xffff0000u);
;     const float x4 = __uint_as_float(raw.z << 16), x5 = __uint_as_float(raw.z & 0xffff0000u), x6 = __uint_as_float(raw.w << 16), x7 = __uint_as_float(raw.w & 0xffff0000u);
;     o[0][0] = fmaf(xm, w0, fmaf(x0, w1, fmaf(x1, w2, b))); o[0][1] = fmaf(x0, w0, fmaf(x1, w1, fmaf(x2, w2, b))); o[0][2] = fmaf(x1, w0, fmaf(x2, w1, fmaf(x3, w2, b))); o[0][3] = fmaf(x2, w0, fmaf(x3, w1, fmaf(x4, w2, b)));
;     o[1][0] = fmaf(x3, w0, fmaf(x4, w1, fmaf(x5, w2, b))); o[1][1] = fmaf(x4, w0, fmaf(x5, w1, fmaf(x6, w2, b))); o[1][2] = fmaf(x5, w0, fmaf(x6, w1, fmaf(x7, w2, b))); o[1][3] = fmaf(x6, w0, fmaf(x7, w1, fmaf(xp, w2, b)));
; }
; template <int R0> __device__ __forceinline__ void hy_pair(LAS cf* X, const int N, const int L, const int tid, const unsigned mA, const unsigned mB, const bf16_t* hyT, bf16_t* hyo, ...
;     ...
;         for (int n = 0; n < NL; ++n) { const int t0 = j0 + n * 4096; f32x4 xa[2], xb[2];
;             conv8(hyT, ob + mA, t0, L, wb0, wb1, wb2, bb, xa); conv8(hyT, ob + mB, t0, L, wb0, wb1, wb2, bb, xb);
;             u32x4v oA, oB;
; #pragma unroll
;             for (int e = 0; e < 8; e += 2) { const f32x4 z = ZS[(unsigned)((t0 + e) >> 1)];
;                 oA[e >> 1] = pk2(VEL(xa, e) * (VEL(yr[n], e) + z.x * d1), VEL(xa, e + 1) * (VEL(yr[n], e + 1) + z.z * d1));
;                 oB[e >> 1] = pk2(VEL(xb, e) * (VEL(yi[n], e) + z.y * d1), VEL(xb, e + 1) * (VEL(yi[n], e + 1) + z.w * d1)); }
;             *(u32x4v*)(hyo + (ov + mA + (unsigned)t0)) = oA; *(u32x4v*)(hyo + (ov + mB + (unsigned)t0)) = oB; } }
.LBB0_411:
	s_or_b64 exec, exec, s[6:7]
	global_load_dwordx4 v[118:121], v[92:93], off
	global_load_dwordx4 v[122:125], v[94:95], off
	s_waitcnt vmcnt(3)
	v_lshlrev_b32_e32 v113, 16, v18
	v_lshlrev_b32_e32 v112, 16, v17
	v_lshlrev_b32_e32 v92, 16, v16
	v_and_b32_e32 v109, 0xffff0000, v17
	v_and_b32_e32 v108, 0xffff0000, v16
	v_pk_fma_f32 v[16:17], v[112:113], v[58:59], v[60:61]
	v_mov_b32_e32 v93, v112
	v_pk_fma_f32 v[16:17], v[108:109], v[56:57], v[16:17]
	v_pk_fma_f32 v[94:95], v[108:109], v[58:59], v[60:61]
	v_pk_fma_f32 v[16:17], v[92:93], v[54:55], v[16:17]
	v_pk_fma_f32 v[92:93], v[92:93], v[56:57], v[94:95]
	v_mov_b32_e32 v99, v108
	s_waitcnt vmcnt(0)
	v_lshlrev_b32_e32 v98, 16, v98
	v_lshlrev_b32_e32 v105, 16, v105
	v_lshlrev_b32_e32 v116, 16, v116
	v_lshlrev_b32_e32 v97, 16, v97
	v_pk_fma_f32 v[92:93], v[98:99], v[54:55], v[92:93]
	v_mov_b32_e32 v94, v14
	v_mov_b32_e32 v95, v22
	v_mov_b32_e32 v98, v106
	v_mov_b32_e32 v99, v114
	v_pk_add_f32 v[94:95], v[94:95], v[98:99]
	v_mov_b32_e32 v98, v12
	v_mov_b32_e32 v99, v20
	v_mov_b32_e32 v102, v100
	v_mov_b32_e32 v103, v110
	v_pk_add_f32 v[98:99], v[98:99], v[102:103]
	v_mov_b32_e32 v20, v13
	v_mov_b32_e32 v110, v101
	v_mov_b32_e32 v22, v15
	v_mov_b32_e32 v114, v107
	v_pk_add_f32 v[12:13], v[20:21], v[110:111]
	v_pk_add_f32 v[14:15], v[22:23], v[114:115]
	v_mov_b32_e32 v100, v2
	v_mov_b32_e32 v101, v6
	v_mov_b32_e32 v106, v26
	v_mov_b32_e32 v107, v30
	v_lshlrev_b32_e32 v104, 16, v19
	v_and_b32_e32 v19, 0xffff0000, v19
	v_and_b32_e32 v18, 0xffff0000, v18
	v_pk_add_f32 v[100:101], v[100:101], v[106:107]
	v_mov_b32_e32 v106, v0
	v_mov_b32_e32 v107, v4
	v_mov_b32_e32 v110, v24
	v_mov_b32_e32 v111, v28
	v_pk_add_f32 v[106:107], v[106:107], v[110:111]
	v_mov_b32_e32 v110, v113
	v_mov_b32_e32 v111, v104
	v_mov_b32_e32 v28, v25
	s_waitcnt vmcnt(2)
	v_lshlrev_b32_e32 v96, 16, v11
	v_mov_b32_e32 v30, v27
	s_waitcnt vmcnt(1)
	v_mov_b32_e32 v102, v118
	s_waitcnt vmcnt(0)
	v_mov_b32_e32 v103, v122
	v_pk_fma_f32 v[98:99], v[62:63], v[102:103], v[98:99]
	v_mov_b32_e32 v122, v119
	v_pk_mul_f32 v[98:99], v[92:93], v[98:99]
	v_mov_b32_e32 v92, v120
	v_mov_b32_e32 v93, v124
	v_pk_fma_f32 v[92:93], v[62:63], v[92:93], v[94:95]
	v_lshlrev_b32_e32 v95, 16, v10
	v_pk_mul_f32 v[102:103], v[16:17], v[92:93]
	v_lshlrev_b32_e32 v17, 16, v9
	v_and_b32_e32 v93, 0xffff0000, v9
	v_and_b32_e32 v92, 0xffff0000, v8
	v_lshlrev_b32_e32 v16, 16, v8
	v_mov_b32_e32 v94, v17
	v_pk_fma_f32 v[8:9], v[92:93], v[58:59], v[60:61]
	v_mov_b32_e32 v117, v92
	v_pk_fma_f32 v[8:9], v[16:17], v[56:57], v[8:9]
	v_pk_fma_f32 v[20:21], v[94:95], v[58:59], v[60:61]
	v_pk_fma_f32 v[8:9], v[116:117], v[54:55], v[8:9]
	v_pk_fma_f32 v[20:21], v[92:93], v[56:57], v[20:21]
	v_pk_fma_f32 v[12:13], v[62:63], v[122:123], v[12:13]
	v_mov_b32_e32 v124, v121
	v_pk_fma_f32 v[16:17], v[16:17], v[54:55], v[20:21]
	v_pk_mul_f32 v[8:9], v[8:9], v[12:13]
	v_pk_fma_f32 v[12:13], v[62:63], v[124:125], v[14:15]
	v_bfe_u32 v4, v103, 16, 1
	v_pk_mul_f32 v[16:17], v[16:17], v[12:13]
	global_load_dwordx4 v[20:23], v[88:89], off
	global_load_dwordx4 v[12:15], v[90:91], off
	v_pk_fma_f32 v[88:89], v[104:105], v[58:59], v[60:61]
	v_pk_fma_f32 v[90:91], v[18:19], v[58:59], v[60:61]
	v_pk_fma_f32 v[88:89], v[18:19], v[56:57], v[88:89]
	v_pk_fma_f32 v[90:91], v[110:111], v[56:57], v[90:91]
	v_pk_mov_b32 v[18:19], v[108:109], v[18:19] op_sel:[1,0]
	v_pk_fma_f32 v[88:89], v[110:111], v[54:55], v[88:89]
	v_pk_fma_f32 v[18:19], v[18:19], v[54:55], v[90:91]
	v_bfe_u32 v6, v102, 16, 1
	v_add3_u32 v4, v103, v4, s36
	v_add3_u32 v6, v102, v6, s36
	s_waitcnt vmcnt(1)
	v_mov_b32_e32 v90, v20
	s_waitcnt vmcnt(0)
	v_mov_b32_e32 v91, v12
	v_pk_fma_f32 v[90:91], v[62:63], v[90:91], v[106:107]
	v_bfe_u32 v12, v98, 16, 1
	v_pk_mul_f32 v[18:19], v[18:19], v[90:91]
	v_mov_b32_e32 v90, v22
	v_mov_b32_e32 v91, v14
	v_pk_fma_f32 v[90:91], v[62:63], v[90:91], v[100:101]
	v_bfe_u32 v14, v99, 16, 1
	v_pk_mul_f32 v[88:89], v[88:89], v[90:91]
	v_bfe_u32 v22, v19, 16, 1
	v_add3_u32 v14, v99, v14, s36
	v_bfe_u32 v0, v89, 16, 1
	v_bfe_u32 v20, v18, 16, 1
	v_add3_u32 v19, v19, v22, s36
	v_add3_u32 v12, v98, v12, s36
	v_lshrrev_b32_e32 v14, 16, v14
	v_bfe_u32 v2, v88, 16, 1
	v_add3_u32 v0, v89, v0, s36
	v_add3_u32 v18, v18, v20, s36
	v_lshrrev_b32_e32 v12, 16, v12
	v_lshrrev_b32_e32 v19, 16, v19
	v_and_or_b32 v89, v4, s29, v14
	v_mov_b32_e32 v4, v1
	v_add3_u32 v2, v88, v2, s36
	v_lshrrev_b32_e32 v18, 16, v18
	v_and_or_b32 v91, v0, s29, v19
	v_and_or_b32 v88, v6, s29, v12
	v_mov_b32_e32 v6, v3
	v_pk_add_f32 v[0:1], v[4:5], v[28:29]
	v_and_b32_e32 v5, 0xffff0000, v11
	v_and_b32_e32 v4, 0xffff0000, v10
	v_and_or_b32 v90, v2, s29, v18
	v_pk_add_f32 v[2:3], v[6:7], v[30:31]
	v_pk_fma_f32 v[6:7], v[4:5], v[58:59], v[60:61]
	v_pk_fma_f32 v[10:11], v[96:97], v[58:59], v[60:61]
	v_mov_b32_e32 v18, v95
	v_mov_b32_e32 v19, v96
	v_pk_fma_f32 v[10:11], v[4:5], v[56:57], v[10:11]
	v_pk_fma_f32 v[6:7], v[18:19], v[56:57], v[6:7]
	v_pk_mov_b32 v[4:5], v[92:93], v[4:5] op_sel:[1,0]
	v_mov_b32_e32 v14, v23
	v_pk_fma_f32 v[4:5], v[4:5], v[54:55], v[6:7]
	v_pk_fma_f32 v[6:7], v[18:19], v[54:55], v[10:11]
	v_mov_b32_e32 v12, v21
	v_pk_fma_f32 v[2:3], v[62:63], v[14:15], v[2:3]
	v_pk_fma_f32 v[0:1], v[62:63], v[12:13], v[0:1]
	v_pk_mul_f32 v[2:3], v[6:7], v[2:3]
	v_pk_mul_f32 v[0:1], v[4:5], v[0:1]
	v_bfe_u32 v4, v3, 16, 1
	v_bfe_u32 v5, v2, 16, 1
	v_add3_u32 v2, v2, v5, s36
	v_add3_u32 v3, v3, v4, s36
	v_bfe_u32 v4, v8, 16, 1
	v_bfe_u32 v5, v9, 16, 1
	v_bfe_u32 v10, v0, 16, 1
	v_bfe_u32 v11, v1, 16, 1
	v_bfe_u32 v6, v17, 16, 1
	v_bfe_u32 v7, v16, 16, 1
	v_add3_u32 v1, v1, v11, s36
	v_add3_u32 v0, v0, v10, s36
	v_add3_u32 v5, v9, v5, s36
	v_add3_u32 v4, v8, v4, s36
	v_add3_u32 v7, v16, v7, s36
	v_add3_u32 v6, v17, v6, s36
	v_lshrrev_b32_e32 v4, 16, v4
	v_lshrrev_b32_e32 v5, 16, v5
	v_lshrrev_b32_e32 v0, 16, v0
	v_lshrrev_b32_e32 v1, 16, v1
	v_and_or_b32 v3, v3, s29, v1
	v_and_or_b32 v2, v2, s29, v0
	v_and_or_b32 v1, v6, s29, v5
	v_and_or_b32 v0, v7, s29, v4
	v_lshl_add_u64 v[6:7], v[84:85], 1, s[38:39]
	v_lshl_add_u64 v[4:5], v[86:87], 1, s[38:39]
	global_store_dwordx4 v[6:7], v[88:91], off
	global_store_dwordx4 v[4:5], v[0:3], off
	s_branch .LBB0_344
; __device__ __forceinline__ float bf2f(bf16_t v) { return __uint_as_float((unsigned)v << 16); }
; __device__ __forceinline__ void conv8(const bf16_t* hyT, unsigned off, int t0, int L, float w0, float w1, float w2, float b, f32x4 (&o)[2]) {
;     const u32x4v raw = *(const u32x4v*)(hyT + (off + (unsigned)t0));
;     const float xm = t0 > 0 ? bf2f(hyT[off + (unsigned)t0 - 1u]) : 0.f, xp = t0 + 8 < L ? bf2f(hyT[off + (unsigned)t0 + 8u]) : 0.f;
;     const float x0 = __uint_as_float(raw.x << 16), x1 = __uint_as_float(raw.x & 0xffff0000u), x2 = __uint_as_float(raw.y << 16), x3 = __uint_as_float(raw.y & 0xffff0000u);
;     const float x4 = __uint_as_float(raw.z << 16), x5 = __uint_as_float(raw.z & 0xffff0000u), x6 = __uint_as_float(raw.w << 16), x7 = __uint_as_float(raw.w & 0xffff0000u);
;     o[0][0] = fmaf(xm, w0, fmaf(x0, w1, fmaf(x1, w2, b))); o[0][1] = fmaf(x0, w0, fmaf(x1, w1, fmaf(x2, w2, b))); o[0][2] = fmaf(x1, w0, fmaf(x2, w1, fmaf(x3, w2, b))); o[0][3] = fmaf(x2, w0, fmaf(x3, w1, fmaf(x4, w2, b)));
;     o[1][0] = fmaf(x3, w0, fmaf(x4, w1, fmaf(x5, w2, b))); o[1][1] = fmaf(x4, w0, fmaf(x5, w1, fmaf(x6, w2, b))); o[1][2] = fmaf(x5, w0, fmaf(x6, w1, fmaf(x7, w2, b))); o[1][3] = fmaf(x6, w0, fmaf(x7, w1, fmaf(xp, w2, b)));
; }
; template <int R0> __device__ __forceinline__ void hy_pair(LAS cf* X, const int N, const int L, const int tid, const unsigned mA, const unsigned mB, const bf16_t* hyT, bf16_t* hyo, ...
;     constexpr int NL = R0 / 2; int j0 = 8 * tid; asm volatile("" : "+v"(j0));
;     {   f32x4 vr[NL][2], vi[NL][2];
; #pragma unroll
;         for (int n = 0; n < NL; ++n) { conv8(hyT, ov + mA, j0 + n * 4096, L, wv0, wv1, wv2, bv, vr[n]); conv8(hyT, ov + mB, j0 + n * 4096, L, wv0, wv1, wv2, bv, vi[n]); }
;         r0_fwd_store<R0>(X, N, j0, vr, vi); }
.LBB0_412:
	v_mov_b32_e32 v209, v206
	s_add_i32 s12, s94, s90
	v_mov_b32_e32 v89, v33
	v_add_u32_e32 v88, s12, v209
	v_lshl_add_u64 v[114:115], v[88:89], 1, s[14:15]
	global_load_dwordx4 v[0:3], v[114:115], off
	v_cmp_lt_i32_e64 s[6:7], 0, v209
	v_mov_b32_e32 v17, 0
	v_add_u32_e32 v100, -1, v88
	v_mov_b32_e32 v19, 0
	s_and_saveexec_b64 s[4:5], s[6:7]
	s_cbranch_execz .LBB0_414
	v_mov_b32_e32 v101, v33
	v_lshl_add_u64 v[4:5], v[100:101], 1, s[14:15]
	global_load_ushort v19, v[4:5], off
.LBB0_414:
	s_or_b64 exec, exec, s[4:5]
	v_cmp_gt_i32_e64 s[8:9], s0, v209
	v_add_u32_e32 v102, 8, v88
	s_and_saveexec_b64 s[4:5], s[8:9]
	s_cbranch_execz .LBB0_416
	v_mov_b32_e32 v103, v33
	v_lshl_add_u64 v[4:5], v[102:103], 1, s[14:15]
	global_load_ushort v17, v[4:5], off
.LBB0_416:
	s_or_b64 exec, exec, s[4:5]
	s_add_i32 s48, s1, s90
	v_add_u32_e32 v90, s48, v209
	v_mov_b32_e32 v91, v33
	v_lshl_add_u64 v[112:113], v[90:91], 1, s[14:15]
	global_load_dwordx4 v[8:11], v[112:113], off
	v_mov_b32_e32 v20, 0
	v_add_u32_e32 v104, -1, v90
	v_mov_b32_e32 v21, 0
	s_and_saveexec_b64 s[4:5], s[6:7]
	s_cbranch_execz .LBB0_418
	v_mov_b32_e32 v105, v33
	v_lshl_add_u64 v[4:5], v[104:105], 1, s[14:15]
	global_load_ushort v21, v[4:5], off
.LBB0_418:
	s_or_b64 exec, exec, s[4:5]
	v_add_u32_e32 v106, 8, v90
	s_and_saveexec_b64 s[4:5], s[8:9]
	s_cbranch_execz .LBB0_420
	v_mov_b32_e32 v107, v33
	v_lshl_add_u64 v[4:5], v[106:107], 1, s[14:15]
	global_load_ushort v20, v[4:5], off
.LBB0_420:
	s_or_b64 exec, exec, s[4:5]
	v_add_u32_e32 v208, 0x1000, v209
	v_add_u32_e32 v84, s12, v208
	v_mov_b32_e32 v85, v33
	v_lshl_add_u64 v[96:97], v[84:85], 1, s[14:15]
	global_load_dwordx4 v[12:15], v[96:97], off
	s_movk_i32 s4, 0xf000
	v_cmp_lt_i32_e32 vcc, s4, v209
	v_mov_b32_e32 v22, 0
	v_add_u32_e32 v92, -1, v84
	v_mov_b32_e32 v16, 0
	s_and_saveexec_b64 s[4:5], vcc
	s_cbranch_execz .LBB0_422
	v_mov_b32_e32 v93, v33
	v_lshl_add_u64 v[4:5], v[92:93], 1, s[14:15]
	global_load_ushort v16, v[4:5], off
.LBB0_422:
	s_or_b64 exec, exec, s[4:5]
	v_cmp_gt_i32_e64 s[4:5], s0, v208
	v_add_u32_e32 v94, 8, v84
	s_and_saveexec_b64 s[12:13], s[4:5]
	s_cbranch_execz .LBB0_424
	v_mov_b32_e32 v95, v33
	v_lshl_add_u64 v[4:5], v[94:95], 1, s[14:15]
	global_load_ushort v22, v[4:5], off
.LBB0_424:
	s_or_b64 exec, exec, s[12:13]
	v_add_u32_e32 v86, s48, v208
	v_mov_b32_e32 v87, v33
	v_lshl_add_u64 v[110:111], v[86:87], 1, s[14:15]
	global_load_dwordx4 v[4:7], v[110:111], off
	v_mov_b32_e32 v32, 0
	v_add_u32_e32 v98, -1, v86
	v_mov_b32_e32 v25, 0
	s_and_saveexec_b64 s[12:13], vcc
	s_cbranch_execz .LBB0_426
	v_mov_b32_e32 v99, v33
	v_lshl_add_u64 v[24:25], v[98:99], 1, s[14:15]
	global_load_ushort v25, v[24:25], off
.LBB0_426:
	s_or_b64 exec, exec, s[12:13]
	v_add_u32_e32 v108, 8, v86
	s_and_saveexec_b64 s[12:13], s[4:5]
	s_cbranch_execz .LBB0_428
	v_mov_b32_e32 v109, v33
	v_lshl_add_u64 v[26:27], v[108:109], 1, s[14:15]
	global_load_ushort v32, v[26:27], off
.LBB0_428:
	s_or_b64 exec, exec, s[12:13]
	s_waitcnt vmcnt(1)
	v_lshlrev_b32_e32 v23, 16, v13
	v_lshlrev_b32_e32 v18, 16, v12
	v_and_b32_e32 v12, 0xffff0000, v12
	v_and_b32_e32 v13, 0xffff0000, v13
	v_fma_f32 v116, v23, v42, v44
	v_and_b32_e32 v28, 0xffff0000, v14
	v_fma_f32 v120, v12, v42, v44
	v_fmac_f32_e32 v116, v12, v40
	v_fma_f32 v26, v13, v42, v44
	v_lshlrev_b32_e32 v27, 16, v14
	v_lshlrev_b32_e32 v29, 16, v15
	v_and_b32_e32 v15, 0xffff0000, v15
	v_fmac_f32_e32 v120, v18, v40
	v_fmac_f32_e32 v116, v18, v38
	v_fmac_f32_e32 v26, v23, v40
	v_fma_f32 v18, v28, v42, v44
	v_fmac_f32_e32 v26, v12, v38
	v_fma_f32 v24, v27, v42, v44
	v_fmac_f32_e32 v18, v27, v40
	v_fma_f32 v14, v15, v42, v44
	s_waitcnt vmcnt(0)
	v_lshlrev_b32_e32 v19, 16, v19
	v_lshlrev_b32_e32 v17, 16, v17
	v_lshlrev_b32_e32 v21, 16, v21
	v_lshlrev_b32_e32 v20, 16, v20
	v_lshlrev_b32_e32 v16, 16, v16
	v_lshlrev_b32_e32 v22, 16, v22
	v_lshlrev_b32_e32 v25, 16, v25
	v_lshlrev_b32_e32 v32, 16, v32
	v_fma_f32 v12, v22, v42, v44
	v_fmac_f32_e32 v120, v16, v38
	v_fmac_f32_e32 v24, v13, v40
	v_fmac_f32_e32 v18, v13, v38
	v_fma_f32 v16, v29, v42, v44
	v_fmac_f32_e32 v14, v29, v40
	v_fmac_f32_e32 v12, v15, v40
	v_lshlrev_b32_e32 v13, 16, v8
	v_and_b32_e32 v8, 0xffff0000, v8
	v_lshlrev_b32_e32 v15, 16, v9
	v_lshlrev_b32_e32 v22, 16, v10
	v_and_b32_e32 v10, 0xffff0000, v10
	v_fmac_f32_e32 v24, v23, v38
	v_fmac_f32_e32 v16, v28, v40
	v_fmac_f32_e32 v14, v28, v38
	v_and_b32_e32 v28, 0xffff0000, v11
	v_fma_f32 v125, v8, v42, v44
	v_fma_f32 v129, v15, v42, v44
	v_fma_f32 v23, v10, v42, v44
	v_fmac_f32_e32 v16, v27, v38
	v_fmac_f32_e32 v12, v29, v38
	v_and_b32_e32 v9, 0xffff0000, v9
	v_lshlrev_b32_e32 v27, 16, v11
	v_fmac_f32_e32 v125, v13, v40
	v_fmac_f32_e32 v129, v8, v40
	v_fma_f32 v29, v22, v42, v44
	v_fmac_f32_e32 v23, v22, v40
	v_fma_f32 v11, v28, v42, v44
	v_fmac_f32_e32 v125, v21, v38
	v_fmac_f32_e32 v129, v13, v38
	v_fma_f32 v31, v9, v42, v44
	v_fmac_f32_e32 v29, v9, v40
	v_fmac_f32_e32 v23, v9, v38
	v_fma_f32 v21, v27, v42, v44
	v_fmac_f32_e32 v11, v27, v40
	v_fma_f32 v9, v20, v42, v44
	v_lshlrev_b32_e32 v13, 16, v2
	v_fmac_f32_e32 v21, v10, v40
	v_fmac_f32_e32 v11, v10, v38
	v_fmac_f32_e32 v9, v28, v40
	v_lshlrev_b32_e32 v10, 16, v1
	v_and_b32_e32 v1, 0xffff0000, v1
	v_fma_f32 v28, v13, v42, v44
	v_fmac_f32_e32 v31, v15, v40
	v_fmac_f32_e32 v29, v15, v38
	v_lshlrev_b32_e32 v15, 16, v3
	v_and_b32_e32 v3, 0xffff0000, v3
	v_fma_f32 v30, v1, v42, v44
	v_fmac_f32_e32 v28, v1, v40
	v_fmac_f32_e32 v31, v8, v38
	v_lshlrev_b32_e32 v8, 16, v0
	v_and_b32_e32 v0, 0xffff0000, v0
	v_and_b32_e32 v2, 0xffff0000, v2
	v_fma_f32 v128, v10, v42, v44
	v_fmac_f32_e32 v30, v10, v40
	v_fmac_f32_e32 v28, v10, v38
	v_fma_f32 v10, v3, v42, v44
	v_fmac_f32_e32 v21, v22, v38
	v_fma_f32 v124, v0, v42, v44
	v_fmac_f32_e32 v128, v0, v40
	v_fma_f32 v22, v2, v42, v44
	v_fma_f32 v20, v15, v42, v44
	v_fmac_f32_e32 v10, v15, v40
	v_fmac_f32_e32 v124, v8, v40
	v_fmac_f32_e32 v128, v8, v38
	v_fmac_f32_e32 v22, v13, v40
	v_fmac_f32_e32 v20, v2, v40
	v_fmac_f32_e32 v10, v2, v38
	v_fma_f32 v8, v17, v42, v44
	s_waitcnt vmcnt(0)
; #define LAS __attribute__((address_space(3)))
; template <int R0> __device__ __forceinline__ void r0_fwd_store(LAS cf* X, const int N, int j0, const f32x4 (&ar)[R0 / 2][2], const f32x4 (&ai)[R0 / 2][2]) {
;     constexpr int q = 4096; const float rN = 1.0f / (float)N; asm volatile("" : "+v"(j0));
; #pragma unroll
;     for (int e = 0; e < 8; e += 2) {
;         cf y[R0][2];
; #pragma unroll
;         for (int h = 0; h < 2; ++h) { const int j = j0 + e + h; const cf w1 = twid((float)j * rN, false);
;             if constexpr (R0 == 4) { const cf a0 = cf{VEL(ar[0], e + h), VEL(ai[0], e + h)}, a1 = cf{VEL(ar[1], e + h), VEL(ai[1], e + h)}; const cf m = cf{a1.y, -a1.x};
;                 const cf w2 = cmul(w1, w1), w3 = cmul(w2, w1);
;                 y[0][h] = a0 + a1; y[1][h] = cmul(a0 + m, w1); y[2][h] = cmul(a0 - a1, w2); y[3][h] = cmul(a0 - m, w3); }
;             else { const cf a0 = cf{VEL(ar[0], e + h), VEL(ai[0], e + h)}; y[0][h] = a0; y[1][h] = cmul(a0, w1); } }
; #pragma unroll
;         for (int k = 0; k < R0; ++k) *(LAS f32x4*)(X + fphys(j0 + e + k * q)) = (f32x4){y[k][0].x, y[k][0].y, y[k][1].x, y[k][1].y};
;     }
; __device__ __forceinline__ void conv8(const bf16_t* hyT, unsigned off, int t0, int L, float w0, float w1, float w2, float b, f32x4 (&o)[2]) {
;     ...
;     o[0][0] = fmaf(xm, w0, fmaf(x0, w1, fmaf(x1, w2, b))); o[0][1] = fmaf(x0, w0, fmaf(x1, w1, fmaf(x2, w2, b))); o[0][2] = fmaf(x1, w0, fmaf(x2, w1, fmaf(x3, w2, b))); o[0][3] = fmaf(x2, w0, fmaf(x3, w1, fmaf(x4, w2, b)));
;     o[1][0] = fmaf(x3, w0, fmaf(x4, w1, fmaf(x5, w2, b))); o[1][1] = fmaf(x4, w0, fmaf(x5, w1, fmaf(x6, w2, b))); o[1][2] = fmaf(x5, w0, fmaf(x6, w1, fmaf(x7, w2, b))); o[1][3] = fmaf(x6, w0, fmaf(x7, w1, fmaf(xp, w2, b)));
	v_lshlrev_b32_e32 v2, 16, v5
	v_fmac_f32_e32 v22, v1, v38
	v_fmac_f32_e32 v8, v3, v40
	v_and_b32_e32 v1, 0xffff0000, v4
	v_and_b32_e32 v3, 0xffff0000, v5
	v_fma_f32 v117, v2, v42, v44
	v_fmac_f32_e32 v9, v27, v38
	v_fmac_f32_e32 v30, v0, v38
	v_lshlrev_b32_e32 v0, 16, v4
	v_fma_f32 v121, v1, v42, v44
	v_fmac_f32_e32 v117, v1, v40
	v_fma_f32 v27, v3, v42, v44
	v_fmac_f32_e32 v121, v0, v40
	v_fmac_f32_e32 v117, v0, v38
	v_fmac_f32_e32 v27, v2, v40
	v_mov_b32_e32 v0, v209
	v_fmac_f32_e32 v27, v1, v38
	v_lshlrev_b32_e32 v4, 16, v6
	v_cvt_f32_i32_e32 v1, v0
	v_and_b32_e32 v5, 0xffff0000, v6
	v_lshlrev_b32_e32 v6, 16, v7
	v_and_b32_e32 v7, 0xffff0000, v7
	v_fmac_f32_e32 v8, v15, v38
	v_fma_f32 v17, v6, v42, v44
	v_fma_f32 v15, v7, v42, v44
	v_fmac_f32_e32 v124, v19, v38
	v_fma_f32 v19, v5, v42, v44
	v_fmac_f32_e32 v17, v5, v40
	v_fmac_f32_e32 v15, v6, v40
	v_mul_f32_e32 v1, 0x38800000, v1
	v_fmac_f32_e32 v121, v25, v38
	v_fma_f32 v25, v4, v42, v44
	v_fmac_f32_e32 v19, v4, v40
	v_fmac_f32_e32 v17, v4, v38
	v_fmac_f32_e32 v15, v5, v38
	v_cos_f32_e32 v4, v1
	v_sin_f32_e64 v5, -v1
	v_add_u32_e32 v1, 1, v0
	v_cvt_f32_i32_e32 v1, v1
	v_fmac_f32_e32 v20, v13, v38
	v_fma_f32 v13, v32, v42, v44
	v_fmac_f32_e32 v13, v7, v40
	v_fmac_f32_e32 v13, v6, v38
	s_nop 1
	v_xor_b32_e32 v7, 0x80000000, v120
	v_mov_b32_e32 v6, v121
	v_pk_mul_f32 v[126:127], v[4:5], v[4:5] op_sel:[0,0] op_sel_hi:[0,1]
	v_mul_f32_e32 v1, 0x38800000, v1
	v_pk_fma_f32 v[126:127], v[4:5], v[4:5], v[126:127] op_sel:[1,1,0] op_sel_hi:[1,0,1] neg_lo:[0,1,0]
	v_pk_add_f32 v[122:123], v[124:125], v[6:7]
	v_pk_mul_f32 v[130:131], v[126:127], v[4:5] op_sel:[0,0] op_sel_hi:[0,1]
	v_cos_f32_e32 v132, v1
	v_pk_mul_f32 v[118:119], v[122:123], v[4:5] op_sel:[0,0] op_sel_hi:[0,1]
	v_sin_f32_e64 v133, -v1
	v_ashrrev_i32_e32 v1, 4, v0
	v_pk_fma_f32 v[130:131], v[126:127], v[4:5], v[130:131] op_sel:[1,1,0] op_sel_hi:[1,0,1] neg_lo:[0,1,0]
	v_pk_fma_f32 v[118:119], v[122:123], v[4:5], v[118:119] op_sel:[1,1,0] op_sel_hi:[1,0,1] neg_lo:[0,1,0]
	v_pk_add_f32 v[4:5], v[124:125], v[120:121] neg_lo:[0,1] neg_hi:[0,1]
	v_lshlrev_b32_e32 v1, 3, v1
	v_pk_mul_f32 v[122:123], v[4:5], v[126:127] op_sel:[0,0] op_sel_hi:[0,1]
	v_fmac_f32_e32 v25, v3, v40
	v_pk_fma_f32 v[122:123], v[4:5], v[126:127], v[122:123] op_sel:[1,1,0] op_sel_hi:[1,0,1] neg_lo:[0,1,0]
	v_pk_add_f32 v[4:5], v[124:125], v[6:7] neg_lo:[0,1] neg_hi:[0,1]
	v_and_b32_e32 v1, -16, v1
	v_pk_mul_f32 v[126:127], v[4:5], v[130:131] op_sel:[0,0] op_sel_hi:[0,1]
	v_lshlrev_b32_e32 v32, 3, v0
	v_fmac_f32_e32 v25, v2, v38
	v_fmac_f32_e32 v19, v3, v38
	v_pk_add_f32 v[2:3], v[124:125], v[120:121]
	v_pk_fma_f32 v[126:127], v[4:5], v[130:131], v[126:127] op_sel:[1,1,0] op_sel_hi:[1,0,1] neg_lo:[0,1,0]
	v_pk_add_f32 v[4:5], v[128:129], v[116:117]
	v_add3_u32 v1, 0, v1, v32
	s_nop 1
	ds_write_b128 v1, v[2:5]
	v_add_u32_e32 v1, 0x1000, v0
	v_ashrrev_i32_e32 v1, 4, v1
	v_lshlrev_b32_e32 v1, 3, v1
	v_xor_b32_e32 v7, 0x80000000, v116
	v_mov_b32_e32 v6, v117
	v_and_b32_e32 v1, -16, v1
	v_pk_add_f32 v[124:125], v[128:129], v[6:7]
	v_add3_u32 v1, 0, v1, v32
	v_pk_mul_f32 v[120:121], v[124:125], v[132:133] op_sel:[0,0] op_sel_hi:[0,1]
	v_pk_mul_f32 v[130:131], v[132:133], v[132:133] op_sel:[0,0] op_sel_hi:[0,1]
	v_pk_add_f32 v[116:117], v[128:129], v[116:117] neg_lo:[0,1] neg_hi:[0,1]
	v_pk_fma_f32 v[120:121], v[124:125], v[132:133], v[120:121] op_sel:[1,1,0] op_sel_hi:[1,0,1] neg_lo:[0,1,0]
	ds_write_b128 v1, v[118:121] offset:32768
	v_add_u32_e32 v1, 0x2000, v0
	v_ashrrev_i32_e32 v2, 4, v1
	v_lshlrev_b32_e32 v2, 3, v2
	v_and_b32_e32 v2, -16, v2
	v_lshlrev_b32_e32 v1, 3, v1
	v_pk_fma_f32 v[130:131], v[132:133], v[132:133], v[130:131] op_sel:[1,1,0] op_sel_hi:[1,0,1] neg_lo:[0,1,0]
	v_add3_u32 v1, 0, v2, v1
	v_pk_mul_f32 v[124:125], v[116:117], v[130:131] op_sel:[0,0] op_sel_hi:[0,1]
	v_pk_mul_f32 v[134:135], v[130:131], v[132:133] op_sel:[0,0] op_sel_hi:[0,1]
	v_add_u32_e32 v39, 2, v0
	v_pk_fma_f32 v[124:125], v[116:117], v[130:131], v[124:125] op_sel:[1,1,0] op_sel_hi:[1,0,1] neg_lo:[0,1,0]
	ds_write_b128 v1, v[122:125]
	v_add_u32_e32 v1, 0x3000, v0
	v_ashrrev_i32_e32 v3, 4, v1
	v_lshlrev_b32_e32 v3, 3, v3
	v_and_b32_e32 v3, -16, v3
	v_lshlrev_b32_e32 v1, 3, v1
	v_pk_fma_f32 v[134:135], v[130:131], v[132:133], v[134:135] op_sel:[1,1,0] op_sel_hi:[1,0,1] neg_lo:[0,1,0]
	v_pk_add_f32 v[6:7], v[128:129], v[6:7] neg_lo:[0,1] neg_hi:[0,1]
	v_cvt_f32_i32_e32 v2, v39
	v_pk_mul_f32 v[128:129], v[6:7], v[134:135] op_sel:[0,0] op_sel_hi:[0,1]
	v_add3_u32 v1, 0, v3, v1
	v_pk_fma_f32 v[128:129], v[6:7], v[134:135], v[128:129] op_sel:[1,1,0] op_sel_hi:[1,0,1] neg_lo:[0,1,0]
	ds_write_b128 v1, v[126:129]
	v_add_u32_e32 v1, 3, v0
	v_cvt_f32_i32_e32 v1, v1
	v_mul_f32_e32 v2, 0x38800000, v2
	v_cos_f32_e32 v4, v2
	v_sin_f32_e64 v5, -v2
	s_nop 1
	v_xor_b32_e32 v7, 0x80000000, v26
	v_mov_b32_e32 v6, v27
	v_pk_mul_f32 v[118:119], v[4:5], v[4:5] op_sel:[0,0] op_sel_hi:[0,1]
	v_mul_f32_e32 v1, 0x38800000, v1
	v_pk_fma_f32 v[118:119], v[4:5], v[4:5], v[118:119] op_sel:[1,1,0] op_sel_hi:[1,0,1] neg_lo:[0,1,0]
	v_pk_add_f32 v[120:121], v[30:31], v[6:7]
	v_pk_mul_f32 v[122:123], v[118:119], v[4:5] op_sel:[0,0] op_sel_hi:[0,1]
	v_cos_f32_e32 v124, v1
	v_pk_mul_f32 v[116:117], v[120:121], v[4:5] op_sel:[0,0] op_sel_hi:[0,1]
	v_sin_f32_e64 v125, -v1
	v_ashrrev_i32_e32 v1, 4, v39
	v_pk_fma_f32 v[122:123], v[118:119], v[4:5], v[122:123] op_sel:[1,1,0] op_sel_hi:[1,0,1] neg_lo:[0,1,0]
	v_pk_fma_f32 v[116:117], v[120:121], v[4:5], v[116:117] op_sel:[1,1,0] op_sel_hi:[1,0,1] neg_lo:[0,1,0]
	v_pk_add_f32 v[4:5], v[30:31], v[26:27] neg_lo:[0,1] neg_hi:[0,1]
	v_lshlrev_b32_e32 v1, 3, v1
; #define LAS __attribute__((address_space(3)))
; template <int R0> __device__ __forceinline__ void r0_fwd_store(LAS cf* X, const int N, int j0, const f32x4 (&ar)[R0 / 2][2], const f32x4 (&ai)[R0 / 2][2]) {
;     constexpr int q = 4096; const float rN = 1.0f / (float)N; asm volatile("" : "+v"(j0));
; #pragma unroll
;     for (int e = 0; e < 8; e += 2) {
;         cf y[R0][2];
; #pragma unroll
;         for (int h = 0; h < 2; ++h) { const int j = j0 + e + h; const cf w1 = twid((float)j * rN, false);
;             if constexpr (R0 == 4) { const cf a0 = cf{VEL(ar[0], e + h), VEL(ai[0], e + h)}, a1 = cf{VEL(ar[1], e + h), VEL(ai[1], e + h)}; const cf m = cf{a1.y, -a1.x};
;                 const cf w2 = cmul(w1, w1), w3 = cmul(w2, w1);
;                 y[0][h] = a0 + a1; y[1][h] = cmul(a0 + m, w1); y[2][h] = cmul(a0 - a1, w2); y[3][h] = cmul(a0 - m, w3); }
;             else { const cf a0 = cf{VEL(ar[0], e + h), VEL(ai[0], e + h)}; y[0][h] = a0; y[1][h] = cmul(a0, w1); } }
; #pragma unroll
;         for (int k = 0; k < R0; ++k) *(LAS f32x4*)(X + fphys(j0 + e + k * q)) = (f32x4){y[k][0].x, y[k][0].y, y[k][1].x, y[k][1].y};
;     }
	v_pk_mul_f32 v[120:121], v[4:5], v[118:119] op_sel:[0,0] op_sel_hi:[0,1]
	v_pk_add_f32 v[2:3], v[30:31], v[26:27]
	v_pk_fma_f32 v[120:121], v[4:5], v[118:119], v[120:121] op_sel:[1,1,0] op_sel_hi:[1,0,1] neg_lo:[0,1,0]
	v_pk_add_f32 v[4:5], v[30:31], v[6:7] neg_lo:[0,1] neg_hi:[0,1]
	v_and_b32_e32 v1, -16, v1
	v_pk_mul_f32 v[26:27], v[4:5], v[122:123] op_sel:[0,0] op_sel_hi:[0,1]
	v_add3_u32 v1, 0, v1, v32
	v_pk_fma_f32 v[26:27], v[4:5], v[122:123], v[26:27] op_sel:[1,1,0] op_sel_hi:[1,0,1] neg_lo:[0,1,0]
	v_pk_add_f32 v[4:5], v[28:29], v[24:25]
	s_nop 1
	ds_write_b128 v1, v[2:5] offset:16
	v_add_u32_e32 v1, 0x1002, v0
	v_ashrrev_i32_e32 v1, 4, v1
	v_lshlrev_b32_e32 v1, 3, v1
	v_xor_b32_e32 v7, 0x80000000, v24
	v_mov_b32_e32 v6, v25
	v_and_b32_e32 v1, -16, v1
	v_pk_add_f32 v[122:123], v[28:29], v[6:7]
	v_add3_u32 v1, 0, v1, v32
	v_pk_mul_f32 v[118:119], v[122:123], v[124:125] op_sel:[0,0] op_sel_hi:[0,1]
	v_pk_mul_f32 v[30:31], v[124:125], v[124:125] op_sel:[0,0] op_sel_hi:[0,1]
	v_pk_add_f32 v[24:25], v[28:29], v[24:25] neg_lo:[0,1] neg_hi:[0,1]
	v_pk_fma_f32 v[118:119], v[122:123], v[124:125], v[118:119] op_sel:[1,1,0] op_sel_hi:[1,0,1] neg_lo:[0,1,0]
	ds_write_b128 v1, v[116:119] offset:32784
	v_add_u32_e32 v1, 0x2002, v0
	v_ashrrev_i32_e32 v2, 4, v1
	v_lshlrev_b32_e32 v2, 3, v2
	v_and_b32_e32 v2, -16, v2
	v_lshlrev_b32_e32 v1, 3, v1
	v_pk_fma_f32 v[30:31], v[124:125], v[124:125], v[30:31] op_sel:[1,1,0] op_sel_hi:[1,0,1] neg_lo:[0,1,0]
	v_add3_u32 v1, 0, v2, v1
	v_pk_mul_f32 v[122:123], v[24:25], v[30:31] op_sel:[0,0] op_sel_hi:[0,1]
	v_pk_mul_f32 v[126:127], v[30:31], v[124:125] op_sel:[0,0] op_sel_hi:[0,1]
	v_add_u32_e32 v39, 4, v0
	v_pk_fma_f32 v[122:123], v[24:25], v[30:31], v[122:123] op_sel:[1,1,0] op_sel_hi:[1,0,1] neg_lo:[0,1,0]
	ds_write_b128 v1, v[120:123]
	v_add_u32_e32 v1, 0x3002, v0
	v_ashrrev_i32_e32 v3, 4, v1
	v_lshlrev_b32_e32 v3, 3, v3
	v_and_b32_e32 v3, -16, v3
	v_lshlrev_b32_e32 v1, 3, v1
	v_pk_fma_f32 v[126:127], v[30:31], v[124:125], v[126:127] op_sel:[1,1,0] op_sel_hi:[1,0,1] neg_lo:[0,1,0]
	v_pk_add_f32 v[6:7], v[28:29], v[6:7] neg_lo:[0,1] neg_hi:[0,1]
	v_cvt_f32_i32_e32 v2, v39
	v_pk_mul_f32 v[28:29], v[6:7], v[126:127] op_sel:[0,0] op_sel_hi:[0,1]
	v_add3_u32 v1, 0, v3, v1
	v_pk_fma_f32 v[28:29], v[6:7], v[126:127], v[28:29] op_sel:[1,1,0] op_sel_hi:[1,0,1] neg_lo:[0,1,0]
	ds_write_b128 v1, v[26:29]
	v_add_u32_e32 v1, 5, v0
	v_cvt_f32_i32_e32 v1, v1
	v_mul_f32_e32 v2, 0x38800000, v2
	v_cos_f32_e32 v4, v2
	v_sin_f32_e64 v5, -v2
	s_nop 1
	v_xor_b32_e32 v7, 0x80000000, v18
	v_mov_b32_e32 v6, v19
	v_pk_mul_f32 v[26:27], v[4:5], v[4:5] op_sel:[0,0] op_sel_hi:[0,1]
	v_mul_f32_e32 v1, 0x38800000, v1
	v_pk_fma_f32 v[26:27], v[4:5], v[4:5], v[26:27] op_sel:[1,1,0] op_sel_hi:[1,0,1] neg_lo:[0,1,0]
	v_pk_add_f32 v[28:29], v[22:23], v[6:7]
	v_pk_mul_f32 v[30:31], v[26:27], v[4:5] op_sel:[0,0] op_sel_hi:[0,1]
	v_cos_f32_e32 v116, v1
	v_pk_mul_f32 v[24:25], v[28:29], v[4:5] op_sel:[0,0] op_sel_hi:[0,1]
	v_sin_f32_e64 v117, -v1
	v_ashrrev_i32_e32 v1, 4, v39
	v_pk_fma_f32 v[30:31], v[26:27], v[4:5], v[30:31] op_sel:[1,1,0] op_sel_hi:[1,0,1] neg_lo:[0,1,0]
	v_pk_fma_f32 v[24:25], v[28:29], v[4:5], v[24:25] op_sel:[1,1,0] op_sel_hi:[1,0,1] neg_lo:[0,1,0]
	v_pk_add_f32 v[4:5], v[22:23], v[18:19] neg_lo:[0,1] neg_hi:[0,1]
	v_lshlrev_b32_e32 v1, 3, v1
	v_pk_mul_f32 v[28:29], v[4:5], v[26:27] op_sel:[0,0] op_sel_hi:[0,1]
	v_pk_add_f32 v[2:3], v[22:23], v[18:19]
	v_pk_fma_f32 v[28:29], v[4:5], v[26:27], v[28:29] op_sel:[1,1,0] op_sel_hi:[1,0,1] neg_lo:[0,1,0]
	v_pk_add_f32 v[4:5], v[22:23], v[6:7] neg_lo:[0,1] neg_hi:[0,1]
	v_and_b32_e32 v1, -16, v1
	v_pk_mul_f32 v[18:19], v[4:5], v[30:31] op_sel:[0,0] op_sel_hi:[0,1]
	v_add3_u32 v1, 0, v1, v32
	v_pk_fma_f32 v[18:19], v[4:5], v[30:31], v[18:19] op_sel:[1,1,0] op_sel_hi:[1,0,1] neg_lo:[0,1,0]
	v_pk_add_f32 v[4:5], v[20:21], v[16:17]
	s_nop 1
	ds_write_b128 v1, v[2:5] offset:32
	v_add_u32_e32 v1, 0x1004, v0
	v_ashrrev_i32_e32 v1, 4, v1
	v_lshlrev_b32_e32 v1, 3, v1
	v_xor_b32_e32 v7, 0x80000000, v16
	v_mov_b32_e32 v6, v17
	v_and_b32_e32 v1, -16, v1
	v_pk_add_f32 v[30:31], v[20:21], v[6:7]
	v_add3_u32 v1, 0, v1, v32
	v_pk_mul_f32 v[26:27], v[30:31], v[116:117] op_sel:[0,0] op_sel_hi:[0,1]
	v_pk_mul_f32 v[22:23], v[116:117], v[116:117] op_sel:[0,0] op_sel_hi:[0,1]
	v_pk_add_f32 v[16:17], v[20:21], v[16:17] neg_lo:[0,1] neg_hi:[0,1]
	v_pk_fma_f32 v[26:27], v[30:31], v[116:117], v[26:27] op_sel:[1,1,0] op_sel_hi:[1,0,1] neg_lo:[0,1,0]
	ds_write_b128 v1, v[24:27] offset:32800
	v_add_u32_e32 v1, 0x2004, v0
	v_ashrrev_i32_e32 v2, 4, v1
; #define LAS __attribute__((address_space(3)))
; template <int R0> __device__ __forceinline__ void r0_fwd_store(LAS cf* X, const int N, int j0, const f32x4 (&ar)[R0 / 2][2], const f32x4 (&ai)[R0 / 2][2]) {
;     constexpr int q = 4096; const float rN = 1.0f / (float)N; asm volatile("" : "+v"(j0));
; #pragma unroll
;     for (int e = 0; e < 8; e += 2) {
;         cf y[R0][2];
; #pragma unroll
;         for (int h = 0; h < 2; ++h) { const int j = j0 + e + h; const cf w1 = twid((float)j * rN, false);
;             if constexpr (R0 == 4) { const cf a0 = cf{VEL(ar[0], e + h), VEL(ai[0], e + h)}, a1 = cf{VEL(ar[1], e + h), VEL(ai[1], e + h)}; const cf m = cf{a1.y, -a1.x};
;                 const cf w2 = cmul(w1, w1), w3 = cmul(w2, w1);
;                 y[0][h] = a0 + a1; y[1][h] = cmul(a0 + m, w1); y[2][h] = cmul(a0 - a1, w2); y[3][h] = cmul(a0 - m, w3); }
;             else { const cf a0 = cf{VEL(ar[0], e + h), VEL(ai[0], e + h)}; y[0][h] = a0; y[1][h] = cmul(a0, w1); } }
; #pragma unroll
;         for (int k = 0; k < R0; ++k) *(LAS f32x4*)(X + fphys(j0 + e + k * q)) = (f32x4){y[k][0].x, y[k][0].y, y[k][1].x, y[k][1].y};
;     }
; }
; __device__ __forceinline__ void fft_mid_chain(LAS cf* X, const int N, const f32x4* Kst, const float sc) {
;     __syncthreads();
;     stage16<4096, false>(X, N); __syncthreads();
	v_lshlrev_b32_e32 v2, 3, v2
	v_and_b32_e32 v2, -16, v2
	v_lshlrev_b32_e32 v1, 3, v1
	v_pk_fma_f32 v[22:23], v[116:117], v[116:117], v[22:23] op_sel:[1,1,0] op_sel_hi:[1,0,1] neg_lo:[0,1,0]
	v_add3_u32 v1, 0, v2, v1
	v_pk_mul_f32 v[30:31], v[16:17], v[22:23] op_sel:[0,0] op_sel_hi:[0,1]
	v_pk_mul_f32 v[118:119], v[22:23], v[116:117] op_sel:[0,0] op_sel_hi:[0,1]
	v_pk_add_f32 v[6:7], v[20:21], v[6:7] neg_lo:[0,1] neg_hi:[0,1]
	v_pk_fma_f32 v[30:31], v[16:17], v[22:23], v[30:31] op_sel:[1,1,0] op_sel_hi:[1,0,1] neg_lo:[0,1,0]
	ds_write_b128 v1, v[28:31]
	v_add_u32_e32 v1, 0x3004, v0
	v_ashrrev_i32_e32 v3, 4, v1
	v_add_u32_e32 v28, 6, v0
	v_lshlrev_b32_e32 v3, 3, v3
	v_cvt_f32_i32_e32 v2, v28
	v_and_b32_e32 v3, -16, v3
	v_lshlrev_b32_e32 v1, 3, v1
	v_pk_fma_f32 v[118:119], v[22:23], v[116:117], v[118:119] op_sel:[1,1,0] op_sel_hi:[1,0,1] neg_lo:[0,1,0]
	v_add3_u32 v1, 0, v3, v1
	v_pk_mul_f32 v[20:21], v[6:7], v[118:119] op_sel:[0,0] op_sel_hi:[0,1]
	v_mul_f32_e32 v2, 0x38800000, v2
	v_pk_fma_f32 v[20:21], v[6:7], v[118:119], v[20:21] op_sel:[1,1,0] op_sel_hi:[1,0,1] neg_lo:[0,1,0]
	ds_write_b128 v1, v[18:21]
	v_add_u32_e32 v1, 7, v0
	v_cvt_f32_i32_e32 v1, v1
	v_cos_f32_e32 v4, v2
	v_sin_f32_e64 v5, -v2
	s_nop 1
	v_xor_b32_e32 v7, 0x80000000, v14
	v_mov_b32_e32 v6, v15
	v_pk_mul_f32 v[18:19], v[4:5], v[4:5] op_sel:[0,0] op_sel_hi:[0,1]
	v_pk_add_f32 v[20:21], v[10:11], v[6:7]
	v_pk_fma_f32 v[18:19], v[4:5], v[4:5], v[18:19] op_sel:[1,1,0] op_sel_hi:[1,0,1] neg_lo:[0,1,0]
	v_mul_f32_e32 v1, 0x38800000, v1
	v_pk_mul_f32 v[22:23], v[18:19], v[4:5] op_sel:[0,0] op_sel_hi:[0,1]
	v_pk_mul_f32 v[16:17], v[20:21], v[4:5] op_sel:[0,0] op_sel_hi:[0,1]
	v_pk_add_f32 v[2:3], v[10:11], v[14:15]
	v_pk_fma_f32 v[22:23], v[18:19], v[4:5], v[22:23] op_sel:[1,1,0] op_sel_hi:[1,0,1] neg_lo:[0,1,0]
	v_pk_fma_f32 v[16:17], v[20:21], v[4:5], v[16:17] op_sel:[1,1,0] op_sel_hi:[1,0,1] neg_lo:[0,1,0]
	v_pk_add_f32 v[4:5], v[10:11], v[14:15] neg_lo:[0,1] neg_hi:[0,1]
	v_cos_f32_e32 v14, v1
	v_sin_f32_e64 v15, -v1
	v_ashrrev_i32_e32 v1, 4, v28
	v_pk_mul_f32 v[20:21], v[4:5], v[18:19] op_sel:[0,0] op_sel_hi:[0,1]
	v_lshlrev_b32_e32 v1, 3, v1
	v_pk_fma_f32 v[20:21], v[4:5], v[18:19], v[20:21] op_sel:[1,1,0] op_sel_hi:[1,0,1] neg_lo:[0,1,0]
	v_pk_add_f32 v[4:5], v[10:11], v[6:7] neg_lo:[0,1] neg_hi:[0,1]
	v_and_b32_e32 v1, -16, v1
	v_pk_mul_f32 v[6:7], v[4:5], v[22:23] op_sel:[0,0] op_sel_hi:[0,1]
	v_add3_u32 v1, 0, v1, v32
	v_pk_fma_f32 v[6:7], v[4:5], v[22:23], v[6:7] op_sel:[1,1,0] op_sel_hi:[1,0,1] neg_lo:[0,1,0]
	v_pk_add_f32 v[4:5], v[8:9], v[12:13]
	s_nop 1
	ds_write_b128 v1, v[2:5] offset:48
	v_add_u32_e32 v1, 0x1006, v0
	v_ashrrev_i32_e32 v1, 4, v1
	v_lshlrev_b32_e32 v1, 3, v1
	v_xor_b32_e32 v11, 0x80000000, v12
	v_mov_b32_e32 v10, v13
	v_and_b32_e32 v1, -16, v1
	v_pk_add_f32 v[22:23], v[8:9], v[10:11]
	v_add3_u32 v1, 0, v1, v32
	v_pk_mul_f32 v[18:19], v[22:23], v[14:15] op_sel:[0,0] op_sel_hi:[0,1]
	v_pk_mul_f32 v[24:25], v[14:15], v[14:15] op_sel:[0,0] op_sel_hi:[0,1]
	v_pk_add_f32 v[12:13], v[8:9], v[12:13] neg_lo:[0,1] neg_hi:[0,1]
	v_pk_fma_f32 v[18:19], v[22:23], v[14:15], v[18:19] op_sel:[1,1,0] op_sel_hi:[1,0,1] neg_lo:[0,1,0]
	ds_write_b128 v1, v[16:19] offset:32816
	v_add_u32_e32 v1, 0x2006, v0
	v_ashrrev_i32_e32 v2, 4, v1
	v_lshlrev_b32_e32 v2, 3, v2
	v_and_b32_e32 v2, -16, v2
	v_lshlrev_b32_e32 v1, 3, v1
	v_pk_fma_f32 v[24:25], v[14:15], v[14:15], v[24:25] op_sel:[1,1,0] op_sel_hi:[1,0,1] neg_lo:[0,1,0]
	v_add3_u32 v1, 0, v2, v1
	v_pk_mul_f32 v[22:23], v[12:13], v[24:25] op_sel:[0,0] op_sel_hi:[0,1]
	v_add_u32_e32 v0, 0x3006, v0
	v_pk_fma_f32 v[22:23], v[12:13], v[24:25], v[22:23] op_sel:[1,1,0] op_sel_hi:[1,0,1] neg_lo:[0,1,0]
	ds_write_b128 v1, v[20:23]
	v_ashrrev_i32_e32 v1, 4, v0
	v_lshlrev_b32_e32 v1, 3, v1
	v_pk_mul_f32 v[26:27], v[24:25], v[14:15] op_sel:[0,0] op_sel_hi:[0,1]
	v_and_b32_e32 v1, -16, v1
	v_lshlrev_b32_e32 v0, 3, v0
	v_pk_fma_f32 v[26:27], v[24:25], v[14:15], v[26:27] op_sel:[1,1,0] op_sel_hi:[1,0,1] neg_lo:[0,1,0]
	v_pk_add_f32 v[10:11], v[8:9], v[10:11] neg_lo:[0,1] neg_hi:[0,1]
	v_add3_u32 v0, 0, v1, v0
	v_pk_mul_f32 v[8:9], v[10:11], v[26:27] op_sel:[0,0] op_sel_hi:[0,1]
	v_mov_b32_e32 v39, v145
	v_pk_fma_f32 v[8:9], v[10:11], v[26:27], v[8:9] op_sel:[1,1,0] op_sel_hi:[1,0,1] neg_lo:[0,1,0]
	ds_write_b128 v0, v[6:9]
	s_waitcnt lgkmcnt(0)
	s_barrier
	s_nop 0
	v_cmp_gt_i32_e64 s[12:13], s97, v39
	s_and_saveexec_b64 s[80:81], s[12:13]
	s_xor_b64 s[80:81], exec, s[80:81]
	s_cbranch_execz .LBB0_432
	v_lshl_add_u32 v32, v39, 3, 0
	s_mov_b64 s[82:83], 0

; #define LAS __attribute__((address_space(3)))
; template <int R0> __device__ __forceinline__ void r0_inv_load(const LAS cf* X, const int N, int j0, f32x4 (&yr)[R0 / 2][2], f32x4 (&yi)[R0 / 2][2]) {
;     constexpr int q = 4096; const float rN = 1.0f / (float)N; asm volatile("" : "+v"(j0));
; #pragma unroll
;     for (int e = 0; e < 8; e += 2) {
;         f32x4 v[R0];
; #pragma unroll
;         for (int k = 0; k < R0; ++k) v[k] = *(const LAS f32x4*)(X + fphys(j0 + e + k * q));
; #pragma unroll
;         for (int h = 0; h < 2; ++h) { const int j = j0 + e + h; const cf w1 = twid((float)j * rN, true);
;             if constexpr (R0 == 4) { const cf w2 = cmul(w1, w1), w3 = cmul(w2, w1);
;                 const cf a0 = h ? cf{v[0].z, v[0].w} : cf{v[0].x, v[0].y}; const cf a1 = cmul(h ? cf{v[1].z, v[1].w} : cf{v[1].x, v[1].y}, w1);
;                 const cf a2 = cmul(h ? cf{v[2].z, v[2].w} : cf{v[2].x, v[2].y}, w2); const cf a3 = cmul(h ? cf{v[3].z, v[3].w} : cf{v[3].x, v[3].y}, w3);
;                 const cf t0 = a0 + a2, t1 = a0 - a2, t2 = a1 + a3, t3 = a1 - a3;
;                 VEL(yr[0], e + h) = t0.x + t2.x; VEL(yi[0], e + h) = t0.y + t2.y; VEL(yr[1], e + h) = t1.x - t3.y; VEL(yi[1], e + h) = t1.y + t3.x; }
.LBB0_444:
	s_or_b64 exec, exec, s[80:81]
	v_mov_b32_e32 v16, v209
	s_waitcnt lgkmcnt(0)
	s_barrier
	v_mov_b32_e32 v103, 0
	v_cvt_f32_i32_e32 v18, v16
	v_add_u32_e32 v4, 0x1000, v16
	v_add_u32_e32 v8, 0x2000, v16
	v_add_u32_e32 v12, 0x3000, v16
	v_ashrrev_i32_e32 v0, 4, v16
	v_ashrrev_i32_e32 v4, 4, v4
	v_ashrrev_i32_e32 v9, 4, v8
	v_ashrrev_i32_e32 v13, 4, v12
	v_lshlrev_b32_e32 v0, 3, v0
	v_lshlrev_b32_e32 v4, 3, v4
	v_lshlrev_b32_e32 v9, 3, v9
	v_lshlrev_b32_e32 v13, 3, v13
	v_and_b32_e32 v0, -16, v0
	v_lshlrev_b32_e32 v17, 3, v16
	v_and_b32_e32 v4, -16, v4
	v_and_b32_e32 v9, -16, v9
	v_lshlrev_b32_e32 v8, 3, v8
	v_and_b32_e32 v13, -16, v13
	v_lshlrev_b32_e32 v12, 3, v12
	v_mul_f32_e32 v19, 0x38800000, v18
	v_add3_u32 v0, 0, v0, v17
	v_add3_u32 v4, 0, v4, v17
	v_add3_u32 v8, 0, v9, v8
	v_add3_u32 v12, 0, v13, v12
	v_cos_f32_e32 v18, v19
	v_sin_f32_e32 v19, v19
	ds_read_b128 v[0:3], v0
	ds_read_b128 v[4:7], v4 offset:32768
	ds_read_b128 v[8:11], v8
	ds_read_b128 v[12:15], v12
	s_nop 1
	s_waitcnt lgkmcnt(2)
	v_pk_mul_f32 v[116:117], v[4:5], v[18:19] op_sel:[0,0] op_sel_hi:[0,1]
	v_pk_mul_f32 v[20:21], v[18:19], v[18:19] op_sel:[0,0] op_sel_hi:[0,1]
	s_nop 0
	v_pk_fma_f32 v[116:117], v[4:5], v[18:19], v[116:117] op_sel:[1,1,0] op_sel_hi:[1,0,1] neg_lo:[0,1,0]
	v_add_u32_e32 v4, 1, v16
	v_cvt_f32_i32_e32 v4, v4
	v_pk_fma_f32 v[20:21], v[18:19], v[18:19], v[20:21] op_sel:[1,1,0] op_sel_hi:[1,0,1] neg_lo:[0,1,0]
	v_mul_f32_e32 v5, 0x38800000, v4
	v_pk_mul_f32 v[22:23], v[20:21], v[18:19] op_sel:[0,0] op_sel_hi:[0,1]
	s_waitcnt lgkmcnt(1)
	v_pk_mul_f32 v[118:119], v[8:9], v[20:21] op_sel:[0,0] op_sel_hi:[0,1]
	v_cos_f32_e32 v4, v5
	v_sin_f32_e32 v5, v5
	v_pk_fma_f32 v[22:23], v[20:21], v[18:19], v[22:23] op_sel:[1,1,0] op_sel_hi:[1,0,1] neg_lo:[0,1,0]
	v_pk_fma_f32 v[118:119], v[8:9], v[20:21], v[118:119] op_sel:[1,1,0] op_sel_hi:[1,0,1] neg_lo:[0,1,0]
	s_nop 1
	v_add_u32_e32 v18, 0x3002, v16
	s_waitcnt lgkmcnt(0)
	v_pk_mul_f32 v[120:121], v[12:13], v[22:23] op_sel:[0,0] op_sel_hi:[0,1]
	v_pk_mul_f32 v[8:9], v[4:5], v[4:5] op_sel:[0,0] op_sel_hi:[0,1]
	v_pk_mul_f32 v[122:123], v[6:7], v[4:5] op_sel:[0,0] op_sel_hi:[0,1]
	v_ashrrev_i32_e32 v19, 4, v18
	v_pk_fma_f32 v[120:121], v[12:13], v[22:23], v[120:121] op_sel:[1,1,0] op_sel_hi:[1,0,1] neg_lo:[0,1,0]
	v_pk_fma_f32 v[8:9], v[4:5], v[4:5], v[8:9] op_sel:[1,1,0] op_sel_hi:[1,0,1] neg_lo:[0,1,0]
	v_add_u32_e32 v22, 2, v16
	v_pk_mul_f32 v[12:13], v[8:9], v[4:5] op_sel:[0,0] op_sel_hi:[0,1]
	v_pk_fma_f32 v[122:123], v[6:7], v[4:5], v[122:123] op_sel:[1,1,0] op_sel_hi:[1,0,1] neg_lo:[0,1,0]
	v_pk_mul_f32 v[124:125], v[10:11], v[8:9] op_sel:[0,0] op_sel_hi:[0,1]
	v_lshlrev_b32_e32 v19, 3, v19
	v_pk_fma_f32 v[12:13], v[8:9], v[4:5], v[12:13] op_sel:[1,1,0] op_sel_hi:[1,0,1] neg_lo:[0,1,0]
	v_ashrrev_i32_e32 v4, 4, v22
	v_pk_mul_f32 v[126:127], v[14:15], v[12:13] op_sel:[0,0] op_sel_hi:[0,1]
	v_cvt_f32_i32_e32 v22, v22
	v_pk_fma_f32 v[124:125], v[10:11], v[8:9], v[124:125] op_sel:[1,1,0] op_sel_hi:[1,0,1] neg_lo:[0,1,0]
	v_pk_fma_f32 v[126:127], v[14:15], v[12:13], v[126:127] op_sel:[1,1,0] op_sel_hi:[1,0,1] neg_lo:[0,1,0]
	v_add_u32_e32 v8, 0x1002, v16
	v_add_u32_e32 v12, 0x2002, v16
	v_ashrrev_i32_e32 v8, 4, v8
	v_ashrrev_i32_e32 v13, 4, v12
	v_lshlrev_b32_e32 v4, 3, v4
	v_lshlrev_b32_e32 v8, 3, v8
	v_lshlrev_b32_e32 v13, 3, v13
	v_and_b32_e32 v4, -16, v4
	v_and_b32_e32 v8, -16, v8
	v_and_b32_e32 v13, -16, v13
	v_lshlrev_b32_e32 v12, 3, v12
	v_and_b32_e32 v19, -16, v19
	v_lshlrev_b32_e32 v18, 3, v18
	v_mul_f32_e32 v23, 0x38800000, v22
	v_add3_u32 v4, 0, v4, v17
	v_add3_u32 v8, 0, v8, v17
	v_add3_u32 v12, 0, v13, v12
	v_add3_u32 v18, 0, v19, v18
	v_cos_f32_e32 v22, v23
	v_sin_f32_e32 v23, v23
	ds_read_b128 v[4:7], v4 offset:16
	ds_read_b128 v[8:11], v8 offset:32784
	ds_read_b128 v[12:15], v12
	ds_read_b128 v[18:21], v18
	s_nop 1
	s_waitcnt lgkmcnt(2)
	v_pk_mul_f32 v[128:129], v[8:9], v[22:23] op_sel:[0,0] op_sel_hi:[0,1]
	v_pk_mul_f32 v[24:25], v[22:23], v[22:23] op_sel:[0,0] op_sel_hi:[0,1]
	s_nop 0
	v_pk_fma_f32 v[128:129], v[8:9], v[22:23], v[128:129] op_sel:[1,1,0] op_sel_hi:[1,0,1] neg_lo:[0,1,0]
	v_add_u32_e32 v8, 3, v16
	v_cvt_f32_i32_e32 v8, v8
	v_pk_fma_f32 v[24:25], v[22:23], v[22:23], v[24:25] op_sel:[1,1,0] op_sel_hi:[1,0,1] neg_lo:[0,1,0]
	v_mul_f32_e32 v9, 0x38800000, v8
	v_pk_mul_f32 v[26:27], v[24:25], v[22:23] op_sel:[0,0] op_sel_hi:[0,1]
	s_waitcnt lgkmcnt(1)
	v_pk_mul_f32 v[130:131], v[12:13], v[24:25] op_sel:[0,0] op_sel_hi:[0,1]
	v_cos_f32_e32 v8, v9
	v_sin_f32_e32 v9, v9
	v_pk_fma_f32 v[26:27], v[24:25], v[22:23], v[26:27] op_sel:[1,1,0] op_sel_hi:[1,0,1] neg_lo:[0,1,0]
	v_pk_fma_f32 v[130:131], v[12:13], v[24:25], v[130:131] op_sel:[1,1,0] op_sel_hi:[1,0,1] neg_lo:[0,1,0]
	s_nop 1
	v_add_u32_e32 v22, 0x3004, v16
	s_waitcnt lgkmcnt(0)
; #define LAS __attribute__((address_space(3)))
; template <int R0> __device__ __forceinline__ void r0_inv_load(const LAS cf* X, const int N, int j0, f32x4 (&yr)[R0 / 2][2], f32x4 (&yi)[R0 / 2][2]) {
;     constexpr int q = 4096; const float rN = 1.0f / (float)N; asm volatile("" : "+v"(j0));
; #pragma unroll
;     for (int e = 0; e < 8; e += 2) {
;         f32x4 v[R0];
; #pragma unroll
;         for (int k = 0; k < R0; ++k) v[k] = *(const LAS f32x4*)(X + fphys(j0 + e + k * q));
; #pragma unroll
;         for (int h = 0; h < 2; ++h) { const int j = j0 + e + h; const cf w1 = twid((float)j * rN, true);
;             if constexpr (R0 == 4) { const cf w2 = cmul(w1, w1), w3 = cmul(w2, w1);
;                 const cf a0 = h ? cf{v[0].z, v[0].w} : cf{v[0].x, v[0].y}; const cf a1 = cmul(h ? cf{v[1].z, v[1].w} : cf{v[1].x, v[1].y}, w1);
;                 const cf a2 = cmul(h ? cf{v[2].z, v[2].w} : cf{v[2].x, v[2].y}, w2); const cf a3 = cmul(h ? cf{v[3].z, v[3].w} : cf{v[3].x, v[3].y}, w3);
;                 const cf t0 = a0 + a2, t1 = a0 - a2, t2 = a1 + a3, t3 = a1 - a3;
;                 VEL(yr[0], e + h) = t0.x + t2.x; VEL(yi[0], e + h) = t0.y + t2.y; VEL(yr[1], e + h) = t1.x - t3.y; VEL(yi[1], e + h) = t1.y + t3.x; }
; template <int R0> __device__ __forceinline__ void hy_pair(LAS cf* X, const int N, const int L, const int tid, const unsigned mA, const unsigned mB, const bf16_t* hyT, bf16_t* hyo, ...
;     ...
;         for (int n = 0; n < NL; ++n) { const int t0 = j0 + n * 4096; f32x4 va[2], vb[2], xa[2], xb[2];
;             conv8(hyT, ov + mA, t0, L, wv0, wv1, wv2, bv, va); conv8(hyT, ov + mB, t0, L, wv0, wv1, wv2, bv, vb);
	v_pk_mul_f32 v[132:133], v[18:19], v[26:27] op_sel:[0,0] op_sel_hi:[0,1]
	v_pk_mul_f32 v[12:13], v[8:9], v[8:9] op_sel:[0,0] op_sel_hi:[0,1]
	v_pk_mul_f32 v[134:135], v[10:11], v[8:9] op_sel:[0,0] op_sel_hi:[0,1]
	v_ashrrev_i32_e32 v23, 4, v22
	v_pk_fma_f32 v[132:133], v[18:19], v[26:27], v[132:133] op_sel:[1,1,0] op_sel_hi:[1,0,1] neg_lo:[0,1,0]
	v_pk_fma_f32 v[12:13], v[8:9], v[8:9], v[12:13] op_sel:[1,1,0] op_sel_hi:[1,0,1] neg_lo:[0,1,0]
	v_add_u32_e32 v26, 4, v16
	v_pk_mul_f32 v[18:19], v[12:13], v[8:9] op_sel:[0,0] op_sel_hi:[0,1]
	v_pk_fma_f32 v[134:135], v[10:11], v[8:9], v[134:135] op_sel:[1,1,0] op_sel_hi:[1,0,1] neg_lo:[0,1,0]
	v_pk_mul_f32 v[136:137], v[14:15], v[12:13] op_sel:[0,0] op_sel_hi:[0,1]
	v_lshlrev_b32_e32 v23, 3, v23
	v_pk_fma_f32 v[18:19], v[12:13], v[8:9], v[18:19] op_sel:[1,1,0] op_sel_hi:[1,0,1] neg_lo:[0,1,0]
	v_ashrrev_i32_e32 v8, 4, v26
	v_pk_mul_f32 v[138:139], v[20:21], v[18:19] op_sel:[0,0] op_sel_hi:[0,1]
	v_cvt_f32_i32_e32 v26, v26
	v_pk_fma_f32 v[136:137], v[14:15], v[12:13], v[136:137] op_sel:[1,1,0] op_sel_hi:[1,0,1] neg_lo:[0,1,0]
	v_pk_fma_f32 v[138:139], v[20:21], v[18:19], v[138:139] op_sel:[1,1,0] op_sel_hi:[1,0,1] neg_lo:[0,1,0]
	v_add_u32_e32 v12, 0x1004, v16
	v_add_u32_e32 v18, 0x2004, v16
	v_ashrrev_i32_e32 v12, 4, v12
	v_ashrrev_i32_e32 v19, 4, v18
	v_lshlrev_b32_e32 v8, 3, v8
	v_lshlrev_b32_e32 v12, 3, v12
	v_lshlrev_b32_e32 v19, 3, v19
	v_and_b32_e32 v8, -16, v8
	v_and_b32_e32 v12, -16, v12
	v_and_b32_e32 v19, -16, v19
	v_lshlrev_b32_e32 v18, 3, v18
	v_and_b32_e32 v23, -16, v23
	v_lshlrev_b32_e32 v22, 3, v22
	v_mul_f32_e32 v27, 0x38800000, v26
	v_add3_u32 v8, 0, v8, v17
	v_add3_u32 v12, 0, v12, v17
	v_add3_u32 v18, 0, v19, v18
	v_add3_u32 v22, 0, v23, v22
	v_cos_f32_e32 v26, v27
	v_sin_f32_e32 v27, v27
	ds_read_b128 v[8:11], v8 offset:32
	ds_read_b128 v[12:15], v12 offset:32800
	ds_read_b128 v[18:21], v18
	ds_read_b128 v[22:25], v22
	s_nop 1
	s_waitcnt lgkmcnt(2)
	v_pk_mul_f32 v[140:141], v[12:13], v[26:27] op_sel:[0,0] op_sel_hi:[0,1]
	v_pk_mul_f32 v[28:29], v[26:27], v[26:27] op_sel:[0,0] op_sel_hi:[0,1]
	s_nop 0
	v_pk_fma_f32 v[140:141], v[12:13], v[26:27], v[140:141] op_sel:[1,1,0] op_sel_hi:[1,0,1] neg_lo:[0,1,0]
	v_add_u32_e32 v12, 5, v16
	v_cvt_f32_i32_e32 v12, v12
	v_pk_fma_f32 v[28:29], v[26:27], v[26:27], v[28:29] op_sel:[1,1,0] op_sel_hi:[1,0,1] neg_lo:[0,1,0]
	v_mul_f32_e32 v13, 0x38800000, v12
	v_pk_mul_f32 v[30:31], v[28:29], v[26:27] op_sel:[0,0] op_sel_hi:[0,1]
	s_waitcnt lgkmcnt(1)
	v_pk_mul_f32 v[142:143], v[18:19], v[28:29] op_sel:[0,0] op_sel_hi:[0,1]
	v_cos_f32_e32 v12, v13
	v_sin_f32_e32 v13, v13
	v_pk_fma_f32 v[30:31], v[28:29], v[26:27], v[30:31] op_sel:[1,1,0] op_sel_hi:[1,0,1] neg_lo:[0,1,0]
	v_pk_fma_f32 v[142:143], v[18:19], v[28:29], v[142:143] op_sel:[1,1,0] op_sel_hi:[1,0,1] neg_lo:[0,1,0]
	s_nop 1
	s_waitcnt lgkmcnt(0)
	v_pk_mul_f32 v[146:147], v[22:23], v[30:31] op_sel:[0,0] op_sel_hi:[0,1]
	v_pk_mul_f32 v[18:19], v[12:13], v[12:13] op_sel:[0,0] op_sel_hi:[0,1]
	v_pk_mul_f32 v[148:149], v[14:15], v[12:13] op_sel:[0,0] op_sel_hi:[0,1]
	s_nop 0
	v_pk_fma_f32 v[146:147], v[22:23], v[30:31], v[146:147] op_sel:[1,1,0] op_sel_hi:[1,0,1] neg_lo:[0,1,0]
	v_pk_fma_f32 v[18:19], v[12:13], v[12:13], v[18:19] op_sel:[1,1,0] op_sel_hi:[1,0,1] neg_lo:[0,1,0]
	v_add_u32_e32 v30, 6, v16
	v_pk_mul_f32 v[22:23], v[18:19], v[12:13] op_sel:[0,0] op_sel_hi:[0,1]
	v_pk_mul_f32 v[150:151], v[20:21], v[18:19] op_sel:[0,0] op_sel_hi:[0,1]
	v_pk_fma_f32 v[148:149], v[14:15], v[12:13], v[148:149] op_sel:[1,1,0] op_sel_hi:[1,0,1] neg_lo:[0,1,0]
	s_nop 0
	v_pk_fma_f32 v[22:23], v[18:19], v[12:13], v[22:23] op_sel:[1,1,0] op_sel_hi:[1,0,1] neg_lo:[0,1,0]
	v_pk_fma_f32 v[150:151], v[20:21], v[18:19], v[150:151] op_sel:[1,1,0] op_sel_hi:[1,0,1] neg_lo:[0,1,0]
	v_add_u32_e32 v18, 0x1006, v16
	v_ashrrev_i32_e32 v12, 4, v30
	v_ashrrev_i32_e32 v18, 4, v18
	v_lshlrev_b32_e32 v12, 3, v12
	v_lshlrev_b32_e32 v18, 3, v18
	v_and_b32_e32 v12, -16, v12
	v_and_b32_e32 v18, -16, v18
	v_add3_u32 v12, 0, v12, v17
	v_add3_u32 v17, 0, v18, v17
	v_pk_mul_f32 v[152:153], v[24:25], v[22:23] op_sel:[0,0] op_sel_hi:[0,1]
	ds_read_b128 v[12:15], v12 offset:48
	ds_read_b128 v[18:21], v17 offset:32816
	v_add_u32_e32 v17, 0x2006, v16
	v_pk_fma_f32 v[152:153], v[24:25], v[22:23], v[152:153] op_sel:[1,1,0] op_sel_hi:[1,0,1] neg_lo:[0,1,0]
	v_ashrrev_i32_e32 v22, 4, v17
	v_lshlrev_b32_e32 v22, 3, v22
	v_and_b32_e32 v22, -16, v22
	v_lshlrev_b32_e32 v17, 3, v17
	v_add3_u32 v17, 0, v22, v17
	ds_read_b128 v[22:25], v17
	v_add_u32_e32 v17, 0x3006, v16
	v_ashrrev_i32_e32 v26, 4, v17
	v_lshlrev_b32_e32 v26, 3, v26
	v_and_b32_e32 v26, -16, v26
	v_lshlrev_b32_e32 v17, 3, v17
	v_add3_u32 v17, 0, v26, v17
	ds_read_b128 v[26:29], v17
	v_cvt_f32_i32_e32 v17, v30
	v_add_u32_e32 v16, 7, v16
	v_cvt_f32_i32_e32 v16, v16
	v_mul_f32_e32 v17, 0x38800000, v17
	v_cos_f32_e32 v30, v17
	v_sin_f32_e32 v31, v17
	s_nop 1
	v_mul_f32_e32 v17, 0x38800000, v16
	v_pk_mul_f32 v[158:159], v[30:31], v[30:31] op_sel:[0,0] op_sel_hi:[0,1]
	s_waitcnt lgkmcnt(2)
	v_pk_mul_f32 v[154:155], v[18:19], v[30:31] op_sel:[0,0] op_sel_hi:[0,1]
	v_cos_f32_e32 v16, v17
	v_pk_fma_f32 v[158:159], v[30:31], v[30:31], v[158:159] op_sel:[1,1,0] op_sel_hi:[1,0,1] neg_lo:[0,1,0]
	v_sin_f32_e32 v17, v17
	v_pk_mul_f32 v[160:161], v[158:159], v[30:31] op_sel:[0,0] op_sel_hi:[0,1]
	s_waitcnt lgkmcnt(1)
	v_pk_mul_f32 v[156:157], v[22:23], v[158:159] op_sel:[0,0] op_sel_hi:[0,1]
	v_pk_fma_f32 v[154:155], v[18:19], v[30:31], v[154:155] op_sel:[1,1,0] op_sel_hi:[1,0,1] neg_lo:[0,1,0]
	s_nop 1
	v_pk_fma_f32 v[160:161], v[158:159], v[30:31], v[160:161] op_sel:[1,1,0] op_sel_hi:[1,0,1] neg_lo:[0,1,0]
	s_nop 0
	v_pk_fma_f32 v[156:157], v[22:23], v[158:159], v[156:157] op_sel:[1,1,0] op_sel_hi:[1,0,1] neg_lo:[0,1,0]
	v_pk_mul_f32 v[18:19], v[16:17], v[16:17] op_sel:[0,0] op_sel_hi:[0,1]
	s_waitcnt lgkmcnt(0)
	v_pk_mul_f32 v[158:159], v[26:27], v[160:161] op_sel:[0,0] op_sel_hi:[0,1]
	v_pk_fma_f32 v[18:19], v[16:17], v[16:17], v[18:19] op_sel:[1,1,0] op_sel_hi:[1,0,1] neg_lo:[0,1,0]
	s_nop 0
	v_pk_fma_f32 v[158:159], v[26:27], v[160:161], v[158:159] op_sel:[1,1,0] op_sel_hi:[1,0,1] neg_lo:[0,1,0]
	v_pk_mul_f32 v[22:23], v[18:19], v[16:17] op_sel:[0,0] op_sel_hi:[0,1]
	v_pk_mul_f32 v[160:161], v[20:21], v[16:17] op_sel:[0,0] op_sel_hi:[0,1]
	v_pk_mul_f32 v[162:163], v[24:25], v[18:19] op_sel:[0,0] op_sel_hi:[0,1]
	s_nop 0
	v_pk_fma_f32 v[22:23], v[18:19], v[16:17], v[22:23] op_sel:[1,1,0] op_sel_hi:[1,0,1] neg_lo:[0,1,0]
	v_pk_fma_f32 v[160:161], v[20:21], v[16:17], v[160:161] op_sel:[1,1,0] op_sel_hi:[1,0,1] neg_lo:[0,1,0]
	v_pk_fma_f32 v[162:163], v[24:25], v[18:19], v[162:163] op_sel:[1,1,0] op_sel_hi:[1,0,1] neg_lo:[0,1,0]
	global_load_dwordx4 v[16:19], v[114:115], off
	v_pk_mul_f32 v[164:165], v[28:29], v[22:23] op_sel:[0,0] op_sel_hi:[0,1]
	v_mov_b32_e32 v114, 0
	v_pk_fma_f32 v[164:165], v[28:29], v[22:23], v[164:165] op_sel:[1,1,0] op_sel_hi:[1,0,1] neg_lo:[0,1,0]
	s_and_saveexec_b64 s[12:13], s[6:7]
	s_cbranch_execz .LBB0_446
; template <int R0> __device__ __forceinline__ void r0_inv_load(const LAS cf* X, const int N, int j0, f32x4 (&yr)[R0 / 2][2], f32x4 (&yi)[R0 / 2][2]) {
;     ...
;                 const cf t0 = a0 + a2, t1 = a0 - a2, t2 = a1 + a3, t3 = a1 - a3;
;                 VEL(yr[0], e + h) = t0.x + t2.x; VEL(yi[0], e + h) = t0.y + t2.y; VEL(yr[1], e + h) = t1.x - t3.y; VEL(yi[1], e + h) = t1.y + t3.x; }
; template <int R0> __device__ __forceinline__ void hy_pair(LAS cf* X, const int N, const int L, const int tid, const unsigned mA, const unsigned mB, const bf16_t* hyT, bf16_t* hyo, ...
;     ...
;         for (int n = 0; n < NL; ++n) { const int t0 = j0 + n * 4096; f32x4 va[2], vb[2], xa[2], xb[2];
;             conv8(hyT, ov + mA, t0, L, wv0, wv1, wv2, bv, va); conv8(hyT, ov + mB, t0, L, wv0, wv1, wv2, bv, vb);
;             conv8(hyT, oa + mA, t0, L, wa0, wa1, wa2, ba, xa); conv8(hyT, oa + mB, t0, L, wa0, wa1, wa2, ba, xb);
; #pragma unroll
;             for (int q4 = 0; q4 < 2; ++q4) { yr[n][q4] = xa[q4] * (yr[n][q4] + va[q4] * d0); yi[n][q4] = xb[q4] * (yi[n][q4] + vb[q4] * d0); }
	v_mov_b32_e32 v101, v33
	v_lshl_add_u64 v[20:21], v[100:101], 1, s[14:15]
	global_load_ushort v114, v[20:21], off
.LBB0_446:
	s_or_b64 exec, exec, s[12:13]
	s_and_saveexec_b64 s[12:13], s[8:9]
	s_cbranch_execz .LBB0_448
	v_mov_b32_e32 v103, v33
	v_lshl_add_u64 v[20:21], v[102:103], 1, s[14:15]
	global_load_ushort v103, v[20:21], off
.LBB0_448:
	s_or_b64 exec, exec, s[12:13]
	global_load_dwordx4 v[24:27], v[112:113], off
	v_mov_b32_e32 v101, 0
	v_mov_b32_e32 v112, 0
	s_and_saveexec_b64 s[12:13], s[6:7]
	s_cbranch_execz .LBB0_450
	v_mov_b32_e32 v105, v33
	v_lshl_add_u64 v[20:21], v[104:105], 1, s[14:15]
	global_load_ushort v112, v[20:21], off
.LBB0_450:
	s_or_b64 exec, exec, s[12:13]
	s_and_saveexec_b64 s[12:13], s[8:9]
	s_cbranch_execz .LBB0_452
	v_mov_b32_e32 v107, v33
	v_lshl_add_u64 v[20:21], v[106:107], 1, s[14:15]
	global_load_ushort v101, v[20:21], off
.LBB0_452:
	s_or_b64 exec, exec, s[12:13]
	s_add_i32 s48, s94, s96
	v_add_u32_e32 v32, s48, v209
	v_lshl_add_u64 v[20:21], v[32:33], 1, s[14:15]
	global_load_dwordx4 v[28:31], v[20:21], off
	v_mov_b32_e32 v167, 0
	v_mov_b32_e32 v168, 0
	s_and_saveexec_b64 s[12:13], s[6:7]
	s_cbranch_execz .LBB0_454
	v_add_u32_e32 v20, -1, v32
	v_mov_b32_e32 v21, v33
	v_lshl_add_u64 v[20:21], v[20:21], 1, s[14:15]
	global_load_ushort v168, v[20:21], off
.LBB0_454:
	s_or_b64 exec, exec, s[12:13]
	s_and_saveexec_b64 s[12:13], s[8:9]
	s_cbranch_execz .LBB0_456
	v_add_u32_e32 v32, 8, v32
	v_lshl_add_u64 v[20:21], v[32:33], 1, s[14:15]
	global_load_ushort v167, v[20:21], off
.LBB0_456:
	s_or_b64 exec, exec, s[12:13]
	s_add_i32 s80, s1, s96
	v_add_u32_e32 v32, s80, v209
	v_lshl_add_u64 v[20:21], v[32:33], 1, s[14:15]
	global_load_dwordx4 v[20:23], v[20:21], off
	v_mov_b32_e32 v105, 0
	v_mov_b32_e32 v106, 0
	s_and_saveexec_b64 s[12:13], s[6:7]
	s_cbranch_execz .LBB0_458
	v_add_u32_e32 v106, -1, v32
	v_mov_b32_e32 v107, v33
	v_lshl_add_u64 v[106:107], v[106:107], 1, s[14:15]
	global_load_ushort v106, v[106:107], off
.LBB0_458:
	s_or_b64 exec, exec, s[12:13]
	s_and_saveexec_b64 s[12:13], s[8:9]
	s_cbranch_execz .LBB0_460
	v_add_u32_e32 v32, 8, v32
	v_lshl_add_u64 v[104:105], v[32:33], 1, s[14:15]
	global_load_ushort v105, v[104:105], off
.LBB0_460:
	s_or_b64 exec, exec, s[12:13]
	v_pk_add_f32 v[220:221], v[0:1], v[118:119]
	v_pk_add_f32 v[222:223], v[116:117], v[120:121]
	v_pk_add_f32 v[224:225], v[2:3], v[124:125]
	v_pk_add_f32 v[226:227], v[122:123], v[126:127]
	v_mov_b32_e32 v228, v220
	v_mov_b32_e32 v229, v224
	v_mov_b32_e32 v230, v222
	v_mov_b32_e32 v231, v226
	v_mov_b32_e32 v224, v221
	v_mov_b32_e32 v226, v223
	v_pk_add_f32 v[228:229], v[228:229], v[230:231]
	v_pk_add_f32 v[220:221], v[224:225], v[226:227]
	v_pk_add_f32 v[222:223], v[4:5], v[130:131]
	v_pk_add_f32 v[224:225], v[128:129], v[132:133]
	v_pk_add_f32 v[226:227], v[6:7], v[136:137]
	v_pk_add_f32 v[230:231], v[134:135], v[138:139]
	v_mov_b32_e32 v232, v222
	v_mov_b32_e32 v233, v226
	v_mov_b32_e32 v234, v224
	v_mov_b32_e32 v235, v230
	v_mov_b32_e32 v226, v223
	v_mov_b32_e32 v230, v225
	s_waitcnt vmcnt(1)
	v_and_b32_e32 v173, 0xffff0000, v28
	v_and_b32_e32 v174, 0xffff0000, v29
	v_pk_add_f32 v[232:233], v[232:233], v[234:235]
	v_pk_add_f32 v[222:223], v[226:227], v[230:231]
	v_pk_add_f32 v[224:225], v[8:9], v[142:143]
	v_pk_add_f32 v[226:227], v[140:141], v[146:147]
	v_pk_add_f32 v[230:231], v[10:11], v[150:151]
	v_pk_add_f32 v[234:235], v[148:149], v[152:153]
	v_lshlrev_b32_e32 v171, 16, v29
	v_lshlrev_b32_e32 v172, 16, v28
	v_mov_b32_e32 v170, v173
	v_and_b32_e32 v175, 16, v30
	v_lshlrev_b32_e32 v29, 16, v30
	v_mov_b32_e32 v28, v174
	v_mov_b32_e32 v53, v52
	v_mov_b32_e32 v51, v50
	v_mov_b32_e32 v236, v224
	v_mov_b32_e32 v237, v230
	v_mov_b32_e32 v238, v226
	v_mov_b32_e32 v239, v234
	v_mov_b32_e32 v230, v225
	v_mov_b32_e32 v234, v227
	v_and_b32_e32 v176, 0xffff0000, v30
	v_pk_mov_b32 v[174:175], v[170:171], v[174:175] op_sel:[1,0]
	v_pk_fma_f32 v[178:179], v[28:29], v[50:51], v[52:53]
	v_pk_fma_f32 v[180:181], v[170:171], v[80:81], v[82:83]
	v_mov_b32_e32 v49, v48
	v_pk_add_f32 v[236:237], v[236:237], v[238:239]
	v_pk_add_f32 v[224:225], v[230:231], v[234:235]
	v_pk_add_f32 v[226:227], v[12:13], v[156:157]
	v_pk_add_f32 v[230:231], v[154:155], v[158:159]
	v_pk_add_f32 v[234:235], v[14:15], v[162:163]
	v_pk_add_f32 v[238:239], v[160:161], v[164:165]
	v_and_b32_e32 v166, 0xffff0000, v31
	v_mov_b32_e32 v169, v172
	v_and_b32_e32 v177, 16, v31
	v_lshlrev_b32_e32 v31, 16, v31
	v_mov_b32_e32 v30, v176
	v_pk_fma_f32 v[174:175], v[174:175], v[48:49], v[178:179]
	v_pk_fma_f32 v[172:173], v[172:173], v[78:79], v[180:181]
	v_mov_b32_e32 v47, v46
	v_mov_b32_e32 v241, v234
	v_mov_b32_e32 v243, v238
	v_mov_b32_e32 v234, v227
	v_mov_b32_e32 v238, v231
	v_pk_mov_b32 v[176:177], v[28:29], v[176:177] op_sel:[1,0]
	v_pk_fma_f32 v[170:171], v[170:171], v[46:47], v[174:175]
	s_waitcnt vmcnt(0)
	v_lshlrev_b32_e32 v114, 16, v114
	v_lshlrev_b32_e32 v103, 16, v103
	v_lshlrev_b32_e32 v112, 16, v112
	v_lshlrev_b32_e32 v101, 16, v101
	v_lshlrev_b32_e32 v168, 16, v168
	v_lshlrev_b32_e32 v167, 16, v167
	v_lshlrev_b32_e32 v106, 16, v106
	v_lshlrev_b32_e32 v105, 16, v105
	v_pk_fma_f32 v[168:169], v[168:169], v[76:77], v[172:173]
	v_mov_b32_e32 v172, v31
	v_mov_b32_e32 v173, v166
	v_pk_fma_f32 v[174:175], v[30:31], v[80:81], v[82:83]
	v_pk_fma_f32 v[166:167], v[166:167], v[50:51], v[52:53]
	v_mov_b32_e32 v240, v226
	v_pk_add_f32 v[226:227], v[234:235], v[238:239]
	s_waitcnt vmcnt(0)
; template <int R0> __device__ __forceinline__ void hy_pair(LAS cf* X, const int N, const int L, const int tid, const unsigned mA, const unsigned mB, const bf16_t* hyT, bf16_t* hyo, ...
;     ...
;         for (int n = 0; n < NL; ++n) { const int t0 = j0 + n * 4096; f32x4 va[2], vb[2], xa[2], xb[2];
;             conv8(hyT, ov + mA, t0, L, wv0, wv1, wv2, bv, va); conv8(hyT, ov + mB, t0, L, wv0, wv1, wv2, bv, vb);
;             conv8(hyT, oa + mA, t0, L, wa0, wa1, wa2, ba, xa); conv8(hyT, oa + mB, t0, L, wa0, wa1, wa2, ba, xb);
; #pragma unroll
;             for (int q4 = 0; q4 < 2; ++q4) { yr[n][q4] = xa[q4] * (yr[n][q4] + va[q4] * d0); yi[n][q4] = xb[q4] * (yi[n][q4] + vb[q4] * d0); }
; #pragma unroll
;             for (int e = 0; e < 8; e += 2) ZS[(unsigned)((t0 + e) >> 1)] = (f32x4){VEL(yr[n], e), VEL(yi[n], e), VEL(yr[n], e + 1), VEL(yi[n], e + 1)}; }
	v_and_b32_e32 v235, 0xffff0000, v20
	v_pk_fma_f32 v[166:167], v[172:173], v[48:49], v[166:167]
	v_pk_fma_f32 v[172:173], v[176:177], v[78:79], v[174:175]
	v_mov_b32_e32 v242, v230
	v_lshlrev_b32_e32 v231, 16, v21
	v_mov_b32_e32 v230, v235
	v_pk_fma_f32 v[28:29], v[28:29], v[76:77], v[172:173]
	v_and_b32_e32 v172, 0xffff0000, v25
	v_lshlrev_b32_e32 v234, 16, v20
	v_and_b32_e32 v238, 0xffff0000, v21
	v_pk_fma_f32 v[246:247], v[230:231], v[80:81], v[82:83]
	v_pk_fma_f32 v[30:31], v[30:31], v[46:47], v[166:167]
	v_lshlrev_b32_e32 v167, 16, v25
	v_lshlrev_b32_e32 v174, 16, v24
	v_and_b32_e32 v175, 0xffff0000, v24
	v_lshlrev_b32_e32 v25, 16, v26
	v_mov_b32_e32 v24, v172
	v_and_b32_e32 v177, 16, v27
	v_and_b32_e32 v176, 0xffff0000, v26
	v_pk_add_f32 v[240:241], v[240:241], v[242:243]
	v_and_b32_e32 v104, 0xffff0000, v23
	v_mov_b32_e32 v107, v234
	v_and_b32_e32 v239, 16, v22
	v_lshlrev_b32_e32 v21, 16, v22
	v_mov_b32_e32 v20, v238
	v_and_b32_e32 v243, 16, v23
	v_lshlrev_b32_e32 v23, 16, v23
	v_pk_fma_f32 v[234:235], v[234:235], v[78:79], v[246:247]
	v_mov_b32_e32 v166, v175
	v_and_b32_e32 v173, 16, v26
	v_pk_mov_b32 v[178:179], v[24:25], v[176:177] op_sel:[1,0]
	v_and_b32_e32 v177, 0xffff0000, v16
	v_and_b32_e32 v214, 0xffff0000, v17
	v_and_b32_e32 v242, 0xffff0000, v22
	v_pk_mov_b32 v[238:239], v[230:231], v[238:239] op_sel:[1,0]
	v_pk_fma_f32 v[244:245], v[20:21], v[50:51], v[52:53]
	v_pk_fma_f32 v[106:107], v[106:107], v[76:77], v[234:235]
	v_mov_b32_e32 v234, v23
	v_mov_b32_e32 v235, v104
	v_pk_fma_f32 v[104:105], v[104:105], v[50:51], v[52:53]
	v_mov_b32_e32 v26, v176
	v_pk_mov_b32 v[180:181], v[166:167], v[172:173] op_sel:[1,0]
	v_lshlrev_b32_e32 v173, 16, v17
	v_lshlrev_b32_e32 v176, 16, v16
	v_mov_b32_e32 v172, v177
	v_and_b32_e32 v215, 16, v18
	v_lshlrev_b32_e32 v17, 16, v18
	v_mov_b32_e32 v16, v214
	v_mov_b32_e32 v22, v242
	v_pk_fma_f32 v[238:239], v[238:239], v[48:49], v[244:245]
	v_pk_fma_f32 v[104:105], v[234:235], v[48:49], v[104:105]
	v_mov_b32_e32 v45, v44
	v_mov_b32_e32 v43, v42
	v_pk_mov_b32 v[214:215], v[172:173], v[214:215] op_sel:[1,0]
	v_pk_fma_f32 v[230:231], v[230:231], v[46:47], v[238:239]
	v_pk_fma_f32 v[238:239], v[22:23], v[80:81], v[82:83]
	v_pk_fma_f32 v[22:23], v[22:23], v[46:47], v[104:105]
	v_pk_fma_f32 v[104:105], v[16:17], v[42:43], v[44:45]
	v_mov_b32_e32 v41, v40
	v_pk_fma_f32 v[104:105], v[214:215], v[40:41], v[104:105]
	v_mov_b32_e32 v39, v38
	v_pk_mov_b32 v[242:243], v[20:21], v[242:243] op_sel:[1,0]
	v_pk_fma_f32 v[104:105], v[172:173], v[38:39], v[104:105]
	v_mov_b32_e32 v65, v64
	v_pk_fma_f32 v[234:235], v[242:243], v[78:79], v[238:239]
	v_pk_fma_f32 v[104:105], v[64:65], v[104:105], v[232:233]
	v_pk_fma_f32 v[20:21], v[20:21], v[76:77], v[234:235]
	v_pk_fma_f32 v[234:235], v[172:173], v[72:73], v[74:75]
	v_pk_mul_f32 v[172:173], v[104:105], v[170:171]
	v_pk_fma_f32 v[104:105], v[24:25], v[42:43], v[44:45]
	v_and_b32_e32 v216, 0xffff0000, v18
	v_pk_fma_f32 v[104:105], v[180:181], v[40:41], v[104:105]
	v_and_b32_e32 v102, 0xffff0000, v19
	v_pk_fma_f32 v[104:105], v[166:167], v[38:39], v[104:105]
	v_mov_b32_e32 v115, v176
	v_and_b32_e32 v217, 16, v19
	v_lshlrev_b32_e32 v19, 16, v19
	v_mov_b32_e32 v18, v216
	v_pk_fma_f32 v[176:177], v[176:177], v[70:71], v[234:235]
	v_pk_fma_f32 v[104:105], v[64:65], v[104:105], v[222:223]
	v_pk_mov_b32 v[216:217], v[16:17], v[216:217] op_sel:[1,0]
	v_mov_b32_e32 v218, v19
	v_mov_b32_e32 v219, v102
	v_pk_fma_f32 v[114:115], v[114:115], v[68:69], v[176:177]
	v_pk_mul_f32 v[170:171], v[104:105], v[230:231]
	v_pk_fma_f32 v[102:103], v[102:103], v[42:43], v[44:45]
	v_pk_fma_f32 v[104:105], v[18:19], v[72:73], v[74:75]
	v_pk_fma_f32 v[114:115], v[66:67], v[114:115], v[228:229]
	v_pk_fma_f32 v[104:105], v[216:217], v[70:71], v[104:105]
	v_pk_fma_f32 v[102:103], v[218:219], v[40:41], v[102:103]
	v_pk_mul_f32 v[176:177], v[114:115], v[168:169]
	v_pk_fma_f32 v[114:115], v[166:167], v[72:73], v[74:75]
	v_pk_fma_f32 v[18:19], v[18:19], v[38:39], v[102:103]
	v_pk_fma_f32 v[16:17], v[16:17], v[68:69], v[104:105]
	v_and_b32_e32 v100, 0xffff0000, v27
	v_mov_b32_e32 v113, v174
	v_lshlrev_b32_e32 v27, 16, v27
	v_pk_fma_f32 v[114:115], v[174:175], v[70:71], v[114:115]
	v_pk_fma_f32 v[16:17], v[66:67], v[16:17], v[236:237]
	v_pk_fma_f32 v[18:19], v[64:65], v[18:19], v[240:241]
	v_mov_b32_e32 v212, v27
	v_mov_b32_e32 v213, v100
	v_pk_fma_f32 v[112:113], v[112:113], v[68:69], v[114:115]
	v_pk_mul_f32 v[114:115], v[18:19], v[30:31]
	v_pk_mul_f32 v[168:169], v[16:17], v[28:29]
	v_pk_fma_f32 v[16:17], v[100:101], v[42:43], v[44:45]
	v_pk_fma_f32 v[18:19], v[26:27], v[72:73], v[74:75]
	v_pk_fma_f32 v[16:17], v[212:213], v[40:41], v[16:17]
	v_pk_fma_f32 v[18:19], v[178:179], v[70:71], v[18:19]
	v_pk_fma_f32 v[112:113], v[66:67], v[112:113], v[220:221]
	v_pk_fma_f32 v[16:17], v[26:27], v[38:39], v[16:17]
	v_pk_fma_f32 v[18:19], v[24:25], v[68:69], v[18:19]
	v_pk_mul_f32 v[174:175], v[112:113], v[106:107]
	v_pk_fma_f32 v[18:19], v[66:67], v[18:19], v[224:225]
	v_pk_fma_f32 v[16:17], v[64:65], v[16:17], v[226:227]
	v_ashrrev_i32_e32 v32, 1, v209
	v_pk_mul_f32 v[112:113], v[16:17], v[22:23]
	v_pk_mul_f32 v[166:167], v[18:19], v[20:21]
	v_lshl_add_u64 v[104:105], v[32:33], 4, s[44:45]
	v_mov_b32_e32 v16, v176
	v_mov_b32_e32 v17, v174
	v_mov_b32_e32 v18, v177
	v_mov_b32_e32 v19, v175
	global_store_dwordx4 v[104:105], v[16:19], off
	v_mov_b32_e32 v95, 0
	s_nop 0
	v_add_u32_e32 v16, 2, v209
	v_ashrrev_i32_e32 v32, 1, v16
	v_lshl_add_u64 v[106:107], v[32:33], 4, s[44:45]
	v_mov_b32_e32 v16, v172
	v_mov_b32_e32 v17, v170
	v_mov_b32_e32 v18, v173
	v_mov_b32_e32 v19, v171
	global_store_dwordx4 v[106:107], v[16:19], off
	s_nop 1
	v_add_u32_e32 v16, 4, v209
	v_ashrrev_i32_e32 v32, 1, v16
	v_lshl_add_u64 v[100:101], v[32:33], 4, s[44:45]
	v_mov_b32_e32 v16, v168
	v_mov_b32_e32 v17, v166
	v_mov_b32_e32 v18, v169
	v_mov_b32_e32 v19, v167
	global_store_dwordx4 v[100:101], v[16:19], off
	s_nop 1
	v_add_u32_e32 v16, 6, v209
	v_ashrrev_i32_e32 v32, 1, v16
	v_lshl_add_u64 v[102:103], v[32:33], 4, s[44:45]
	v_mov_b32_e32 v16, v114
	v_mov_b32_e32 v17, v112
	v_mov_b32_e32 v18, v115
	v_mov_b32_e32 v19, v113
	global_store_dwordx4 v[102:103], v[16:19], off
	global_load_dwordx4 v[16:19], v[96:97], off
	v_mov_b32_e32 v96, 0
	s_and_saveexec_b64 s[12:13], vcc
	s_cbranch_execz .LBB0_462
	v_mov_b32_e32 v93, v33
	v_lshl_add_u64 v[20:21], v[92:93], 1, s[14:15]
	global_load_ushort v96, v[20:21], off
; template <int R0> __device__ __forceinline__ void r0_inv_load(const LAS cf* X, const int N, int j0, f32x4 (&yr)[R0 / 2][2], f32x4 (&yi)[R0 / 2][2]) {
;     ...
;                 const cf t0 = a0 + a2, t1 = a0 - a2, t2 = a1 + a3, t3 = a1 - a3;
;                 VEL(yr[0], e + h) = t0.x + t2.x; VEL(yi[0], e + h) = t0.y + t2.y; VEL(yr[1], e + h) = t1.x - t3.y; VEL(yi[1], e + h) = t1.y + t3.x; }
; template <int R0> __device__ __forceinline__ void hy_pair(LAS cf* X, const int N, const int L, const int tid, const unsigned mA, const unsigned mB, const bf16_t* hyT, bf16_t* hyo, ...
;     ...
;         for (int n = 0; n < NL; ++n) { const int t0 = j0 + n * 4096; f32x4 va[2], vb[2], xa[2], xb[2];
;             conv8(hyT, ov + mA, t0, L, wv0, wv1, wv2, bv, va); conv8(hyT, ov + mB, t0, L, wv0, wv1, wv2, bv, vb);
;             conv8(hyT, oa + mA, t0, L, wa0, wa1, wa2, ba, xa); conv8(hyT, oa + mB, t0, L, wa0, wa1, wa2, ba, xb);
; #pragma unroll
;             for (int q4 = 0; q4 < 2; ++q4) { yr[n][q4] = xa[q4] * (yr[n][q4] + va[q4] * d0); yi[n][q4] = xb[q4] * (yi[n][q4] + vb[q4] * d0); }
.LBB0_462:
	s_or_b64 exec, exec, s[12:13]
	s_and_saveexec_b64 s[12:13], s[4:5]
	s_cbranch_execz .LBB0_464
	v_mov_b32_e32 v95, v33
	v_lshl_add_u64 v[20:21], v[94:95], 1, s[14:15]
	global_load_ushort v95, v[20:21], off
.LBB0_464:
	s_or_b64 exec, exec, s[12:13]
	global_load_dwordx4 v[24:27], v[110:111], off
	v_mov_b32_e32 v93, 0
	v_mov_b32_e32 v110, 0
	s_and_saveexec_b64 s[12:13], vcc
	s_cbranch_execz .LBB0_466
	v_mov_b32_e32 v99, v33
	v_lshl_add_u64 v[20:21], v[98:99], 1, s[14:15]
	global_load_ushort v110, v[20:21], off
.LBB0_466:
	s_or_b64 exec, exec, s[12:13]
	s_and_saveexec_b64 s[12:13], s[4:5]
	s_cbranch_execz .LBB0_468
	v_mov_b32_e32 v109, v33
	v_lshl_add_u64 v[20:21], v[108:109], 1, s[14:15]
	global_load_ushort v93, v[20:21], off
.LBB0_468:
	s_or_b64 exec, exec, s[12:13]
	v_add_u32_e32 v32, s48, v208
	v_lshl_add_u64 v[20:21], v[32:33], 1, s[14:15]
	global_load_dwordx4 v[28:31], v[20:21], off
	v_mov_b32_e32 v179, 0
	v_mov_b32_e32 v180, 0
	s_and_saveexec_b64 s[12:13], vcc
	s_cbranch_execz .LBB0_470
	v_add_u32_e32 v20, -1, v32
	v_mov_b32_e32 v21, v33
	v_lshl_add_u64 v[20:21], v[20:21], 1, s[14:15]
	global_load_ushort v180, v[20:21], off
.LBB0_470:
	s_or_b64 exec, exec, s[12:13]
	s_and_saveexec_b64 s[12:13], s[4:5]
	s_cbranch_execz .LBB0_472
	v_add_u32_e32 v32, 8, v32
	v_lshl_add_u64 v[20:21], v[32:33], 1, s[14:15]
	global_load_ushort v179, v[20:21], off
.LBB0_472:
	s_or_b64 exec, exec, s[12:13]
	v_add_u32_e32 v32, s80, v208
	v_lshl_add_u64 v[20:21], v[32:33], 1, s[14:15]
	global_load_dwordx4 v[20:23], v[20:21], off
	v_mov_b32_e32 v99, 0
	v_mov_b32_e32 v108, 0
	s_and_saveexec_b64 s[12:13], vcc
	s_cbranch_execz .LBB0_474
	v_add_u32_e32 v108, -1, v32
	v_mov_b32_e32 v109, v33
	v_lshl_add_u64 v[108:109], v[108:109], 1, s[14:15]
	global_load_ushort v108, v[108:109], off
.LBB0_474:
	s_or_b64 exec, exec, s[12:13]
	s_and_saveexec_b64 s[12:13], s[4:5]
	s_cbranch_execz .LBB0_476
	v_add_u32_e32 v32, 8, v32
	v_lshl_add_u64 v[98:99], v[32:33], 1, s[14:15]
	global_load_ushort v99, v[98:99], off
.LBB0_476:
	s_or_b64 exec, exec, s[12:13]
	v_pk_add_f32 v[0:1], v[0:1], v[118:119] neg_lo:[0,1] neg_hi:[0,1]
	v_pk_add_f32 v[116:117], v[116:117], v[120:121] neg_lo:[0,1] neg_hi:[0,1]
	v_pk_add_f32 v[2:3], v[2:3], v[124:125] neg_lo:[0,1] neg_hi:[0,1]
	v_pk_add_f32 v[118:119], v[122:123], v[126:127] neg_lo:[0,1] neg_hi:[0,1]
	v_mov_b32_e32 v121, v2
	v_mov_b32_e32 v122, v117
	v_mov_b32_e32 v2, v1
	v_mov_b32_e32 v117, v118
	v_mov_b32_e32 v120, v0
	v_mov_b32_e32 v123, v119
	v_pk_add_f32 v[0:1], v[2:3], v[116:117]
	v_pk_add_f32 v[2:3], v[4:5], v[130:131] neg_lo:[0,1] neg_hi:[0,1]
	v_pk_add_f32 v[4:5], v[128:129], v[132:133] neg_lo:[0,1] neg_hi:[0,1]
	v_pk_add_f32 v[6:7], v[6:7], v[136:137] neg_lo:[0,1] neg_hi:[0,1]
	v_pk_add_f32 v[116:117], v[134:135], v[138:139] neg_lo:[0,1] neg_hi:[0,1]
	v_pk_add_f32 v[120:121], v[120:121], v[122:123] neg_lo:[0,1] neg_hi:[0,1]
	v_mov_b32_e32 v119, v6
	v_mov_b32_e32 v122, v5
	v_mov_b32_e32 v6, v3
	v_mov_b32_e32 v5, v116
	v_mov_b32_e32 v118, v2
	v_mov_b32_e32 v123, v117
	v_pk_add_f32 v[2:3], v[6:7], v[4:5]
	v_pk_add_f32 v[4:5], v[8:9], v[142:143] neg_lo:[0,1] neg_hi:[0,1]
	v_pk_add_f32 v[6:7], v[140:141], v[146:147] neg_lo:[0,1] neg_hi:[0,1]
	v_pk_add_f32 v[8:9], v[10:11], v[150:151] neg_lo:[0,1] neg_hi:[0,1]
	v_pk_add_f32 v[10:11], v[148:149], v[152:153] neg_lo:[0,1] neg_hi:[0,1]
	v_pk_add_f32 v[118:119], v[118:119], v[122:123] neg_lo:[0,1] neg_hi:[0,1]
	v_mov_b32_e32 v117, v8
	v_mov_b32_e32 v122, v7
	v_mov_b32_e32 v8, v5
	v_mov_b32_e32 v7, v10
	v_mov_b32_e32 v116, v4
	v_mov_b32_e32 v123, v11
	v_pk_add_f32 v[4:5], v[8:9], v[6:7]
	v_pk_add_f32 v[6:7], v[12:13], v[156:157] neg_lo:[0,1] neg_hi:[0,1]
	v_pk_add_f32 v[8:9], v[154:155], v[158:159] neg_lo:[0,1] neg_hi:[0,1]
	v_pk_add_f32 v[10:11], v[14:15], v[162:163] neg_lo:[0,1] neg_hi:[0,1]
	v_pk_add_f32 v[12:13], v[160:161], v[164:165] neg_lo:[0,1] neg_hi:[0,1]
	v_pk_add_f32 v[116:117], v[116:117], v[122:123] neg_lo:[0,1] neg_hi:[0,1]
	v_mov_b32_e32 v15, v10
	v_mov_b32_e32 v122, v9
	v_mov_b32_e32 v10, v7
	v_mov_b32_e32 v9, v12
	v_mov_b32_e32 v123, v13
	v_pk_add_f32 v[12:13], v[10:11], v[8:9]
	s_waitcnt vmcnt(0)
	v_and_b32_e32 v9, 0xffff0000, v20
	v_and_b32_e32 v10, 0xffff0000, v21
	v_mov_b32_e32 v53, v52
	v_mov_b32_e32 v51, v50
	v_mov_b32_e32 v14, v6
	v_lshlrev_b32_e32 v7, 16, v21
	v_lshlrev_b32_e32 v8, 16, v20
	v_mov_b32_e32 v6, v9
	v_and_b32_e32 v11, 16, v22
	v_lshlrev_b32_e32 v21, 16, v22
	v_mov_b32_e32 v20, v10
	v_and_b32_e32 v215, 0xffff0000, v28
	v_and_b32_e32 v216, 0xffff0000, v29
	v_mov_b32_e32 v49, v48
	v_pk_add_f32 v[14:15], v[14:15], v[122:123] neg_lo:[0,1] neg_hi:[0,1]
	v_and_b32_e32 v122, 0xffff0000, v22
	v_pk_mov_b32 v[10:11], v[6:7], v[10:11] op_sel:[1,0]
	v_pk_fma_f32 v[124:125], v[20:21], v[50:51], v[52:53]
	v_lshlrev_b32_e32 v213, 16, v29
	v_lshlrev_b32_e32 v214, 16, v28
	v_mov_b32_e32 v212, v215
	v_and_b32_e32 v217, 16, v30
	v_lshlrev_b32_e32 v29, 16, v30
	v_mov_b32_e32 v28, v216
	v_mov_b32_e32 v47, v46
	v_and_b32_e32 v98, 0xffff0000, v23
	v_and_b32_e32 v123, 16, v23
	v_lshlrev_b32_e32 v23, 16, v23
	v_mov_b32_e32 v22, v122
	v_pk_fma_f32 v[126:127], v[6:7], v[80:81], v[82:83]
	v_pk_fma_f32 v[10:11], v[10:11], v[48:49], v[124:125]
	v_and_b32_e32 v218, 0xffff0000, v30
	v_pk_mov_b32 v[216:217], v[212:213], v[216:217] op_sel:[1,0]
	v_pk_fma_f32 v[220:221], v[28:29], v[50:51], v[52:53]
	v_pk_fma_f32 v[222:223], v[212:213], v[80:81], v[82:83]
	v_and_b32_e32 v225, 0xffff0000, v16
	v_mov_b32_e32 v109, v8
	v_pk_mov_b32 v[122:123], v[20:21], v[122:123] op_sel:[1,0]
	v_pk_fma_f32 v[8:9], v[8:9], v[78:79], v[126:127]
	v_pk_fma_f32 v[6:7], v[6:7], v[46:47], v[10:11]
	v_pk_fma_f32 v[10:11], v[22:23], v[80:81], v[82:83]
	v_and_b32_e32 v178, 0xffff0000, v31
	v_mov_b32_e32 v181, v214
	v_and_b32_e32 v219, 16, v31
	v_lshlrev_b32_e32 v31, 16, v31
	v_mov_b32_e32 v30, v218
	v_pk_fma_f32 v[216:217], v[216:217], v[48:49], v[220:221]
	v_pk_fma_f32 v[214:215], v[214:215], v[78:79], v[222:223]
	v_lshlrev_b32_e32 v223, 16, v17
	v_mov_b32_e32 v222, v225
	v_and_b32_e32 v226, 0xffff0000, v17
	s_waitcnt vmcnt(0)
; template <int R0> __device__ __forceinline__ void hy_pair(LAS cf* X, const int N, const int L, const int tid, const unsigned mA, const unsigned mB, const bf16_t* hyT, bf16_t* hyo, ...
;     ...
;         for (int n = 0; n < NL; ++n) { const int t0 = j0 + n * 4096; f32x4 va[2], vb[2], xa[2], xb[2];
;             conv8(hyT, ov + mA, t0, L, wv0, wv1, wv2, bv, va); conv8(hyT, ov + mB, t0, L, wv0, wv1, wv2, bv, vb);
;             conv8(hyT, oa + mA, t0, L, wa0, wa1, wa2, ba, xa); conv8(hyT, oa + mB, t0, L, wa0, wa1, wa2, ba, xb);
; #pragma unroll
;             for (int q4 = 0; q4 < 2; ++q4) { yr[n][q4] = xa[q4] * (yr[n][q4] + va[q4] * d0); yi[n][q4] = xb[q4] * (yi[n][q4] + vb[q4] * d0); }
; #pragma unroll
;             for (int e = 0; e < 8; e += 2) ZS[(unsigned)((t0 + e) >> 1)] = (f32x4){VEL(yr[n], e), VEL(yi[n], e), VEL(yr[n], e + 1), VEL(yi[n], e + 1)}; }
;         r0_fwd_store<R0>(X, N, j0, yr, yi); }
	v_lshlrev_b32_e32 v96, 16, v96
	v_lshlrev_b32_e32 v95, 16, v95
	v_lshlrev_b32_e32 v110, 16, v110
	v_lshlrev_b32_e32 v93, 16, v93
	v_lshlrev_b32_e32 v180, 16, v180
	v_lshlrev_b32_e32 v179, 16, v179
	v_lshlrev_b32_e32 v108, 16, v108
	v_lshlrev_b32_e32 v99, 16, v99
	v_pk_fma_f32 v[108:109], v[108:109], v[76:77], v[8:9]
	v_mov_b32_e32 v8, v23
	v_mov_b32_e32 v9, v98
	v_pk_fma_f32 v[98:99], v[98:99], v[50:51], v[52:53]
	v_pk_fma_f32 v[10:11], v[122:123], v[78:79], v[10:11]
	v_pk_mov_b32 v[218:219], v[28:29], v[218:219] op_sel:[1,0]
	v_pk_fma_f32 v[212:213], v[212:213], v[46:47], v[216:217]
	v_pk_fma_f32 v[180:181], v[180:181], v[76:77], v[214:215]
	v_mov_b32_e32 v214, v31
	v_mov_b32_e32 v215, v178
	v_pk_fma_f32 v[216:217], v[30:31], v[80:81], v[82:83]
	v_pk_fma_f32 v[178:179], v[178:179], v[50:51], v[52:53]
	v_lshlrev_b32_e32 v224, 16, v16
	v_and_b32_e32 v227, 16, v18
	v_lshlrev_b32_e32 v17, 16, v18
	v_mov_b32_e32 v16, v226
	v_pk_fma_f32 v[8:9], v[8:9], v[48:49], v[98:99]
	v_pk_fma_f32 v[20:21], v[20:21], v[76:77], v[10:11]
	v_mov_b32_e32 v45, v44
	v_mov_b32_e32 v43, v42
	v_pk_fma_f32 v[10:11], v[222:223], v[72:73], v[74:75]
	v_pk_fma_f32 v[178:179], v[214:215], v[48:49], v[178:179]
	v_pk_fma_f32 v[214:215], v[218:219], v[78:79], v[216:217]
	v_mov_b32_e32 v97, v224
	v_pk_mov_b32 v[226:227], v[222:223], v[226:227] op_sel:[1,0]
	v_pk_fma_f32 v[22:23], v[22:23], v[46:47], v[8:9]
	v_pk_fma_f32 v[8:9], v[16:17], v[42:43], v[44:45]
	v_mov_b32_e32 v41, v40
	v_pk_fma_f32 v[10:11], v[224:225], v[70:71], v[10:11]
	v_pk_fma_f32 v[28:29], v[28:29], v[76:77], v[214:215]
	v_and_b32_e32 v215, 0xffff0000, v24
	v_pk_fma_f32 v[8:9], v[226:227], v[40:41], v[8:9]
	v_mov_b32_e32 v39, v38
	v_pk_fma_f32 v[10:11], v[96:97], v[68:69], v[10:11]
	v_pk_fma_f32 v[30:31], v[30:31], v[46:47], v[178:179]
	v_lshlrev_b32_e32 v179, 16, v25
	v_mov_b32_e32 v178, v215
	v_and_b32_e32 v216, 0xffff0000, v25
	v_pk_fma_f32 v[8:9], v[222:223], v[38:39], v[8:9]
	v_pk_fma_f32 v[96:97], v[66:67], v[10:11], v[120:121]
	v_mov_b32_e32 v65, v64
	v_lshlrev_b32_e32 v214, 16, v24
	v_and_b32_e32 v217, 16, v26
	v_lshlrev_b32_e32 v25, 16, v26
	v_mov_b32_e32 v24, v216
	v_pk_fma_f32 v[8:9], v[64:65], v[8:9], v[118:119]
	v_pk_mul_f32 v[118:119], v[96:97], v[180:181]
	v_pk_fma_f32 v[96:97], v[178:179], v[72:73], v[74:75]
	v_mov_b32_e32 v111, v214
	v_pk_mov_b32 v[216:217], v[178:179], v[216:217] op_sel:[1,0]
	v_pk_mul_f32 v[10:11], v[8:9], v[212:213]
	v_pk_fma_f32 v[8:9], v[24:25], v[42:43], v[44:45]
	v_pk_fma_f32 v[96:97], v[214:215], v[70:71], v[96:97]
	v_pk_fma_f32 v[8:9], v[216:217], v[40:41], v[8:9]
	v_pk_fma_f32 v[96:97], v[110:111], v[68:69], v[96:97]
	v_and_b32_e32 v94, 0xffff0000, v19
	v_and_b32_e32 v229, 16, v19
	v_and_b32_e32 v228, 0xffff0000, v18
	v_lshlrev_b32_e32 v19, 16, v19
	v_pk_fma_f32 v[8:9], v[178:179], v[38:39], v[8:9]
	v_pk_fma_f32 v[0:1], v[66:67], v[96:97], v[0:1]
	v_mov_b32_e32 v18, v228
	v_mov_b32_e32 v230, v19
	v_mov_b32_e32 v231, v94
	v_pk_fma_f32 v[2:3], v[64:65], v[8:9], v[2:3]
	v_pk_mul_f32 v[108:109], v[0:1], v[108:109]
	v_pk_fma_f32 v[0:1], v[94:95], v[42:43], v[44:45]
	v_pk_mov_b32 v[228:229], v[16:17], v[228:229] op_sel:[1,0]
	v_pk_mul_f32 v[8:9], v[2:3], v[6:7]
	v_pk_fma_f32 v[2:3], v[18:19], v[72:73], v[74:75]
	v_pk_fma_f32 v[0:1], v[230:231], v[40:41], v[0:1]
	v_and_b32_e32 v218, 0xffff0000, v26
	v_pk_fma_f32 v[2:3], v[228:229], v[70:71], v[2:3]
	v_pk_fma_f32 v[0:1], v[18:19], v[38:39], v[0:1]
	v_and_b32_e32 v92, 0xffff0000, v27
	v_and_b32_e32 v219, 16, v27
	v_lshlrev_b32_e32 v27, 16, v27
	v_mov_b32_e32 v26, v218
	v_pk_fma_f32 v[2:3], v[16:17], v[68:69], v[2:3]
	v_pk_fma_f32 v[0:1], v[64:65], v[0:1], v[14:15]
	v_pk_mov_b32 v[218:219], v[24:25], v[218:219] op_sel:[1,0]
	v_mov_b32_e32 v220, v27
	v_mov_b32_e32 v221, v92
	v_pk_fma_f32 v[6:7], v[66:67], v[2:3], v[116:117]
	v_pk_mul_f32 v[2:3], v[0:1], v[30:31]
	v_pk_fma_f32 v[0:1], v[92:93], v[42:43], v[44:45]
	v_pk_fma_f32 v[14:15], v[26:27], v[72:73], v[74:75]
	v_pk_fma_f32 v[0:1], v[220:221], v[40:41], v[0:1]
	v_pk_fma_f32 v[14:15], v[218:219], v[70:71], v[14:15]
	v_pk_fma_f32 v[0:1], v[26:27], v[38:39], v[0:1]
	v_pk_fma_f32 v[14:15], v[24:25], v[68:69], v[14:15]
	v_ashrrev_i32_e32 v32, 1, v208
	v_pk_fma_f32 v[4:5], v[66:67], v[14:15], v[4:5]
	v_pk_fma_f32 v[0:1], v[64:65], v[0:1], v[12:13]
	v_lshl_add_u64 v[96:97], v[32:33], 4, s[44:45]
	v_mov_b32_e32 v12, v118
	v_mov_b32_e32 v13, v108
	v_mov_b32_e32 v14, v119
	v_mov_b32_e32 v15, v109
	global_store_dwordx4 v[96:97], v[12:15], off
	v_pk_mul_f32 v[6:7], v[6:7], v[28:29]
	v_pk_mul_f32 v[4:5], v[4:5], v[20:21]
	v_add_u32_e32 v12, 0x1002, v209
	v_ashrrev_i32_e32 v32, 1, v12
	v_lshl_add_u64 v[98:99], v[32:33], 4, s[44:45]
	v_mov_b32_e32 v12, v10
	v_mov_b32_e32 v13, v8
	v_mov_b32_e32 v14, v11
	v_mov_b32_e32 v15, v9
	global_store_dwordx4 v[98:99], v[12:15], off
	v_pk_mul_f32 v[0:1], v[0:1], v[22:23]
	v_mov_b32_e32 v20, v176
	v_add_u32_e32 v12, 0x1004, v209
	v_ashrrev_i32_e32 v32, 1, v12
	v_lshl_add_u64 v[92:93], v[32:33], 4, s[44:45]
	v_mov_b32_e32 v12, v6
	v_mov_b32_e32 v13, v4
	v_mov_b32_e32 v14, v7
	v_mov_b32_e32 v15, v5
	global_store_dwordx4 v[92:93], v[12:15], off
	v_mov_b32_e32 v21, v174
	v_xor_b32_e32 v25, 0x80000000, v118
	v_add_u32_e32 v12, 0x1006, v209
	v_ashrrev_i32_e32 v32, 1, v12
	v_lshl_add_u64 v[94:95], v[32:33], 4, s[44:45]
	v_mov_b32_e32 v12, v2
	v_mov_b32_e32 v13, v0
	v_mov_b32_e32 v14, v3
	v_mov_b32_e32 v15, v1
	global_store_dwordx4 v[94:95], v[12:15], off
	v_mov_b32_e32 v24, v108
	v_pk_add_f32 v[30:31], v[20:21], v[24:25]
	v_mov_b32_e32 v12, v209
	v_mov_b32_e32 v22, v118
	v_cvt_f32_i32_e32 v13, v12
	v_mov_b32_e32 v23, v108
	v_pk_add_f32 v[14:15], v[20:21], v[22:23]
; #define LAS __attribute__((address_space(3)))
; template <int R0> __device__ __forceinline__ void r0_fwd_store(LAS cf* X, const int N, int j0, const f32x4 (&ar)[R0 / 2][2], const f32x4 (&ai)[R0 / 2][2]) {
;     constexpr int q = 4096; const float rN = 1.0f / (float)N; asm volatile("" : "+v"(j0));
; #pragma unroll
;     for (int e = 0; e < 8; e += 2) {
;         cf y[R0][2];
; #pragma unroll
;         for (int h = 0; h < 2; ++h) { const int j = j0 + e + h; const cf w1 = twid((float)j * rN, false);
;             if constexpr (R0 == 4) { const cf a0 = cf{VEL(ar[0], e + h), VEL(ai[0], e + h)}, a1 = cf{VEL(ar[1], e + h), VEL(ai[1], e + h)}; const cf m = cf{a1.y, -a1.x};
;                 const cf w2 = cmul(w1, w1), w3 = cmul(w2, w1);
;                 y[0][h] = a0 + a1; y[1][h] = cmul(a0 + m, w1); y[2][h] = cmul(a0 - a1, w2); y[3][h] = cmul(a0 - m, w3); }
;             else { const cf a0 = cf{VEL(ar[0], e + h), VEL(ai[0], e + h)}; y[0][h] = a0; y[1][h] = cmul(a0, w1); } }
; #pragma unroll
;         for (int k = 0; k < R0; ++k) *(LAS f32x4*)(X + fphys(j0 + e + k * q)) = (f32x4){y[k][0].x, y[k][0].y, y[k][1].x, y[k][1].y};
;     }
	v_mov_b32_e32 v174, v177
	v_mul_f32_e32 v13, 0x38800000, v13
	v_cos_f32_e32 v16, v13
	v_sin_f32_e64 v17, -v13
	v_add_u32_e32 v13, 1, v12
	v_cvt_f32_i32_e32 v13, v13
	s_nop 1
	v_mov_b32_e32 v108, v119
	v_pk_mul_f32 v[26:27], v[16:17], v[16:17] op_sel:[0,0] op_sel_hi:[0,1]
	v_pk_mul_f32 v[18:19], v[30:31], v[16:17] op_sel:[0,0] op_sel_hi:[0,1]
	v_mul_f32_e32 v13, 0x38800000, v13
	v_pk_fma_f32 v[26:27], v[16:17], v[16:17], v[26:27] op_sel:[1,1,0] op_sel_hi:[1,0,1] neg_lo:[0,1,0]
	v_pk_fma_f32 v[18:19], v[30:31], v[16:17], v[18:19] op_sel:[1,1,0] op_sel_hi:[1,0,1] neg_lo:[0,1,0]
	v_cos_f32_e32 v30, v13
	v_pk_mul_f32 v[28:29], v[26:27], v[16:17] op_sel:[0,0] op_sel_hi:[0,1]
	v_sin_f32_e64 v31, -v13
	v_ashrrev_i32_e32 v13, 4, v12
	v_pk_fma_f32 v[28:29], v[26:27], v[16:17], v[28:29] op_sel:[1,1,0] op_sel_hi:[1,0,1] neg_lo:[0,1,0]
	v_pk_add_f32 v[16:17], v[20:21], v[22:23] neg_lo:[0,1] neg_hi:[0,1]
	v_lshlrev_b32_e32 v13, 3, v13
	v_pk_mul_f32 v[22:23], v[16:17], v[26:27] op_sel:[0,0] op_sel_hi:[0,1]
	v_and_b32_e32 v13, -16, v13
	v_pk_fma_f32 v[22:23], v[16:17], v[26:27], v[22:23] op_sel:[1,1,0] op_sel_hi:[1,0,1] neg_lo:[0,1,0]
	v_pk_add_f32 v[16:17], v[20:21], v[24:25] neg_lo:[0,1] neg_hi:[0,1]
	v_lshlrev_b32_e32 v32, 3, v12
	v_pk_mul_f32 v[26:27], v[16:17], v[28:29] op_sel:[0,0] op_sel_hi:[0,1]
	v_add3_u32 v13, 0, v13, v32
	v_pk_fma_f32 v[26:27], v[16:17], v[28:29], v[26:27] op_sel:[1,1,0] op_sel_hi:[1,0,1] neg_lo:[0,1,0]
	v_pk_add_f32 v[16:17], v[174:175], v[108:109]
	s_nop 1
	ds_write_b128 v13, v[14:17]
	v_add_u32_e32 v13, 0x1000, v12
	v_ashrrev_i32_e32 v13, 4, v13
	v_lshlrev_b32_e32 v13, 3, v13
	v_xor_b32_e32 v29, 0x80000000, v119
	v_mov_b32_e32 v28, v109
	v_and_b32_e32 v13, -16, v13
	v_pk_add_f32 v[24:25], v[174:175], v[28:29]
	v_add3_u32 v13, 0, v13, v32
	v_pk_mul_f32 v[20:21], v[24:25], v[30:31] op_sel:[0,0] op_sel_hi:[0,1]
	v_pk_mul_f32 v[110:111], v[30:31], v[30:31] op_sel:[0,0] op_sel_hi:[0,1]
	v_add_u32_e32 v39, 2, v12
	v_pk_fma_f32 v[20:21], v[24:25], v[30:31], v[20:21] op_sel:[1,1,0] op_sel_hi:[1,0,1] neg_lo:[0,1,0]
	ds_write_b128 v13, v[18:21] offset:32768
	v_add_u32_e32 v13, 0x2000, v12
	v_ashrrev_i32_e32 v14, 4, v13
	v_lshlrev_b32_e32 v14, 3, v14
	v_pk_fma_f32 v[110:111], v[30:31], v[30:31], v[110:111] op_sel:[1,1,0] op_sel_hi:[1,0,1] neg_lo:[0,1,0]
	v_and_b32_e32 v14, -16, v14
	v_pk_mul_f32 v[116:117], v[110:111], v[30:31] op_sel:[0,0] op_sel_hi:[0,1]
	v_lshlrev_b32_e32 v13, 3, v13
	v_pk_fma_f32 v[116:117], v[110:111], v[30:31], v[116:117] op_sel:[1,1,0] op_sel_hi:[1,0,1] neg_lo:[0,1,0]
	v_pk_add_f32 v[30:31], v[174:175], v[108:109] neg_lo:[0,1] neg_hi:[0,1]
	v_add3_u32 v13, 0, v14, v13
	v_pk_mul_f32 v[24:25], v[30:31], v[110:111] op_sel:[0,0] op_sel_hi:[0,1]
	v_cvt_f32_i32_e32 v14, v39
	v_pk_fma_f32 v[24:25], v[30:31], v[110:111], v[24:25] op_sel:[1,1,0] op_sel_hi:[1,0,1] neg_lo:[0,1,0]
	ds_write_b128 v13, v[22:25]
	v_add_u32_e32 v13, 0x3000, v12
	v_ashrrev_i32_e32 v15, 4, v13
	v_lshlrev_b32_e32 v15, 3, v15
	v_mov_b32_e32 v23, v8
	v_mov_b32_e32 v24, v8
	v_add_u32_e32 v8, 3, v12
	v_and_b32_e32 v15, -16, v15
	v_mul_f32_e32 v14, 0x38800000, v14
	v_lshlrev_b32_e32 v13, 3, v13
	v_cvt_f32_i32_e32 v8, v8
	v_pk_add_f32 v[30:31], v[174:175], v[28:29] neg_lo:[0,1] neg_hi:[0,1]
	v_cos_f32_e32 v16, v14
	v_pk_mul_f32 v[28:29], v[30:31], v[116:117] op_sel:[0,0] op_sel_hi:[0,1]
	v_sin_f32_e64 v17, -v14
	v_add3_u32 v13, 0, v15, v13
	v_pk_fma_f32 v[28:29], v[30:31], v[116:117], v[28:29] op_sel:[1,1,0] op_sel_hi:[1,0,1] neg_lo:[0,1,0]
	ds_write_b128 v13, v[26:29]
	s_nop 1
	v_mov_b32_e32 v20, v172
	v_mov_b32_e32 v21, v170
	v_xor_b32_e32 v25, 0x80000000, v10
	v_pk_mul_f32 v[26:27], v[16:17], v[16:17] op_sel:[0,0] op_sel_hi:[0,1]
	v_mov_b32_e32 v22, v10
	v_pk_fma_f32 v[26:27], v[16:17], v[16:17], v[26:27] op_sel:[1,1,0] op_sel_hi:[1,0,1] neg_lo:[0,1,0]
	v_pk_add_f32 v[30:31], v[20:21], v[24:25]
	v_pk_mul_f32 v[28:29], v[26:27], v[16:17] op_sel:[0,0] op_sel_hi:[0,1]
	v_pk_add_f32 v[14:15], v[20:21], v[22:23]
	v_pk_mul_f32 v[18:19], v[30:31], v[16:17] op_sel:[0,0] op_sel_hi:[0,1]
	v_pk_fma_f32 v[28:29], v[26:27], v[16:17], v[28:29] op_sel:[1,1,0] op_sel_hi:[1,0,1] neg_lo:[0,1,0]
	v_mul_f32_e32 v8, 0x38800000, v8
	v_pk_fma_f32 v[18:19], v[30:31], v[16:17], v[18:19] op_sel:[1,1,0] op_sel_hi:[1,0,1] neg_lo:[0,1,0]
	v_pk_add_f32 v[16:17], v[20:21], v[22:23] neg_lo:[0,1] neg_hi:[0,1]
	v_cos_f32_e32 v30, v8
	v_pk_mul_f32 v[22:23], v[16:17], v[26:27] op_sel:[0,0] op_sel_hi:[0,1]
	v_sin_f32_e64 v31, -v8
	v_pk_fma_f32 v[22:23], v[16:17], v[26:27], v[22:23] op_sel:[1,1,0] op_sel_hi:[1,0,1] neg_lo:[0,1,0]
	v_pk_add_f32 v[16:17], v[20:21], v[24:25] neg_lo:[0,1] neg_hi:[0,1]
	v_mov_b32_e32 v170, v173
	v_pk_mul_f32 v[26:27], v[16:17], v[28:29] op_sel:[0,0] op_sel_hi:[0,1]
	v_mov_b32_e32 v8, v11
	v_xor_b32_e32 v11, 0x80000000, v11
	v_mov_b32_e32 v10, v9
	v_pk_fma_f32 v[26:27], v[16:17], v[28:29], v[26:27] op_sel:[1,1,0] op_sel_hi:[1,0,1] neg_lo:[0,1,0]
	s_nop 1
	v_pk_add_f32 v[24:25], v[170:171], v[10:11]
	v_pk_mul_f32 v[28:29], v[30:31], v[30:31] op_sel:[0,0] op_sel_hi:[0,1]
	v_pk_add_f32 v[16:17], v[170:171], v[8:9]
	v_pk_mul_f32 v[20:21], v[24:25], v[30:31] op_sel:[0,0] op_sel_hi:[0,1]
	v_pk_fma_f32 v[28:29], v[30:31], v[30:31], v[28:29] op_sel:[1,1,0] op_sel_hi:[1,0,1] neg_lo:[0,1,0]
	v_pk_add_f32 v[8:9], v[170:171], v[8:9] neg_lo:[0,1] neg_hi:[0,1]
	v_pk_mul_f32 v[108:109], v[28:29], v[30:31] op_sel:[0,0] op_sel_hi:[0,1]
	v_pk_fma_f32 v[20:21], v[24:25], v[30:31], v[20:21] op_sel:[1,1,0] op_sel_hi:[1,0,1] neg_lo:[0,1,0]
	v_add_u32_e32 v13, 4, v12
	v_pk_mul_f32 v[24:25], v[8:9], v[28:29] op_sel:[0,0] op_sel_hi:[0,1]
; #define LAS __attribute__((address_space(3)))
; template <int R0> __device__ __forceinline__ void r0_fwd_store(LAS cf* X, const int N, int j0, const f32x4 (&ar)[R0 / 2][2], const f32x4 (&ai)[R0 / 2][2]) {
;     constexpr int q = 4096; const float rN = 1.0f / (float)N; asm volatile("" : "+v"(j0));
; #pragma unroll
;     for (int e = 0; e < 8; e += 2) {
;         cf y[R0][2];
; #pragma unroll
;         for (int h = 0; h < 2; ++h) { const int j = j0 + e + h; const cf w1 = twid((float)j * rN, false);
;             if constexpr (R0 == 4) { const cf a0 = cf{VEL(ar[0], e + h), VEL(ai[0], e + h)}, a1 = cf{VEL(ar[1], e + h), VEL(ai[1], e + h)}; const cf m = cf{a1.y, -a1.x};
;                 const cf w2 = cmul(w1, w1), w3 = cmul(w2, w1);
;                 y[0][h] = a0 + a1; y[1][h] = cmul(a0 + m, w1); y[2][h] = cmul(a0 - a1, w2); y[3][h] = cmul(a0 - m, w3); }
;             else { const cf a0 = cf{VEL(ar[0], e + h), VEL(ai[0], e + h)}; y[0][h] = a0; y[1][h] = cmul(a0, w1); } }
; #pragma unroll
;         for (int k = 0; k < R0; ++k) *(LAS f32x4*)(X + fphys(j0 + e + k * q)) = (f32x4){y[k][0].x, y[k][0].y, y[k][1].x, y[k][1].y};
;     }
	v_pk_fma_f32 v[108:109], v[28:29], v[30:31], v[108:109] op_sel:[1,1,0] op_sel_hi:[1,0,1] neg_lo:[0,1,0]
	s_nop 0
	v_pk_fma_f32 v[24:25], v[8:9], v[28:29], v[24:25] op_sel:[1,1,0] op_sel_hi:[1,0,1] neg_lo:[0,1,0]
	v_pk_add_f32 v[8:9], v[170:171], v[10:11] neg_lo:[0,1] neg_hi:[0,1]
	s_nop 0
	v_pk_mul_f32 v[28:29], v[8:9], v[108:109] op_sel:[0,0] op_sel_hi:[0,1]
	s_nop 0
	v_pk_fma_f32 v[28:29], v[8:9], v[108:109], v[28:29] op_sel:[1,1,0] op_sel_hi:[1,0,1] neg_lo:[0,1,0]
	v_ashrrev_i32_e32 v8, 4, v39
	v_lshlrev_b32_e32 v8, 3, v8
	v_and_b32_e32 v8, -16, v8
	v_add3_u32 v8, 0, v8, v32
	ds_write_b128 v8, v[14:17] offset:16
	v_add_u32_e32 v8, 0x1002, v12
	v_ashrrev_i32_e32 v8, 4, v8
	v_lshlrev_b32_e32 v8, 3, v8
	v_and_b32_e32 v8, -16, v8
	v_add3_u32 v8, 0, v8, v32
	ds_write_b128 v8, v[18:21] offset:32784
	v_add_u32_e32 v8, 0x2002, v12
	v_ashrrev_i32_e32 v9, 4, v8
	v_lshlrev_b32_e32 v9, 3, v9
	v_and_b32_e32 v9, -16, v9
	v_lshlrev_b32_e32 v8, 3, v8
	v_add3_u32 v8, 0, v9, v8
	v_cvt_f32_i32_e32 v9, v13
	ds_write_b128 v8, v[22:25]
	v_add_u32_e32 v8, 0x3002, v12
	v_ashrrev_i32_e32 v10, 4, v8
	v_lshlrev_b32_e32 v10, 3, v10
	v_mov_b32_e32 v19, v4
	v_mov_b32_e32 v20, v4
	v_add_u32_e32 v4, 5, v12
	v_and_b32_e32 v14, -16, v10
	v_mul_f32_e32 v9, 0x38800000, v9
	v_lshlrev_b32_e32 v8, 3, v8
	v_cvt_f32_i32_e32 v4, v4
	v_cos_f32_e32 v10, v9
	v_sin_f32_e64 v11, -v9
	v_add3_u32 v8, 0, v14, v8
	ds_write_b128 v8, v[26:29]
	s_nop 1
	v_mov_b32_e32 v16, v168
	v_mov_b32_e32 v17, v166
	v_xor_b32_e32 v21, 0x80000000, v6
	v_pk_mul_f32 v[22:23], v[10:11], v[10:11] op_sel:[0,0] op_sel_hi:[0,1]
	v_mov_b32_e32 v18, v6
	v_pk_fma_f32 v[22:23], v[10:11], v[10:11], v[22:23] op_sel:[1,1,0] op_sel_hi:[1,0,1] neg_lo:[0,1,0]
	v_pk_add_f32 v[26:27], v[16:17], v[20:21]
	v_pk_mul_f32 v[24:25], v[22:23], v[10:11] op_sel:[0,0] op_sel_hi:[0,1]
	v_pk_add_f32 v[8:9], v[16:17], v[18:19]
	v_pk_mul_f32 v[14:15], v[26:27], v[10:11] op_sel:[0,0] op_sel_hi:[0,1]
	v_pk_fma_f32 v[24:25], v[22:23], v[10:11], v[24:25] op_sel:[1,1,0] op_sel_hi:[1,0,1] neg_lo:[0,1,0]
	v_mul_f32_e32 v4, 0x38800000, v4
	v_pk_fma_f32 v[14:15], v[26:27], v[10:11], v[14:15] op_sel:[1,1,0] op_sel_hi:[1,0,1] neg_lo:[0,1,0]
	v_pk_add_f32 v[10:11], v[16:17], v[18:19] neg_lo:[0,1] neg_hi:[0,1]
	v_cos_f32_e32 v26, v4
	v_pk_mul_f32 v[18:19], v[10:11], v[22:23] op_sel:[0,0] op_sel_hi:[0,1]
	v_sin_f32_e64 v27, -v4
	v_pk_fma_f32 v[18:19], v[10:11], v[22:23], v[18:19] op_sel:[1,1,0] op_sel_hi:[1,0,1] neg_lo:[0,1,0]
	v_pk_add_f32 v[10:11], v[16:17], v[20:21] neg_lo:[0,1] neg_hi:[0,1]
	v_mov_b32_e32 v166, v169
	v_pk_mul_f32 v[22:23], v[10:11], v[24:25] op_sel:[0,0] op_sel_hi:[0,1]
	v_mov_b32_e32 v4, v7
	v_xor_b32_e32 v7, 0x80000000, v7
	v_mov_b32_e32 v6, v5
	v_pk_fma_f32 v[22:23], v[10:11], v[24:25], v[22:23] op_sel:[1,1,0] op_sel_hi:[1,0,1] neg_lo:[0,1,0]
	s_nop 1
	v_pk_add_f32 v[20:21], v[166:167], v[6:7]
	v_pk_mul_f32 v[24:25], v[26:27], v[26:27] op_sel:[0,0] op_sel_hi:[0,1]
	v_pk_add_f32 v[10:11], v[166:167], v[4:5]
	v_pk_mul_f32 v[16:17], v[20:21], v[26:27] op_sel:[0,0] op_sel_hi:[0,1]
	v_pk_fma_f32 v[24:25], v[26:27], v[26:27], v[24:25] op_sel:[1,1,0] op_sel_hi:[1,0,1] neg_lo:[0,1,0]
	v_pk_add_f32 v[4:5], v[166:167], v[4:5] neg_lo:[0,1] neg_hi:[0,1]
	v_pk_mul_f32 v[28:29], v[24:25], v[26:27] op_sel:[0,0] op_sel_hi:[0,1]
	v_pk_fma_f32 v[16:17], v[20:21], v[26:27], v[16:17] op_sel:[1,1,0] op_sel_hi:[1,0,1] neg_lo:[0,1,0]
	v_mov_b32_e32 v39, v145
	v_pk_mul_f32 v[20:21], v[4:5], v[24:25] op_sel:[0,0] op_sel_hi:[0,1]
	v_pk_fma_f32 v[28:29], v[24:25], v[26:27], v[28:29] op_sel:[1,1,0] op_sel_hi:[1,0,1] neg_lo:[0,1,0]
	s_nop 0
	v_pk_fma_f32 v[20:21], v[4:5], v[24:25], v[20:21] op_sel:[1,1,0] op_sel_hi:[1,0,1] neg_lo:[0,1,0]
	v_pk_add_f32 v[4:5], v[166:167], v[6:7] neg_lo:[0,1] neg_hi:[0,1]
	s_nop 0
	v_pk_mul_f32 v[24:25], v[4:5], v[28:29] op_sel:[0,0] op_sel_hi:[0,1]
	s_nop 0
	v_pk_fma_f32 v[24:25], v[4:5], v[28:29], v[24:25] op_sel:[1,1,0] op_sel_hi:[1,0,1] neg_lo:[0,1,0]
	v_ashrrev_i32_e32 v4, 4, v13
	v_lshlrev_b32_e32 v4, 3, v4
	v_and_b32_e32 v4, -16, v4
	v_add3_u32 v4, 0, v4, v32
	ds_write_b128 v4, v[8:11] offset:32
	v_add_u32_e32 v4, 0x1004, v12
	v_ashrrev_i32_e32 v4, 4, v4
	v_lshlrev_b32_e32 v4, 3, v4
; #define LAS __attribute__((address_space(3)))
; template <int R0> __device__ __forceinline__ void r0_fwd_store(LAS cf* X, const int N, int j0, const f32x4 (&ar)[R0 / 2][2], const f32x4 (&ai)[R0 / 2][2]) {
;     constexpr int q = 4096; const float rN = 1.0f / (float)N; asm volatile("" : "+v"(j0));
; #pragma unroll
;     for (int e = 0; e < 8; e += 2) {
;         cf y[R0][2];
; #pragma unroll
;         for (int h = 0; h < 2; ++h) { const int j = j0 + e + h; const cf w1 = twid((float)j * rN, false);
;             if constexpr (R0 == 4) { const cf a0 = cf{VEL(ar[0], e + h), VEL(ai[0], e + h)}, a1 = cf{VEL(ar[1], e + h), VEL(ai[1], e + h)}; const cf m = cf{a1.y, -a1.x};
;                 const cf w2 = cmul(w1, w1), w3 = cmul(w2, w1);
;                 y[0][h] = a0 + a1; y[1][h] = cmul(a0 + m, w1); y[2][h] = cmul(a0 - a1, w2); y[3][h] = cmul(a0 - m, w3); }
;             else { const cf a0 = cf{VEL(ar[0], e + h), VEL(ai[0], e + h)}; y[0][h] = a0; y[1][h] = cmul(a0, w1); } }
; #pragma unroll
;         for (int k = 0; k < R0; ++k) *(LAS f32x4*)(X + fphys(j0 + e + k * q)) = (f32x4){y[k][0].x, y[k][0].y, y[k][1].x, y[k][1].y};
;     }
; }
; __device__ __forceinline__ void fft_mid_chain(LAS cf* X, const int N, const f32x4* Kst, const float sc) {
;     __syncthreads();
;     stage16<4096, false>(X, N); __syncthreads();
	v_and_b32_e32 v4, -16, v4
	v_add3_u32 v4, 0, v4, v32
	ds_write_b128 v4, v[14:17] offset:32800
	v_add_u32_e32 v4, 0x2004, v12
	v_ashrrev_i32_e32 v5, 4, v4
	v_lshlrev_b32_e32 v5, 3, v5
	v_and_b32_e32 v5, -16, v5
	v_lshlrev_b32_e32 v4, 3, v4
	v_add_u32_e32 v13, 6, v12
	v_add3_u32 v4, 0, v5, v4
	v_cvt_f32_i32_e32 v5, v13
	ds_write_b128 v4, v[18:21]
	v_add_u32_e32 v4, 0x3004, v12
	v_ashrrev_i32_e32 v6, 4, v4
	v_lshlrev_b32_e32 v6, 3, v6
	v_mov_b32_e32 v15, v0
	v_mov_b32_e32 v16, v0
	v_add_u32_e32 v0, 7, v12
	v_and_b32_e32 v8, -16, v6
	v_mul_f32_e32 v5, 0x38800000, v5
	v_lshlrev_b32_e32 v4, 3, v4
	v_cvt_f32_i32_e32 v0, v0
	v_cos_f32_e32 v6, v5
	v_sin_f32_e64 v7, -v5
	v_add3_u32 v4, 0, v8, v4
	ds_write_b128 v4, v[22:25]
	s_nop 1
	v_mov_b32_e32 v10, v114
	v_mov_b32_e32 v11, v112
	v_xor_b32_e32 v17, 0x80000000, v2
	v_pk_mul_f32 v[18:19], v[6:7], v[6:7] op_sel:[0,0] op_sel_hi:[0,1]
	v_mov_b32_e32 v14, v2
	v_pk_fma_f32 v[18:19], v[6:7], v[6:7], v[18:19] op_sel:[1,1,0] op_sel_hi:[1,0,1] neg_lo:[0,1,0]
	v_pk_add_f32 v[22:23], v[10:11], v[16:17]
	v_pk_mul_f32 v[20:21], v[18:19], v[6:7] op_sel:[0,0] op_sel_hi:[0,1]
	v_pk_add_f32 v[4:5], v[10:11], v[14:15]
	v_pk_mul_f32 v[8:9], v[22:23], v[6:7] op_sel:[0,0] op_sel_hi:[0,1]
	v_pk_fma_f32 v[20:21], v[18:19], v[6:7], v[20:21] op_sel:[1,1,0] op_sel_hi:[1,0,1] neg_lo:[0,1,0]
	v_mul_f32_e32 v0, 0x38800000, v0
	v_pk_fma_f32 v[8:9], v[22:23], v[6:7], v[8:9] op_sel:[1,1,0] op_sel_hi:[1,0,1] neg_lo:[0,1,0]
	v_pk_add_f32 v[6:7], v[10:11], v[14:15] neg_lo:[0,1] neg_hi:[0,1]
	v_cos_f32_e32 v22, v0
	v_pk_mul_f32 v[14:15], v[6:7], v[18:19] op_sel:[0,0] op_sel_hi:[0,1]
	v_sin_f32_e64 v23, -v0
	v_pk_fma_f32 v[14:15], v[6:7], v[18:19], v[14:15] op_sel:[1,1,0] op_sel_hi:[1,0,1] neg_lo:[0,1,0]
	v_pk_add_f32 v[6:7], v[10:11], v[16:17] neg_lo:[0,1] neg_hi:[0,1]
	v_mov_b32_e32 v112, v115
	v_pk_mul_f32 v[18:19], v[6:7], v[20:21] op_sel:[0,0] op_sel_hi:[0,1]
	v_mov_b32_e32 v0, v3
	v_xor_b32_e32 v3, 0x80000000, v3
	v_mov_b32_e32 v2, v1
	v_pk_fma_f32 v[18:19], v[6:7], v[20:21], v[18:19] op_sel:[1,1,0] op_sel_hi:[1,0,1] neg_lo:[0,1,0]
	s_nop 1
	v_pk_add_f32 v[16:17], v[112:113], v[2:3]
	v_pk_mul_f32 v[20:21], v[22:23], v[22:23] op_sel:[0,0] op_sel_hi:[0,1]
	v_pk_add_f32 v[6:7], v[112:113], v[0:1]
	v_pk_mul_f32 v[10:11], v[16:17], v[22:23] op_sel:[0,0] op_sel_hi:[0,1]
	v_pk_fma_f32 v[20:21], v[22:23], v[22:23], v[20:21] op_sel:[1,1,0] op_sel_hi:[1,0,1] neg_lo:[0,1,0]
	v_pk_add_f32 v[0:1], v[112:113], v[0:1] neg_lo:[0,1] neg_hi:[0,1]
	v_pk_mul_f32 v[24:25], v[20:21], v[22:23] op_sel:[0,0] op_sel_hi:[0,1]
	v_pk_fma_f32 v[10:11], v[16:17], v[22:23], v[10:11] op_sel:[1,1,0] op_sel_hi:[1,0,1] neg_lo:[0,1,0]
	s_nop 0
	v_pk_mul_f32 v[16:17], v[0:1], v[20:21] op_sel:[0,0] op_sel_hi:[0,1]
	v_pk_fma_f32 v[24:25], v[20:21], v[22:23], v[24:25] op_sel:[1,1,0] op_sel_hi:[1,0,1] neg_lo:[0,1,0]
	s_nop 0
	v_pk_fma_f32 v[16:17], v[0:1], v[20:21], v[16:17] op_sel:[1,1,0] op_sel_hi:[1,0,1] neg_lo:[0,1,0]
	v_pk_add_f32 v[0:1], v[112:113], v[2:3] neg_lo:[0,1] neg_hi:[0,1]
	s_nop 0
	v_pk_mul_f32 v[20:21], v[0:1], v[24:25] op_sel:[0,0] op_sel_hi:[0,1]
	s_nop 0
	v_pk_fma_f32 v[20:21], v[0:1], v[24:25], v[20:21] op_sel:[1,1,0] op_sel_hi:[1,0,1] neg_lo:[0,1,0]
	v_ashrrev_i32_e32 v0, 4, v13
	v_lshlrev_b32_e32 v0, 3, v0
	v_and_b32_e32 v0, -16, v0
	v_add3_u32 v0, 0, v0, v32
	ds_write_b128 v0, v[4:7] offset:48
	v_add_u32_e32 v0, 0x1006, v12
	v_ashrrev_i32_e32 v0, 4, v0
	v_lshlrev_b32_e32 v0, 3, v0
	v_and_b32_e32 v0, -16, v0
	v_add3_u32 v0, 0, v0, v32
	ds_write_b128 v0, v[8:11] offset:32816
	v_add_u32_e32 v0, 0x2006, v12
	v_ashrrev_i32_e32 v1, 4, v0
	v_lshlrev_b32_e32 v1, 3, v1
	v_and_b32_e32 v1, -16, v1
	v_lshlrev_b32_e32 v0, 3, v0
	v_add3_u32 v0, 0, v1, v0
	ds_write_b128 v0, v[14:17]
	v_add_u32_e32 v0, 0x3006, v12
	v_ashrrev_i32_e32 v1, 4, v0
	v_lshlrev_b32_e32 v1, 3, v1
	v_and_b32_e32 v1, -16, v1
	v_lshlrev_b32_e32 v0, 3, v0
	v_add3_u32 v0, 0, v1, v0
	ds_write_b128 v0, v[18:21]
	s_waitcnt lgkmcnt(0)
	s_barrier
	s_nop 0
	v_cmp_gt_i32_e64 s[12:13], s97, v39
	s_and_saveexec_b64 s[80:81], s[12:13]
	s_xor_b64 s[80:81], exec, s[80:81]
	s_cbranch_execz .LBB0_480
	v_lshl_add_u32 v32, v39, 3, 0
	s_mov_b64 s[82:83], 0

; #define LAS __attribute__((address_space(3)))
; template <int R0> __device__ __forceinline__ void r0_inv_load(const LAS cf* X, const int N, int j0, f32x4 (&yr)[R0 / 2][2], f32x4 (&yi)[R0 / 2][2]) {
;     constexpr int q = 4096; const float rN = 1.0f / (float)N; asm volatile("" : "+v"(j0));
; #pragma unroll
;     for (int e = 0; e < 8; e += 2) {
;         f32x4 v[R0];
; #pragma unroll
;         for (int k = 0; k < R0; ++k) v[k] = *(const LAS f32x4*)(X + fphys(j0 + e + k * q));
; #pragma unroll
;         for (int h = 0; h < 2; ++h) { const int j = j0 + e + h; const cf w1 = twid((float)j * rN, true);
;             if constexpr (R0 == 4) { const cf w2 = cmul(w1, w1), w3 = cmul(w2, w1);
;                 const cf a0 = h ? cf{v[0].z, v[0].w} : cf{v[0].x, v[0].y}; const cf a1 = cmul(h ? cf{v[1].z, v[1].w} : cf{v[1].x, v[1].y}, w1);
;                 const cf a2 = cmul(h ? cf{v[2].z, v[2].w} : cf{v[2].x, v[2].y}, w2); const cf a3 = cmul(h ? cf{v[3].z, v[3].w} : cf{v[3].x, v[3].y}, w3);
;                 const cf t0 = a0 + a2, t1 = a0 - a2, t2 = a1 + a3, t3 = a1 - a3;
;                 VEL(yr[0], e + h) = t0.x + t2.x; VEL(yi[0], e + h) = t0.y + t2.y; VEL(yr[1], e + h) = t1.x - t3.y; VEL(yi[1], e + h) = t1.y + t3.x; }
.LBB0_492:
	s_or_b64 exec, exec, s[80:81]
	v_mov_b32_e32 v16, v209
	s_waitcnt lgkmcnt(0)
	s_barrier
	s_add_i32 s94, s94, s89
	v_cvt_f32_i32_e32 v18, v16
	v_add_u32_e32 v4, 0x1000, v16
	v_add_u32_e32 v8, 0x2000, v16
	v_add_u32_e32 v12, 0x3000, v16
	v_ashrrev_i32_e32 v0, 4, v16
	v_ashrrev_i32_e32 v4, 4, v4
	v_ashrrev_i32_e32 v9, 4, v8
	v_ashrrev_i32_e32 v13, 4, v12
	v_lshlrev_b32_e32 v0, 3, v0
	v_lshlrev_b32_e32 v4, 3, v4
	v_lshlrev_b32_e32 v9, 3, v9
	v_lshlrev_b32_e32 v13, 3, v13
	v_and_b32_e32 v0, -16, v0
	v_lshlrev_b32_e32 v17, 3, v16
	v_and_b32_e32 v4, -16, v4
	v_and_b32_e32 v9, -16, v9
	v_lshlrev_b32_e32 v8, 3, v8
	v_and_b32_e32 v13, -16, v13
	v_lshlrev_b32_e32 v12, 3, v12
	v_mul_f32_e32 v19, 0x38800000, v18
	v_add3_u32 v0, 0, v0, v17
	v_add3_u32 v4, 0, v4, v17
	v_add3_u32 v8, 0, v9, v8
	v_add3_u32 v12, 0, v13, v12
	v_cos_f32_e32 v18, v19
	v_sin_f32_e32 v19, v19
	ds_read_b128 v[0:3], v0
	ds_read_b128 v[4:7], v4 offset:32768
	ds_read_b128 v[8:11], v8
	ds_read_b128 v[12:15], v12
	s_nop 1
	v_add_u32_e32 v32, s94, v209
	s_waitcnt lgkmcnt(2)
	v_pk_mul_f32 v[28:29], v[4:5], v[18:19] op_sel:[0,0] op_sel_hi:[0,1]
	v_pk_mul_f32 v[20:21], v[18:19], v[18:19] op_sel:[0,0] op_sel_hi:[0,1]
	v_mov_b32_e32 v157, 0
	v_pk_fma_f32 v[28:29], v[4:5], v[18:19], v[28:29] op_sel:[1,1,0] op_sel_hi:[1,0,1] neg_lo:[0,1,0]
	v_add_u32_e32 v4, 1, v16
	v_cvt_f32_i32_e32 v4, v4
	v_pk_fma_f32 v[20:21], v[18:19], v[18:19], v[20:21] op_sel:[1,1,0] op_sel_hi:[1,0,1] neg_lo:[0,1,0]
	v_mul_f32_e32 v5, 0x38800000, v4
	v_pk_mul_f32 v[22:23], v[20:21], v[18:19] op_sel:[0,0] op_sel_hi:[0,1]
	s_waitcnt lgkmcnt(1)
	v_pk_mul_f32 v[30:31], v[8:9], v[20:21] op_sel:[0,0] op_sel_hi:[0,1]
	v_cos_f32_e32 v4, v5
	v_sin_f32_e32 v5, v5
	v_pk_fma_f32 v[22:23], v[20:21], v[18:19], v[22:23] op_sel:[1,1,0] op_sel_hi:[1,0,1] neg_lo:[0,1,0]
	v_pk_fma_f32 v[30:31], v[8:9], v[20:21], v[30:31] op_sel:[1,1,0] op_sel_hi:[1,0,1] neg_lo:[0,1,0]
	s_nop 1
	v_add_u32_e32 v18, 0x3002, v16
	s_waitcnt lgkmcnt(0)
	v_pk_mul_f32 v[108:109], v[12:13], v[22:23] op_sel:[0,0] op_sel_hi:[0,1]
	v_pk_mul_f32 v[8:9], v[4:5], v[4:5] op_sel:[0,0] op_sel_hi:[0,1]
	v_pk_mul_f32 v[110:111], v[6:7], v[4:5] op_sel:[0,0] op_sel_hi:[0,1]
	v_ashrrev_i32_e32 v19, 4, v18
	v_pk_fma_f32 v[108:109], v[12:13], v[22:23], v[108:109] op_sel:[1,1,0] op_sel_hi:[1,0,1] neg_lo:[0,1,0]
	v_pk_fma_f32 v[8:9], v[4:5], v[4:5], v[8:9] op_sel:[1,1,0] op_sel_hi:[1,0,1] neg_lo:[0,1,0]
	v_add_u32_e32 v22, 2, v16
	v_pk_mul_f32 v[12:13], v[8:9], v[4:5] op_sel:[0,0] op_sel_hi:[0,1]
	v_pk_fma_f32 v[110:111], v[6:7], v[4:5], v[110:111] op_sel:[1,1,0] op_sel_hi:[1,0,1] neg_lo:[0,1,0]
	v_pk_mul_f32 v[112:113], v[10:11], v[8:9] op_sel:[0,0] op_sel_hi:[0,1]
	v_lshlrev_b32_e32 v19, 3, v19
	v_pk_fma_f32 v[12:13], v[8:9], v[4:5], v[12:13] op_sel:[1,1,0] op_sel_hi:[1,0,1] neg_lo:[0,1,0]
	v_ashrrev_i32_e32 v4, 4, v22
	v_pk_mul_f32 v[114:115], v[14:15], v[12:13] op_sel:[0,0] op_sel_hi:[0,1]
	v_cvt_f32_i32_e32 v22, v22
	v_pk_fma_f32 v[112:113], v[10:11], v[8:9], v[112:113] op_sel:[1,1,0] op_sel_hi:[1,0,1] neg_lo:[0,1,0]
	v_pk_fma_f32 v[114:115], v[14:15], v[12:13], v[114:115] op_sel:[1,1,0] op_sel_hi:[1,0,1] neg_lo:[0,1,0]
	v_add_u32_e32 v8, 0x1002, v16
	v_add_u32_e32 v12, 0x2002, v16
	v_ashrrev_i32_e32 v8, 4, v8
	v_ashrrev_i32_e32 v13, 4, v12
	v_lshlrev_b32_e32 v4, 3, v4
	v_lshlrev_b32_e32 v8, 3, v8
	v_lshlrev_b32_e32 v13, 3, v13
	v_and_b32_e32 v4, -16, v4
	v_and_b32_e32 v8, -16, v8
	v_and_b32_e32 v13, -16, v13
	v_lshlrev_b32_e32 v12, 3, v12
	v_and_b32_e32 v19, -16, v19
	v_lshlrev_b32_e32 v18, 3, v18
	v_mul_f32_e32 v23, 0x38800000, v22
	v_add3_u32 v4, 0, v4, v17
	v_add3_u32 v8, 0, v8, v17
	v_add3_u32 v12, 0, v13, v12
	v_add3_u32 v18, 0, v19, v18
	v_cos_f32_e32 v22, v23
	v_sin_f32_e32 v23, v23
	ds_read_b128 v[4:7], v4 offset:16
	ds_read_b128 v[8:11], v8 offset:32784
	ds_read_b128 v[12:15], v12
	ds_read_b128 v[18:21], v18
	s_nop 1
	s_waitcnt lgkmcnt(2)
	v_pk_mul_f32 v[116:117], v[8:9], v[22:23] op_sel:[0,0] op_sel_hi:[0,1]
	v_pk_mul_f32 v[24:25], v[22:23], v[22:23] op_sel:[0,0] op_sel_hi:[0,1]
	s_nop 0
	v_pk_fma_f32 v[116:117], v[8:9], v[22:23], v[116:117] op_sel:[1,1,0] op_sel_hi:[1,0,1] neg_lo:[0,1,0]
	v_add_u32_e32 v8, 3, v16
	v_cvt_f32_i32_e32 v8, v8
	v_pk_fma_f32 v[24:25], v[22:23], v[22:23], v[24:25] op_sel:[1,1,0] op_sel_hi:[1,0,1] neg_lo:[0,1,0]
	v_mul_f32_e32 v9, 0x38800000, v8
	v_pk_mul_f32 v[26:27], v[24:25], v[22:23] op_sel:[0,0] op_sel_hi:[0,1]
	s_waitcnt lgkmcnt(1)
	v_pk_mul_f32 v[118:119], v[12:13], v[24:25] op_sel:[0,0] op_sel_hi:[0,1]
	v_cos_f32_e32 v8, v9
	v_sin_f32_e32 v9, v9
	v_pk_fma_f32 v[26:27], v[24:25], v[22:23], v[26:27] op_sel:[1,1,0] op_sel_hi:[1,0,1] neg_lo:[0,1,0]
	v_pk_fma_f32 v[118:119], v[12:13], v[24:25], v[118:119] op_sel:[1,1,0] op_sel_hi:[1,0,1] neg_lo:[0,1,0]
	s_nop 1
	v_add_u32_e32 v22, 0x3004, v16
	s_waitcnt lgkmcnt(0)
; #define LAS __attribute__((address_space(3)))
; template <int R0> __device__ __forceinline__ void r0_inv_load(const LAS cf* X, const int N, int j0, f32x4 (&yr)[R0 / 2][2], f32x4 (&yi)[R0 / 2][2]) {
;     constexpr int q = 4096; const float rN = 1.0f / (float)N; asm volatile("" : "+v"(j0));
; #pragma unroll
;     for (int e = 0; e < 8; e += 2) {
;         f32x4 v[R0];
; #pragma unroll
;         for (int k = 0; k < R0; ++k) v[k] = *(const LAS f32x4*)(X + fphys(j0 + e + k * q));
; #pragma unroll
;         for (int h = 0; h < 2; ++h) { const int j = j0 + e + h; const cf w1 = twid((float)j * rN, true);
;             if constexpr (R0 == 4) { const cf w2 = cmul(w1, w1), w3 = cmul(w2, w1);
;                 const cf a0 = h ? cf{v[0].z, v[0].w} : cf{v[0].x, v[0].y}; const cf a1 = cmul(h ? cf{v[1].z, v[1].w} : cf{v[1].x, v[1].y}, w1);
;                 const cf a2 = cmul(h ? cf{v[2].z, v[2].w} : cf{v[2].x, v[2].y}, w2); const cf a3 = cmul(h ? cf{v[3].z, v[3].w} : cf{v[3].x, v[3].y}, w3);
;                 const cf t0 = a0 + a2, t1 = a0 - a2, t2 = a1 + a3, t3 = a1 - a3;
;                 VEL(yr[0], e + h) = t0.x + t2.x; VEL(yi[0], e + h) = t0.y + t2.y; VEL(yr[1], e + h) = t1.x - t3.y; VEL(yi[1], e + h) = t1.y + t3.x; }
	v_pk_mul_f32 v[120:121], v[18:19], v[26:27] op_sel:[0,0] op_sel_hi:[0,1]
	v_pk_mul_f32 v[12:13], v[8:9], v[8:9] op_sel:[0,0] op_sel_hi:[0,1]
	v_pk_mul_f32 v[122:123], v[10:11], v[8:9] op_sel:[0,0] op_sel_hi:[0,1]
	v_ashrrev_i32_e32 v23, 4, v22
	v_pk_fma_f32 v[120:121], v[18:19], v[26:27], v[120:121] op_sel:[1,1,0] op_sel_hi:[1,0,1] neg_lo:[0,1,0]
	v_pk_fma_f32 v[12:13], v[8:9], v[8:9], v[12:13] op_sel:[1,1,0] op_sel_hi:[1,0,1] neg_lo:[0,1,0]
	v_add_u32_e32 v26, 4, v16
	v_pk_mul_f32 v[18:19], v[12:13], v[8:9] op_sel:[0,0] op_sel_hi:[0,1]
	v_pk_fma_f32 v[122:123], v[10:11], v[8:9], v[122:123] op_sel:[1,1,0] op_sel_hi:[1,0,1] neg_lo:[0,1,0]
	v_pk_mul_f32 v[124:125], v[14:15], v[12:13] op_sel:[0,0] op_sel_hi:[0,1]
	v_lshlrev_b32_e32 v23, 3, v23
	v_pk_fma_f32 v[18:19], v[12:13], v[8:9], v[18:19] op_sel:[1,1,0] op_sel_hi:[1,0,1] neg_lo:[0,1,0]
	v_ashrrev_i32_e32 v8, 4, v26
	v_pk_mul_f32 v[126:127], v[20:21], v[18:19] op_sel:[0,0] op_sel_hi:[0,1]
	v_cvt_f32_i32_e32 v26, v26
	v_pk_fma_f32 v[124:125], v[14:15], v[12:13], v[124:125] op_sel:[1,1,0] op_sel_hi:[1,0,1] neg_lo:[0,1,0]
	v_pk_fma_f32 v[126:127], v[20:21], v[18:19], v[126:127] op_sel:[1,1,0] op_sel_hi:[1,0,1] neg_lo:[0,1,0]
	v_add_u32_e32 v12, 0x1004, v16
	v_add_u32_e32 v18, 0x2004, v16
	v_ashrrev_i32_e32 v12, 4, v12
	v_ashrrev_i32_e32 v19, 4, v18
	v_lshlrev_b32_e32 v8, 3, v8
	v_lshlrev_b32_e32 v12, 3, v12
	v_lshlrev_b32_e32 v19, 3, v19
	v_and_b32_e32 v8, -16, v8
	v_and_b32_e32 v12, -16, v12
	v_and_b32_e32 v19, -16, v19
	v_lshlrev_b32_e32 v18, 3, v18
	v_and_b32_e32 v23, -16, v23
	v_lshlrev_b32_e32 v22, 3, v22
	v_mul_f32_e32 v27, 0x38800000, v26
	v_add3_u32 v8, 0, v8, v17
	v_add3_u32 v12, 0, v12, v17
	v_add3_u32 v18, 0, v19, v18
	v_add3_u32 v22, 0, v23, v22
	v_cos_f32_e32 v26, v27
	v_sin_f32_e32 v27, v27
	ds_read_b128 v[8:11], v8 offset:32
	ds_read_b128 v[12:15], v12 offset:32800
	ds_read_b128 v[18:21], v18
	ds_read_b128 v[22:25], v22
	s_nop 1
	s_waitcnt lgkmcnt(2)
	v_pk_mul_f32 v[128:129], v[12:13], v[26:27] op_sel:[0,0] op_sel_hi:[0,1]
	v_pk_mul_f32 v[132:133], v[26:27], v[26:27] op_sel:[0,0] op_sel_hi:[0,1]
	s_nop 0
	v_pk_fma_f32 v[128:129], v[12:13], v[26:27], v[128:129] op_sel:[1,1,0] op_sel_hi:[1,0,1] neg_lo:[0,1,0]
	v_add_u32_e32 v12, 5, v16
	v_cvt_f32_i32_e32 v12, v12
	v_pk_fma_f32 v[132:133], v[26:27], v[26:27], v[132:133] op_sel:[1,1,0] op_sel_hi:[1,0,1] neg_lo:[0,1,0]
	v_mul_f32_e32 v13, 0x38800000, v12
	v_pk_mul_f32 v[134:135], v[132:133], v[26:27] op_sel:[0,0] op_sel_hi:[0,1]
	s_waitcnt lgkmcnt(1)
	v_pk_mul_f32 v[130:131], v[18:19], v[132:133] op_sel:[0,0] op_sel_hi:[0,1]
	v_cos_f32_e32 v12, v13
	v_sin_f32_e32 v13, v13
	v_pk_fma_f32 v[134:135], v[132:133], v[26:27], v[134:135] op_sel:[1,1,0] op_sel_hi:[1,0,1] neg_lo:[0,1,0]
	v_pk_fma_f32 v[130:131], v[18:19], v[132:133], v[130:131] op_sel:[1,1,0] op_sel_hi:[1,0,1] neg_lo:[0,1,0]
	s_nop 1
	v_add_u32_e32 v26, 6, v16
	s_waitcnt lgkmcnt(0)
; #define LAS __attribute__((address_space(3)))
; template <int R0> __device__ __forceinline__ void r0_inv_load(const LAS cf* X, const int N, int j0, f32x4 (&yr)[R0 / 2][2], f32x4 (&yi)[R0 / 2][2]) {
;     constexpr int q = 4096; const float rN = 1.0f / (float)N; asm volatile("" : "+v"(j0));
; #pragma unroll
;     for (int e = 0; e < 8; e += 2) {
;         f32x4 v[R0];
; #pragma unroll
;         for (int k = 0; k < R0; ++k) v[k] = *(const LAS f32x4*)(X + fphys(j0 + e + k * q));
; #pragma unroll
;         for (int h = 0; h < 2; ++h) { const int j = j0 + e + h; const cf w1 = twid((float)j * rN, true);
;             if constexpr (R0 == 4) { const cf w2 = cmul(w1, w1), w3 = cmul(w2, w1);
;                 const cf a0 = h ? cf{v[0].z, v[0].w} : cf{v[0].x, v[0].y}; const cf a1 = cmul(h ? cf{v[1].z, v[1].w} : cf{v[1].x, v[1].y}, w1);
;                 const cf a2 = cmul(h ? cf{v[2].z, v[2].w} : cf{v[2].x, v[2].y}, w2); const cf a3 = cmul(h ? cf{v[3].z, v[3].w} : cf{v[3].x, v[3].y}, w3);
;                 const cf t0 = a0 + a2, t1 = a0 - a2, t2 = a1 + a3, t3 = a1 - a3;
;                 VEL(yr[0], e + h) = t0.x + t2.x; VEL(yi[0], e + h) = t0.y + t2.y; VEL(yr[1], e + h) = t1.x - t3.y; VEL(yi[1], e + h) = t1.y + t3.x; }
; template <int R0> __device__ __forceinline__ void hy_pair(LAS cf* X, const int N, const int L, const int tid, const unsigned mA, const unsigned mB, const bf16_t* hyT, bf16_t* hyo, ...
;     ...
;         for (int n = 0; n < NL; ++n) { const int t0 = j0 + n * 4096; f32x4 xa[2], xb[2];
;             conv8(hyT, ob + mA, t0, L, wb0, wb1, wb2, bb, xa); conv8(hyT, ob + mB, t0, L, wb0, wb1, wb2, bb, xb);
	v_pk_mul_f32 v[132:133], v[22:23], v[134:135] op_sel:[0,0] op_sel_hi:[0,1]
	v_pk_mul_f32 v[18:19], v[12:13], v[12:13] op_sel:[0,0] op_sel_hi:[0,1]
	s_nop 0
	v_pk_fma_f32 v[132:133], v[22:23], v[134:135], v[132:133] op_sel:[1,1,0] op_sel_hi:[1,0,1] neg_lo:[0,1,0]
	v_pk_fma_f32 v[18:19], v[12:13], v[12:13], v[18:19] op_sel:[1,1,0] op_sel_hi:[1,0,1] neg_lo:[0,1,0]
	v_pk_mul_f32 v[134:135], v[14:15], v[12:13] op_sel:[0,0] op_sel_hi:[0,1]
	s_nop 0
	v_pk_mul_f32 v[22:23], v[18:19], v[12:13] op_sel:[0,0] op_sel_hi:[0,1]
	v_pk_mul_f32 v[136:137], v[20:21], v[18:19] op_sel:[0,0] op_sel_hi:[0,1]
	v_pk_fma_f32 v[134:135], v[14:15], v[12:13], v[134:135] op_sel:[1,1,0] op_sel_hi:[1,0,1] neg_lo:[0,1,0]
	s_nop 0
	v_pk_fma_f32 v[22:23], v[18:19], v[12:13], v[22:23] op_sel:[1,1,0] op_sel_hi:[1,0,1] neg_lo:[0,1,0]
	v_pk_fma_f32 v[136:137], v[20:21], v[18:19], v[136:137] op_sel:[1,1,0] op_sel_hi:[1,0,1] neg_lo:[0,1,0]
	v_add_u32_e32 v18, 0x1006, v16
	v_ashrrev_i32_e32 v12, 4, v26
	v_ashrrev_i32_e32 v18, 4, v18
	v_lshlrev_b32_e32 v12, 3, v12
	v_lshlrev_b32_e32 v18, 3, v18
	v_and_b32_e32 v12, -16, v12
	v_and_b32_e32 v18, -16, v18
	v_add3_u32 v12, 0, v12, v17
	v_add3_u32 v17, 0, v18, v17
	v_pk_mul_f32 v[138:139], v[24:25], v[22:23] op_sel:[0,0] op_sel_hi:[0,1]
	ds_read_b128 v[12:15], v12 offset:48
	ds_read_b128 v[18:21], v17 offset:32816
	v_add_u32_e32 v17, 0x2006, v16
	v_pk_fma_f32 v[138:139], v[24:25], v[22:23], v[138:139] op_sel:[1,1,0] op_sel_hi:[1,0,1] neg_lo:[0,1,0]
	v_ashrrev_i32_e32 v22, 4, v17
	v_lshlrev_b32_e32 v22, 3, v22
	v_and_b32_e32 v22, -16, v22
	v_lshlrev_b32_e32 v17, 3, v17
	v_add3_u32 v17, 0, v22, v17
	ds_read_b128 v[22:25], v17
	v_add_u32_e32 v17, 0x3006, v16
	v_ashrrev_i32_e32 v27, 4, v17
	v_lshlrev_b32_e32 v27, 3, v27
	v_and_b32_e32 v27, -16, v27
	v_lshlrev_b32_e32 v17, 3, v17
	v_add3_u32 v17, 0, v27, v17
	ds_read_b128 v[152:155], v17
	v_cvt_f32_i32_e32 v17, v26
	v_add_u32_e32 v16, 7, v16
	v_cvt_f32_i32_e32 v16, v16
	v_mul_f32_e32 v17, 0x38800000, v17
	v_cos_f32_e32 v26, v17
	v_sin_f32_e32 v27, v17
	s_nop 1
	v_mul_f32_e32 v17, 0x38800000, v16
	v_pk_mul_f32 v[146:147], v[26:27], v[26:27] op_sel:[0,0] op_sel_hi:[0,1]
	s_waitcnt lgkmcnt(2)
	v_pk_mul_f32 v[140:141], v[18:19], v[26:27] op_sel:[0,0] op_sel_hi:[0,1]
	v_cos_f32_e32 v16, v17
	v_pk_fma_f32 v[146:147], v[26:27], v[26:27], v[146:147] op_sel:[1,1,0] op_sel_hi:[1,0,1] neg_lo:[0,1,0]
	v_sin_f32_e32 v17, v17
	v_pk_mul_f32 v[148:149], v[146:147], v[26:27] op_sel:[0,0] op_sel_hi:[0,1]
	s_waitcnt lgkmcnt(1)
	v_pk_mul_f32 v[142:143], v[22:23], v[146:147] op_sel:[0,0] op_sel_hi:[0,1]
	v_pk_fma_f32 v[140:141], v[18:19], v[26:27], v[140:141] op_sel:[1,1,0] op_sel_hi:[1,0,1] neg_lo:[0,1,0]
	s_nop 1
	v_pk_fma_f32 v[148:149], v[146:147], v[26:27], v[148:149] op_sel:[1,1,0] op_sel_hi:[1,0,1] neg_lo:[0,1,0]
	s_nop 0
	v_pk_fma_f32 v[142:143], v[22:23], v[146:147], v[142:143] op_sel:[1,1,0] op_sel_hi:[1,0,1] neg_lo:[0,1,0]
	v_pk_mul_f32 v[18:19], v[16:17], v[16:17] op_sel:[0,0] op_sel_hi:[0,1]
	v_mov_b32_e32 v26, 0
	s_waitcnt lgkmcnt(0)
	v_pk_mul_f32 v[146:147], v[152:153], v[148:149] op_sel:[0,0] op_sel_hi:[0,1]
	v_pk_fma_f32 v[18:19], v[16:17], v[16:17], v[18:19] op_sel:[1,1,0] op_sel_hi:[1,0,1] neg_lo:[0,1,0]
	s_nop 0
	v_pk_fma_f32 v[146:147], v[152:153], v[148:149], v[146:147] op_sel:[1,1,0] op_sel_hi:[1,0,1] neg_lo:[0,1,0]
	v_pk_mul_f32 v[22:23], v[18:19], v[16:17] op_sel:[0,0] op_sel_hi:[0,1]
	v_pk_mul_f32 v[148:149], v[20:21], v[16:17] op_sel:[0,0] op_sel_hi:[0,1]
	v_pk_mul_f32 v[150:151], v[24:25], v[18:19] op_sel:[0,0] op_sel_hi:[0,1]
	s_nop 0
	v_pk_fma_f32 v[22:23], v[18:19], v[16:17], v[22:23] op_sel:[1,1,0] op_sel_hi:[1,0,1] neg_lo:[0,1,0]
	v_pk_fma_f32 v[148:149], v[20:21], v[16:17], v[148:149] op_sel:[1,1,0] op_sel_hi:[1,0,1] neg_lo:[0,1,0]
	v_lshl_add_u64 v[16:17], v[32:33], 1, s[14:15]
	v_pk_mul_f32 v[152:153], v[154:155], v[22:23] op_sel:[0,0] op_sel_hi:[0,1]
	v_pk_fma_f32 v[150:151], v[24:25], v[18:19], v[150:151] op_sel:[1,1,0] op_sel_hi:[1,0,1] neg_lo:[0,1,0]
	s_nop 0
	v_pk_fma_f32 v[152:153], v[154:155], v[22:23], v[152:153] op_sel:[1,1,0] op_sel_hi:[1,0,1] neg_lo:[0,1,0]
	global_load_dwordx4 v[20:23], v[16:17], off
	s_and_saveexec_b64 s[12:13], s[6:7]
	s_cbranch_execz .LBB0_494
	v_add_u32_e32 v16, -1, v32
	v_mov_b32_e32 v17, v33
	v_lshl_add_u64 v[16:17], v[16:17], 1, s[14:15]
	global_load_ushort v26, v[16:17], off
.LBB0_494:
	s_or_b64 exec, exec, s[12:13]
	s_and_saveexec_b64 s[12:13], s[8:9]
	s_cbranch_execz .LBB0_496
	v_add_u32_e32 v32, 8, v32
	v_lshl_add_u64 v[16:17], v[32:33], 1, s[14:15]
	global_load_ushort v157, v[16:17], off

; __device__ __forceinline__ unsigned pk2(float lo, float hi) { return f2bf(lo) | (f2bf(hi) << 16); }
; template <int R0> __device__ __forceinline__ void r0_inv_load(const LAS cf* X, const int N, int j0, f32x4 (&yr)[R0 / 2][2], f32x4 (&yi)[R0 / 2][2]) {
;     ...
;                 const cf t0 = a0 + a2, t1 = a0 - a2, t2 = a1 + a3, t3 = a1 - a3;
;                 VEL(yr[0], e + h) = t0.x + t2.x; VEL(yi[0], e + h) = t0.y + t2.y; VEL(yr[1], e + h) = t1.x - t3.y; VEL(yi[1], e + h) = t1.y + t3.x; }
; template <int R0> __device__ __forceinline__ void hy_pair(LAS cf* X, const int N, const int L, const int tid, const unsigned mA, const unsigned mB, const bf16_t* hyT, bf16_t* hyo, ...
;     ...
;         for (int n = 0; n < NL; ++n) { const int t0 = j0 + n * 4096; f32x4 xa[2], xb[2];
;             conv8(hyT, ob + mA, t0, L, wb0, wb1, wb2, bb, xa); conv8(hyT, ob + mB, t0, L, wb0, wb1, wb2, bb, xb);
;             u32x4v oA, oB;
; #pragma unroll
;             for (int e = 0; e < 8; e += 2) { const f32x4 z = ZS[(unsigned)((t0 + e) >> 1)];
;                 oA[e >> 1] = pk2(VEL(xa, e) * (VEL(yr[n], e) + z.x * d1), VEL(xa, e + 1) * (VEL(yr[n], e + 1) + z.z * d1));
;                 oB[e >> 1] = pk2(VEL(xb, e) * (VEL(yi[n], e) + z.y * d1), VEL(xb, e + 1) * (VEL(yi[n], e + 1) + z.w * d1)); }
;             *(u32x4v*)(hyo + (ov + mA + (unsigned)t0)) = oA; *(u32x4v*)(hyo + (ov + mB + (unsigned)t0)) = oB; } }
.LBB0_498:
	s_or_b64 exec, exec, s[12:13]
	s_and_saveexec_b64 s[6:7], s[8:9]
	s_cbranch_execz .LBB0_500
	v_add_u32_e32 v32, 8, v32
	v_lshl_add_u64 v[154:155], v[32:33], 1, s[14:15]
	global_load_ushort v155, v[154:155], off
.LBB0_500:
	s_or_b64 exec, exec, s[6:7]
	s_waitcnt vmcnt(1)
	v_lshlrev_b32_e32 v161, 16, v21
	v_lshlrev_b32_e32 v163, 16, v22
	v_and_b32_e32 v165, 0xffff0000, v21
	v_and_b32_e32 v164, 0xffff0000, v20
	v_mov_b32_e32 v162, v161
	v_lshlrev_b32_e32 v159, 16, v23
	v_lshlrev_b32_e32 v160, 16, v20
	v_pk_fma_f32 v[20:21], v[164:165], v[58:59], v[60:61]
	v_pk_fma_f32 v[166:167], v[162:163], v[58:59], v[60:61]
	v_pk_fma_f32 v[20:21], v[160:161], v[56:57], v[20:21]
	v_pk_fma_f32 v[166:167], v[164:165], v[56:57], v[166:167]
	v_mov_b32_e32 v27, v164
	v_and_b32_e32 v23, 0xffff0000, v23
	v_and_b32_e32 v22, 0xffff0000, v22
	v_mov_b32_e32 v156, v159
	s_waitcnt vmcnt(0)
	v_lshlrev_b32_e32 v26, 16, v26
	v_lshlrev_b32_e32 v157, 16, v157
	v_lshlrev_b32_e32 v24, 16, v24
	v_lshlrev_b32_e32 v155, 16, v155
	v_pk_fma_f32 v[26:27], v[26:27], v[54:55], v[20:21]
	v_pk_fma_f32 v[20:21], v[160:161], v[54:55], v[166:167]
	v_pk_fma_f32 v[160:161], v[22:23], v[58:59], v[60:61]
	v_mov_b32_e32 v158, v163
	v_pk_fma_f32 v[156:157], v[156:157], v[58:59], v[60:61]
	v_pk_fma_f32 v[160:161], v[158:159], v[56:57], v[160:161]
	v_pk_fma_f32 v[156:157], v[22:23], v[56:57], v[156:157]
	v_pk_mov_b32 v[22:23], v[164:165], v[22:23] op_sel:[1,0]
	v_pk_add_f32 v[166:167], v[4:5], v[118:119]
	v_pk_fma_f32 v[162:163], v[22:23], v[54:55], v[160:161]
	v_pk_fma_f32 v[160:161], v[158:159], v[54:55], v[156:157]
	v_pk_add_f32 v[22:23], v[0:1], v[30:31]
	v_pk_add_f32 v[156:157], v[28:29], v[108:109]
	v_pk_add_f32 v[170:171], v[116:117], v[120:121]
	v_mov_b32_e32 v169, v166
	v_mov_b32_e32 v173, v170
	v_mov_b32_e32 v166, v23
	v_mov_b32_e32 v170, v157
	v_pk_add_f32 v[158:159], v[2:3], v[112:113]
	v_pk_add_f32 v[164:165], v[110:111], v[114:115]
	v_mov_b32_e32 v168, v22
	v_mov_b32_e32 v172, v156
	v_pk_add_f32 v[22:23], v[166:167], v[170:171]
	v_pk_add_f32 v[156:157], v[6:7], v[124:125]
	v_pk_add_f32 v[166:167], v[122:123], v[126:127]
	v_pk_add_f32 v[168:169], v[168:169], v[172:173]
	v_mov_b32_e32 v171, v156
	v_mov_b32_e32 v173, v166
	v_mov_b32_e32 v156, v159
	v_mov_b32_e32 v166, v165
	v_mov_b32_e32 v170, v158
	v_pk_add_f32 v[174:175], v[156:157], v[166:167]
	v_pk_add_f32 v[156:157], v[8:9], v[130:131]
	v_pk_add_f32 v[158:159], v[128:129], v[132:133]
	v_pk_add_f32 v[166:167], v[12:13], v[142:143]
	v_pk_add_f32 v[178:179], v[140:141], v[146:147]
	v_mov_b32_e32 v172, v164
	v_mov_b32_e32 v165, v166
	v_mov_b32_e32 v181, v178
	v_mov_b32_e32 v166, v157
	v_mov_b32_e32 v178, v159
	v_pk_add_f32 v[172:173], v[170:171], v[172:173]
	v_pk_add_f32 v[170:171], v[10:11], v[136:137]
	v_pk_add_f32 v[176:177], v[134:135], v[138:139]
	v_mov_b32_e32 v164, v156
	v_mov_b32_e32 v180, v158
	v_pk_add_f32 v[156:157], v[166:167], v[178:179]
	v_pk_add_f32 v[158:159], v[14:15], v[150:151]
	v_pk_add_f32 v[178:179], v[148:149], v[152:153]
	v_pk_add_f32 v[164:165], v[164:165], v[180:181]
	v_mov_b32_e32 v167, v158
	v_mov_b32_e32 v181, v178
	v_mov_b32_e32 v158, v171
	v_mov_b32_e32 v178, v177
	v_mov_b32_e32 v180, v176
	v_pk_add_f32 v[158:159], v[158:159], v[178:179]
	global_load_dwordx4 v[176:179], v[104:105], off
	global_load_dwordx4 v[212:215], v[106:107], off
	v_mov_b32_e32 v166, v170
	s_waitcnt vmcnt(2)
	v_and_b32_e32 v107, 0xffff0000, v17
	v_and_b32_e32 v106, 0xffff0000, v16
	v_mov_b32_e32 v25, v106
	v_pk_add_f32 v[166:167], v[166:167], v[180:181]
	v_lshlrev_b32_e32 v154, 16, v19
	v_and_b32_e32 v19, 0xffff0000, v19
	s_waitcnt vmcnt(1)
	v_mov_b32_e32 v104, v176
	s_waitcnt vmcnt(0)
	v_mov_b32_e32 v105, v212
	v_pk_fma_f32 v[104:105], v[62:63], v[104:105], v[168:169]
	v_lshlrev_b32_e32 v169, 16, v18
	v_pk_mul_f32 v[170:171], v[26:27], v[104:105]
	v_mov_b32_e32 v26, v178
	v_mov_b32_e32 v27, v214
	v_pk_fma_f32 v[26:27], v[62:63], v[26:27], v[172:173]
	v_mov_b32_e32 v212, v177
	v_pk_mul_f32 v[172:173], v[20:21], v[26:27]
	v_lshlrev_b32_e32 v20, 16, v16
	v_lshlrev_b32_e32 v21, 16, v17
	v_pk_fma_f32 v[16:17], v[106:107], v[58:59], v[60:61]
	v_mov_b32_e32 v168, v21
	v_pk_fma_f32 v[16:17], v[20:21], v[56:57], v[16:17]
	v_pk_fma_f32 v[22:23], v[62:63], v[212:213], v[22:23]
	v_pk_fma_f32 v[16:17], v[24:25], v[54:55], v[16:17]
	v_pk_fma_f32 v[24:25], v[168:169], v[58:59], v[60:61]
	v_mov_b32_e32 v214, v179
	v_pk_fma_f32 v[24:25], v[106:107], v[56:57], v[24:25]
	v_pk_mul_f32 v[16:17], v[16:17], v[22:23]
	v_pk_fma_f32 v[20:21], v[20:21], v[54:55], v[24:25]
	v_pk_fma_f32 v[22:23], v[62:63], v[214:215], v[174:175]
	v_and_b32_e32 v18, 0xffff0000, v18
	v_pk_mul_f32 v[104:105], v[20:21], v[22:23]
	global_load_dwordx4 v[24:27], v[100:101], off
	global_load_dwordx4 v[20:23], v[102:103], off
	v_bfe_u32 v32, v170, 16, 1
	v_add3_u32 v32, v170, v32, s36
	v_bfe_u32 v39, v171, 16, 1
	v_lshrrev_b32_e32 v32, 16, v32
	v_add3_u32 v39, v171, v39, s36
	v_lshrrev_b32_e32 v39, 16, v39
	s_waitcnt vmcnt(1)
; __device__ __forceinline__ float bf2f(bf16_t v) { return __uint_as_float((unsigned)v << 16); }
; __device__ __forceinline__ unsigned pk2(float lo, float hi) { return f2bf(lo) | (f2bf(hi) << 16); }
; __device__ __forceinline__ void conv8(const bf16_t* hyT, unsigned off, int t0, int L, float w0, float w1, float w2, float b, f32x4 (&o)[2]) {
;     const u32x4v raw = *(const u32x4v*)(hyT + (off + (unsigned)t0));
;     const float xm = t0 > 0 ? bf2f(hyT[off + (unsigned)t0 - 1u]) : 0.f, xp = t0 + 8 < L ? bf2f(hyT[off + (unsigned)t0 + 8u]) : 0.f;
; template <int R0> __device__ __forceinline__ void hy_pair(LAS cf* X, const int N, const int L, const int tid, const unsigned mA, const unsigned mB, const bf16_t* hyT, bf16_t* hyo, ...
;     ...
;         for (int n = 0; n < NL; ++n) { const int t0 = j0 + n * 4096; f32x4 xa[2], xb[2];
;             conv8(hyT, ob + mA, t0, L, wb0, wb1, wb2, bb, xa); conv8(hyT, ob + mB, t0, L, wb0, wb1, wb2, bb, xb);
;             u32x4v oA, oB;
; #pragma unroll
;             for (int e = 0; e < 8; e += 2) { const f32x4 z = ZS[(unsigned)((t0 + e) >> 1)];
;                 oA[e >> 1] = pk2(VEL(xa, e) * (VEL(yr[n], e) + z.x * d1), VEL(xa, e + 1) * (VEL(yr[n], e + 1) + z.z * d1));
;                 oB[e >> 1] = pk2(VEL(xb, e) * (VEL(yi[n], e) + z.y * d1), VEL(xb, e + 1) * (VEL(yi[n], e + 1) + z.w * d1)); }
;             *(u32x4v*)(hyo + (ov + mA + (unsigned)t0)) = oA; *(u32x4v*)(hyo + (ov + mB + (unsigned)t0)) = oB; } }
	v_mov_b32_e32 v100, v24
	s_waitcnt vmcnt(0)
	v_mov_b32_e32 v101, v20
	v_pk_fma_f32 v[100:101], v[62:63], v[100:101], v[164:165]
	v_mov_b32_e32 v102, v26
	v_mov_b32_e32 v103, v22
	v_pk_mul_f32 v[100:101], v[162:163], v[100:101]
	v_pk_fma_f32 v[102:103], v[62:63], v[102:103], v[166:167]
	v_bfe_u32 v43, v101, 16, 1
	v_pk_mul_f32 v[102:103], v[160:161], v[102:103]
	v_bfe_u32 v41, v100, 16, 1
	v_bfe_u32 v20, v103, 16, 1
	v_add3_u32 v43, v101, v43, s36
	v_bfe_u32 v22, v102, 16, 1
	v_add3_u32 v20, v103, v20, s36
	v_add3_u32 v41, v100, v41, s36
	v_lshrrev_b32_e32 v43, 16, v43
	v_pk_fma_f32 v[160:161], v[18:19], v[58:59], v[60:61]
	v_pk_fma_f32 v[162:163], v[154:155], v[58:59], v[60:61]
	v_mov_b32_e32 v164, v169
	v_mov_b32_e32 v165, v154
	v_add3_u32 v22, v102, v22, s36
	v_lshrrev_b32_e32 v41, 16, v41
	v_and_or_b32 v103, v20, s29, v43
	v_pk_fma_f32 v[162:163], v[18:19], v[56:57], v[162:163]
	v_pk_fma_f32 v[154:155], v[164:165], v[56:57], v[160:161]
	v_pk_mov_b32 v[18:19], v[106:107], v[18:19] op_sel:[1,0]
	v_mov_b32_e32 v20, v25
	v_and_or_b32 v102, v22, s29, v41
	v_pk_fma_f32 v[18:19], v[18:19], v[54:55], v[154:155]
	v_pk_fma_f32 v[20:21], v[62:63], v[20:21], v[156:157]
	v_mov_b32_e32 v22, v27
	v_bfe_u32 v26, v172, 16, 1
	v_pk_fma_f32 v[106:107], v[164:165], v[54:55], v[162:163]
	v_pk_mul_f32 v[18:19], v[18:19], v[20:21]
	v_pk_fma_f32 v[20:21], v[62:63], v[22:23], v[158:159]
	v_add3_u32 v26, v172, v26, s36
	v_pk_mul_f32 v[20:21], v[106:107], v[20:21]
	v_bfe_u32 v24, v173, 16, 1
	v_and_or_b32 v100, v26, s29, v32
	v_bfe_u32 v22, v21, 16, 1
	v_bfe_u32 v23, v20, 16, 1
	v_bfe_u32 v26, v18, 16, 1
	v_bfe_u32 v27, v19, 16, 1
	v_add3_u32 v24, v173, v24, s36
	v_add3_u32 v20, v20, v23, s36
	v_add3_u32 v21, v21, v22, s36
	v_bfe_u32 v22, v16, 16, 1
	v_bfe_u32 v23, v17, 16, 1
	v_add3_u32 v19, v19, v27, s36
	v_add3_u32 v18, v18, v26, s36
	v_and_or_b32 v101, v24, s29, v39
	v_bfe_u32 v24, v105, 16, 1
	v_bfe_u32 v25, v104, 16, 1
	v_add3_u32 v17, v17, v23, s36
	v_add3_u32 v16, v16, v22, s36
	v_lshrrev_b32_e32 v18, 16, v18
	v_lshrrev_b32_e32 v19, 16, v19
	v_add3_u32 v25, v104, v25, s36
	v_add3_u32 v24, v105, v24, s36
	v_lshrrev_b32_e32 v16, 16, v16
	v_lshrrev_b32_e32 v17, 16, v17
	v_and_or_b32 v19, v21, s29, v19
	v_and_or_b32 v18, v20, s29, v18
	v_lshl_add_u64 v[20:21], v[88:89], 1, s[38:39]
	v_and_or_b32 v17, v24, s29, v17
	v_and_or_b32 v16, v25, s29, v16
	global_store_dwordx4 v[20:21], v[100:103], off
	v_lshl_add_u64 v[20:21], v[90:91], 1, s[38:39]
	v_add_u32_e32 v32, s94, v208
	global_store_dwordx4 v[20:21], v[16:19], off
	v_mov_b32_e32 v27, 0
	v_mov_b32_e32 v106, 0
	v_lshl_add_u64 v[16:17], v[32:33], 1, s[14:15]
	global_load_dwordx4 v[20:23], v[16:17], off
	s_and_saveexec_b64 s[6:7], vcc
	s_cbranch_execz .LBB0_502
	v_add_u32_e32 v16, -1, v32
	v_mov_b32_e32 v17, v33
	v_lshl_add_u64 v[16:17], v[16:17], 1, s[14:15]
	global_load_ushort v106, v[16:17], off
.LBB0_502:
	s_or_b64 exec, exec, s[6:7]
	s_and_saveexec_b64 s[6:7], s[4:5]
	s_cbranch_execz .LBB0_504
	v_add_u32_e32 v32, 8, v32
	v_lshl_add_u64 v[16:17], v[32:33], 1, s[14:15]
	global_load_ushort v27, v[16:17], off
.LBB0_504:
	s_or_b64 exec, exec, s[6:7]
	v_add_u32_e32 v32, s1, v208
	v_lshl_add_u64 v[16:17], v[32:33], 1, s[14:15]
	global_load_dwordx4 v[16:19], v[16:17], off
	v_mov_b32_e32 v25, 0
	v_mov_b32_e32 v154, 0
	s_and_saveexec_b64 s[6:7], vcc
	s_cbranch_execz .LBB0_506
	v_add_u32_e32 v88, -1, v32
	v_mov_b32_e32 v89, v33
	v_lshl_add_u64 v[88:89], v[88:89], 1, s[14:15]
	global_load_ushort v154, v[88:89], off
.LBB0_506:
	s_or_b64 exec, exec, s[6:7]
	s_and_saveexec_b64 s[6:7], s[4:5]
	s_cbranch_execz .LBB0_343
	v_add_u32_e32 v32, 8, v32
	v_lshl_add_u64 v[24:25], v[32:33], 1, s[14:15]
	global_load_ushort v25, v[24:25], off
	s_branch .LBB0_343
